# GEMM K-loops: redundant second s_waitcnt lgkmcnt(0) before each MFMA cluster and the s_nop pads after M0 writes (address add moved into the slot) removed: 156 issue slots
# speedup vs baseline: 1.0048x; 1.0048x over previous
.LBB0_191:
	ds_read_b128 v[48:51], v147
	ds_read_b128 v[132:135], v147 offset:1024
	ds_read_b128 v[162:165], v147 offset:2048
	ds_read_b128 v[166:169], v147 offset:3072
	s_add_u32 s34, s8, 0x100
	s_addc_u32 s35, s9, 0
	s_cmp_eq_u32 s70, 12
	s_cselect_b32 s39, s62, s35
	s_cselect_b32 s38, s63, s34
	s_cselect_b32 s37, s15, s69
	s_cselect_b32 s36, s67, s68
	s_mov_b32 m0, s57
	v_lshl_add_u64 v[186:187], s[8:9], 0, v[150:151]
	ds_read_b128 v[170:173], v159
	ds_read_b128 v[174:177], v159 offset:1024
	ds_read_b128 v[178:181], v159 offset:2048
	ds_read_b128 v[182:185], v159 offset:3072
	ds_read_b128 v[190:193], v159 offset:4096
	ds_read_b128 v[194:197], v159 offset:5120
	ds_read_b128 v[198:201], v159 offset:6144
	ds_read_b128 v[202:205], v159 offset:7168
	global_load_lds_dwordx4 v[186:187], off
	s_mov_b32 m0, s58
	v_lshl_add_u64 v[186:187], s[8:9], 0, v[152:153]
	global_load_lds_dwordx4 v[186:187], off
	s_waitcnt lgkmcnt(8)
	s_barrier
	s_waitcnt lgkmcnt(0)
	v_mfma_f32_16x16x32_bf16 v[72:75], v[48:51], v[170:173], v[72:75]
	v_mfma_f32_16x16x32_bf16 v[28:31], v[162:165], v[170:173], v[28:31]
	v_mfma_f32_16x16x32_bf16 v[64:67], v[48:51], v[178:181], v[64:67]
	v_mfma_f32_16x16x32_bf16 v[24:27], v[162:165], v[178:181], v[24:27]
	v_mfma_f32_16x16x32_bf16 v[128:131], v[48:51], v[190:193], v[128:131]
	v_mfma_f32_16x16x32_bf16 v[124:127], v[162:165], v[190:193], v[124:127]
	v_mfma_f32_16x16x32_bf16 v[120:123], v[48:51], v[198:201], v[120:123]
	v_mfma_f32_16x16x32_bf16 v[116:119], v[162:165], v[198:201], v[116:119]
	v_mfma_f32_16x16x32_bf16 v[72:75], v[132:135], v[174:177], v[72:75]
	v_mfma_f32_16x16x32_bf16 v[28:31], v[166:169], v[174:177], v[28:31]
	v_mfma_f32_16x16x32_bf16 v[64:67], v[132:135], v[182:185], v[64:67]
	v_mfma_f32_16x16x32_bf16 v[24:27], v[166:169], v[182:185], v[24:27]
	v_mfma_f32_16x16x32_bf16 v[128:131], v[132:135], v[194:197], v[128:131]
	v_mfma_f32_16x16x32_bf16 v[124:127], v[166:169], v[194:197], v[124:127]
	v_mfma_f32_16x16x32_bf16 v[120:123], v[132:135], v[202:205], v[120:123]
	v_mfma_f32_16x16x32_bf16 v[116:119], v[166:169], v[202:205], v[116:119]
	s_barrier
	s_add_i32 s8, s54, s43
	v_lshl_add_u64 v[186:187], s[36:37], 0, v[138:139]
	s_mov_b32 m0, s8
	ds_read_b128 v[206:209], v160
	ds_read_b128 v[210:213], v160 offset:1024
	ds_read_b128 v[214:217], v160 offset:2048
	ds_read_b128 v[218:221], v160 offset:3072
	global_load_lds_dwordx4 v[186:187], off
	s_add_i32 m0, s8, 0x2000
	v_lshl_add_u64 v[222:223], s[36:37], 0, v[142:143]
	global_load_lds_dwordx4 v[222:223], off
	s_barrier
	s_waitcnt lgkmcnt(0)
	v_mfma_f32_16x16x32_bf16 v[56:59], v[206:209], v[170:173], v[56:59]
	v_mfma_f32_16x16x32_bf16 v[20:23], v[214:217], v[170:173], v[20:23]
	v_mfma_f32_16x16x32_bf16 v[52:55], v[206:209], v[178:181], v[52:55]
	v_mfma_f32_16x16x32_bf16 v[16:19], v[214:217], v[178:181], v[16:19]
	v_mfma_f32_16x16x32_bf16 v[112:115], v[206:209], v[190:193], v[112:115]
	v_mfma_f32_16x16x32_bf16 v[108:111], v[214:217], v[190:193], v[108:111]
	v_mfma_f32_16x16x32_bf16 v[104:107], v[206:209], v[198:201], v[104:107]
	v_mfma_f32_16x16x32_bf16 v[100:103], v[214:217], v[198:201], v[100:103]
	v_mfma_f32_16x16x32_bf16 v[56:59], v[210:213], v[174:177], v[56:59]
	v_mfma_f32_16x16x32_bf16 v[20:23], v[218:221], v[174:177], v[20:23]
	v_mfma_f32_16x16x32_bf16 v[52:55], v[210:213], v[182:185], v[52:55]
	v_mfma_f32_16x16x32_bf16 v[16:19], v[218:221], v[182:185], v[16:19]
	v_mfma_f32_16x16x32_bf16 v[112:115], v[210:213], v[194:197], v[112:115]
	v_mfma_f32_16x16x32_bf16 v[108:111], v[218:221], v[194:197], v[108:111]
	v_mfma_f32_16x16x32_bf16 v[104:107], v[210:213], v[202:205], v[104:107]
	v_mfma_f32_16x16x32_bf16 v[100:103], v[218:221], v[202:205], v[100:103]
	s_mov_b32 m0, s44
	v_lshl_add_u64 v[224:225], s[38:39], 0, v[136:137]
	s_barrier
	ds_read_b128 v[170:173], v159 offset:16384
	ds_read_b128 v[174:177], v159 offset:17408
	ds_read_b128 v[178:181], v159 offset:18432
	ds_read_b128 v[182:185], v159 offset:19456
	ds_read_b128 v[190:193], v159 offset:20480
	ds_read_b128 v[194:197], v159 offset:21504
	ds_read_b128 v[198:201], v159 offset:22528
	ds_read_b128 v[202:205], v159 offset:23552
	global_load_lds_dwordx4 v[224:225], off
	s_mov_b32 m0, s45
	v_lshl_add_u64 v[226:227], s[38:39], 0, v[140:141]
	global_load_lds_dwordx4 v[226:227], off
	s_barrier
	s_waitcnt lgkmcnt(0)
	v_mfma_f32_16x16x32_bf16 v[44:47], v[48:51], v[170:173], v[44:47]
	v_mfma_f32_16x16x32_bf16 v[12:15], v[162:165], v[170:173], v[12:15]
	v_mfma_f32_16x16x32_bf16 v[40:43], v[48:51], v[178:181], v[40:43]
	v_mfma_f32_16x16x32_bf16 v[8:11], v[162:165], v[178:181], v[8:11]
	v_mfma_f32_16x16x32_bf16 v[96:99], v[48:51], v[190:193], v[96:99]
	v_mfma_f32_16x16x32_bf16 v[92:95], v[162:165], v[190:193], v[92:95]
	v_mfma_f32_16x16x32_bf16 v[76:79], v[162:165], v[198:201], v[76:79]
	v_mfma_f32_16x16x32_bf16 v[44:47], v[132:135], v[174:177], v[44:47]
	v_mfma_f32_16x16x32_bf16 v[12:15], v[166:169], v[174:177], v[12:15]
	v_mfma_f32_16x16x32_bf16 v[40:43], v[132:135], v[182:185], v[40:43]
	v_mfma_f32_16x16x32_bf16 v[8:11], v[166:169], v[182:185], v[8:11]
	v_mfma_f32_16x16x32_bf16 v[96:99], v[132:135], v[194:197], v[96:99]
	v_mfma_f32_16x16x32_bf16 v[92:95], v[166:169], v[194:197], v[92:95]
	v_mfma_f32_16x16x32_bf16 v[48:51], v[48:51], v[198:201], v[84:87]
	v_mfma_f32_16x16x32_bf16 v[76:79], v[166:169], v[202:205], v[76:79]
	v_mfma_f32_16x16x32_bf16 v[48:51], v[132:135], v[202:205], v[48:51]
	s_barrier
	s_add_u32 s8, s36, 0x40000
	s_addc_u32 s9, s37, 0
	s_add_i32 s71, s55, s43
	s_mov_b32 m0, s71
	v_lshl_add_u64 v[84:85], s[8:9], 0, v[138:139]
	global_load_lds_dwordx4 v[84:85], off
	s_add_i32 m0, s71, 0x2000
	v_lshl_add_u64 v[84:85], s[8:9], 0, v[142:143]
	global_load_lds_dwordx4 v[84:85], off
	s_waitcnt vmcnt(6)
	s_barrier
	v_mfma_f32_16x16x32_bf16 v[36:39], v[206:209], v[170:173], v[36:39]
	v_mfma_f32_16x16x32_bf16 v[4:7], v[214:217], v[170:173], v[4:7]
	v_mfma_f32_16x16x32_bf16 v[32:35], v[206:209], v[178:181], v[32:35]
	v_mfma_f32_16x16x32_bf16 v[0:3], v[214:217], v[178:181], v[0:3]
	v_mfma_f32_16x16x32_bf16 v[84:87], v[206:209], v[190:193], v[88:91]
	v_mfma_f32_16x16x32_bf16 v[80:83], v[214:217], v[190:193], v[80:83]
	v_mfma_f32_16x16x32_bf16 v[68:71], v[206:209], v[198:201], v[68:71]
	v_mfma_f32_16x16x32_bf16 v[60:63], v[214:217], v[198:201], v[60:63]
	v_mfma_f32_16x16x32_bf16 v[36:39], v[210:213], v[174:177], v[36:39]
	v_mfma_f32_16x16x32_bf16 v[4:7], v[218:221], v[174:177], v[4:7]
	v_mfma_f32_16x16x32_bf16 v[32:35], v[210:213], v[182:185], v[32:35]
	v_mfma_f32_16x16x32_bf16 v[0:3], v[218:221], v[182:185], v[0:3]
	v_mfma_f32_16x16x32_bf16 v[88:91], v[210:213], v[194:197], v[84:87]
	v_mfma_f32_16x16x32_bf16 v[80:83], v[218:221], v[194:197], v[80:83]
	v_mfma_f32_16x16x32_bf16 v[68:71], v[210:213], v[202:205], v[68:71]
	v_mfma_f32_16x16x32_bf16 v[60:63], v[218:221], v[202:205], v[60:63]
	s_add_i32 s71, 0, 0x18000
	v_add_u32_e32 v166, s71, v156
	s_barrier
	ds_read_b128 v[84:87], v166
	ds_read_b128 v[132:135], v166 offset:1024
	ds_read_b128 v[162:165], v166 offset:2048
	ds_read_b128 v[166:169], v166 offset:3072
	s_add_u32 s8, s38, 0x40000
	s_addc_u32 s9, s39, 0
	s_mov_b32 m0, s46
	v_lshl_add_u64 v[206:207], s[8:9], 0, v[136:137]
	ds_read_b128 v[170:173], v159 offset:32768
	ds_read_b128 v[174:177], v159 offset:33792
	ds_read_b128 v[178:181], v159 offset:34816
	ds_read_b128 v[182:185], v159 offset:35840
	ds_read_b128 v[190:193], v159 offset:36864
	ds_read_b128 v[194:197], v159 offset:37888
	ds_read_b128 v[198:201], v159 offset:38912
	ds_read_b128 v[202:205], v159 offset:39936
	global_load_lds_dwordx4 v[206:207], off
	s_mov_b32 m0, s47
	v_lshl_add_u64 v[206:207], s[8:9], 0, v[140:141]
	global_load_lds_dwordx4 v[206:207], off
	s_waitcnt lgkmcnt(8)
	s_barrier
	s_waitcnt lgkmcnt(0)
	v_mfma_f32_16x16x32_bf16 v[72:75], v[84:87], v[170:173], v[72:75]
	v_mfma_f32_16x16x32_bf16 v[28:31], v[162:165], v[170:173], v[28:31]
	v_mfma_f32_16x16x32_bf16 v[64:67], v[84:87], v[178:181], v[64:67]
	v_mfma_f32_16x16x32_bf16 v[24:27], v[162:165], v[178:181], v[24:27]
	v_mfma_f32_16x16x32_bf16 v[128:131], v[84:87], v[190:193], v[128:131]
	v_mfma_f32_16x16x32_bf16 v[124:127], v[162:165], v[190:193], v[124:127]
	v_mfma_f32_16x16x32_bf16 v[120:123], v[84:87], v[198:201], v[120:123]
	v_mfma_f32_16x16x32_bf16 v[116:119], v[162:165], v[198:201], v[116:119]
	v_mfma_f32_16x16x32_bf16 v[72:75], v[132:135], v[174:177], v[72:75]
	v_mfma_f32_16x16x32_bf16 v[28:31], v[166:169], v[174:177], v[28:31]
	v_mfma_f32_16x16x32_bf16 v[64:67], v[132:135], v[182:185], v[64:67]
	v_mfma_f32_16x16x32_bf16 v[24:27], v[166:169], v[182:185], v[24:27]
	v_mfma_f32_16x16x32_bf16 v[128:131], v[132:135], v[194:197], v[128:131]
	v_mfma_f32_16x16x32_bf16 v[124:127], v[166:169], v[194:197], v[124:127]
	v_mfma_f32_16x16x32_bf16 v[120:123], v[132:135], v[202:205], v[120:123]
	v_mfma_f32_16x16x32_bf16 v[116:119], v[166:169], v[202:205], v[116:119]
	s_barrier
	s_add_i32 s38, 0, 0x1c000
	s_add_i32 s8, s71, s43
	v_add_u32_e32 v189, s38, v156
	v_lshl_add_u64 v[186:187], v[186:187], 0, s[24:25]
	s_mov_b32 m0, s8
	ds_read_b128 v[206:209], v189
	ds_read_b128 v[210:213], v189 offset:1024
	ds_read_b128 v[214:217], v189 offset:2048
	ds_read_b128 v[218:221], v189 offset:3072
	global_load_lds_dwordx4 v[186:187], off
	s_add_i32 m0, s8, 0x2000
	v_lshl_add_u64 v[186:187], v[222:223], 0, s[24:25]
	global_load_lds_dwordx4 v[186:187], off
	s_barrier
	s_waitcnt lgkmcnt(0)
	v_mfma_f32_16x16x32_bf16 v[56:59], v[206:209], v[170:173], v[56:59]
	v_mfma_f32_16x16x32_bf16 v[20:23], v[214:217], v[170:173], v[20:23]
	v_mfma_f32_16x16x32_bf16 v[52:55], v[206:209], v[178:181], v[52:55]
	v_mfma_f32_16x16x32_bf16 v[16:19], v[214:217], v[178:181], v[16:19]
	v_mfma_f32_16x16x32_bf16 v[112:115], v[206:209], v[190:193], v[112:115]
	v_mfma_f32_16x16x32_bf16 v[108:111], v[214:217], v[190:193], v[108:111]
	v_mfma_f32_16x16x32_bf16 v[104:107], v[206:209], v[198:201], v[104:107]
	v_mfma_f32_16x16x32_bf16 v[100:103], v[214:217], v[198:201], v[100:103]
	v_mfma_f32_16x16x32_bf16 v[56:59], v[210:213], v[174:177], v[56:59]
	v_mfma_f32_16x16x32_bf16 v[20:23], v[218:221], v[174:177], v[20:23]
	v_mfma_f32_16x16x32_bf16 v[52:55], v[210:213], v[182:185], v[52:55]
	v_mfma_f32_16x16x32_bf16 v[16:19], v[218:221], v[182:185], v[16:19]
	v_mfma_f32_16x16x32_bf16 v[112:115], v[210:213], v[194:197], v[112:115]
	v_mfma_f32_16x16x32_bf16 v[108:111], v[218:221], v[194:197], v[108:111]
	v_mfma_f32_16x16x32_bf16 v[104:107], v[210:213], v[202:205], v[104:107]
	v_mfma_f32_16x16x32_bf16 v[100:103], v[218:221], v[202:205], v[100:103]
	s_mov_b32 m0, s50
	v_lshl_add_u64 v[186:187], v[224:225], 0, s[24:25]
	s_barrier
	ds_read_b128 v[170:173], v159 offset:49152
	ds_read_b128 v[174:177], v159 offset:50176
	ds_read_b128 v[178:181], v159 offset:51200
	ds_read_b128 v[182:185], v159 offset:52224
	ds_read_b128 v[190:193], v159 offset:53248
	ds_read_b128 v[194:197], v159 offset:54272
	ds_read_b128 v[198:201], v159 offset:55296
	ds_read_b128 v[202:205], v159 offset:56320
	global_load_lds_dwordx4 v[186:187], off
	s_mov_b32 m0, s51
	v_lshl_add_u64 v[186:187], v[226:227], 0, s[24:25]
	global_load_lds_dwordx4 v[186:187], off
	s_barrier
	s_waitcnt lgkmcnt(0)
	v_mfma_f32_16x16x32_bf16 v[48:51], v[84:87], v[198:201], v[48:51]
	v_mfma_f32_16x16x32_bf16 v[44:47], v[84:87], v[170:173], v[44:47]
	v_mfma_f32_16x16x32_bf16 v[12:15], v[162:165], v[170:173], v[12:15]
	v_mfma_f32_16x16x32_bf16 v[40:43], v[84:87], v[178:181], v[40:43]
	v_mfma_f32_16x16x32_bf16 v[8:11], v[162:165], v[178:181], v[8:11]
	v_mfma_f32_16x16x32_bf16 v[96:99], v[84:87], v[190:193], v[96:99]
	v_mfma_f32_16x16x32_bf16 v[92:95], v[162:165], v[190:193], v[92:95]
	v_mfma_f32_16x16x32_bf16 v[84:87], v[132:135], v[202:205], v[48:51]
	v_mfma_f32_16x16x32_bf16 v[48:51], v[162:165], v[198:201], v[76:79]
	v_mfma_f32_16x16x32_bf16 v[44:47], v[132:135], v[174:177], v[44:47]
	v_mfma_f32_16x16x32_bf16 v[12:15], v[166:169], v[174:177], v[12:15]
	v_mfma_f32_16x16x32_bf16 v[40:43], v[132:135], v[182:185], v[40:43]
	v_mfma_f32_16x16x32_bf16 v[8:11], v[166:169], v[182:185], v[8:11]
	v_mfma_f32_16x16x32_bf16 v[96:99], v[132:135], v[194:197], v[96:99]
	v_mfma_f32_16x16x32_bf16 v[92:95], v[166:169], v[194:197], v[92:95]
	v_mfma_f32_16x16x32_bf16 v[76:79], v[166:169], v[202:205], v[48:51]
	s_barrier
	s_add_u32 s8, s36, 0x40080
	s_addc_u32 s9, s37, 0
	s_add_i32 s36, s38, s43
	s_mov_b32 m0, s36
	v_lshl_add_u64 v[48:49], s[8:9], 0, v[138:139]
	global_load_lds_dwordx4 v[48:49], off
	s_add_i32 m0, s36, 0x2000
	v_lshl_add_u64 v[48:49], s[8:9], 0, v[142:143]
	global_load_lds_dwordx4 v[48:49], off
	s_waitcnt vmcnt(6)
	s_barrier
	v_mfma_f32_16x16x32_bf16 v[48:51], v[206:209], v[190:193], v[88:91]
	v_mfma_f32_16x16x32_bf16 v[88:91], v[210:213], v[194:197], v[48:51]
	v_mfma_f32_16x16x32_bf16 v[48:51], v[214:217], v[190:193], v[80:83]
	v_mfma_f32_16x16x32_bf16 v[80:83], v[218:221], v[194:197], v[48:51]
	v_mfma_f32_16x16x32_bf16 v[48:51], v[206:209], v[198:201], v[68:71]
	v_mfma_f32_16x16x32_bf16 v[36:39], v[206:209], v[170:173], v[36:39]
	v_mfma_f32_16x16x32_bf16 v[4:7], v[214:217], v[170:173], v[4:7]
	v_mfma_f32_16x16x32_bf16 v[32:35], v[206:209], v[178:181], v[32:35]
	v_mfma_f32_16x16x32_bf16 v[0:3], v[214:217], v[178:181], v[0:3]
	v_mfma_f32_16x16x32_bf16 v[68:71], v[210:213], v[202:205], v[48:51]
	v_mfma_f32_16x16x32_bf16 v[48:51], v[214:217], v[198:201], v[60:63]
	v_mfma_f32_16x16x32_bf16 v[36:39], v[210:213], v[174:177], v[36:39]
	v_mfma_f32_16x16x32_bf16 v[4:7], v[218:221], v[174:177], v[4:7]
	v_mfma_f32_16x16x32_bf16 v[32:35], v[210:213], v[182:185], v[32:35]
	v_mfma_f32_16x16x32_bf16 v[0:3], v[218:221], v[182:185], v[0:3]
	v_mfma_f32_16x16x32_bf16 v[60:63], v[218:221], v[202:205], v[48:51]
	s_add_i32 s70, s70, 2
	s_add_u32 s68, s68, 0x100
	s_addc_u32 s69, s69, 0
	s_cmp_gt_u32 s70, 13
	s_mov_b64 s[8:9], s[34:35]
	s_barrier
	s_cbranch_scc0 .LBB0_191
	v_cndmask_b32_e64 v48, 0, 1, s[30:31]
	v_cmp_ne_u32_e64 s[8:9], 1, v48
	s_andn2_b64 vcc, exec, s[30:31]
	s_cbranch_vccnz .LBB0_196
	v_mov_b32_e32 v48, 0
	v_mov_b32_e32 v49, 0
	v_mov_b32_e32 v50, 0
	v_mov_b32_e32 v51, 0
	s_and_saveexec_b64 s[30:31], s[2:3]
	s_cbranch_execz .LBB0_195
	s_lshl_b32 s34, s14, 7
	s_ashr_i32 s35, s34, 31
	v_lshl_add_u64 v[48:49], s[34:35], 2, v[148:149]
	global_load_dwordx4 v[48:51], v[48:49], off

.LBB0_286:
	ds_read_b128 v[128:131], v162
	ds_read_b128 v[148:151], v162 offset:1024
	ds_read_b128 v[152:155], v162 offset:2048
	ds_read_b128 v[166:169], v162 offset:3072
	s_add_u32 s36, s34, 0xfffc0080
	s_addc_u32 s37, s35, -1
	s_cmp_eq_u32 s59, 12
	s_cselect_b32 s39, s23, s37
	s_cselect_b32 s38, s55, s36
	s_cselect_b32 s37, s21, s58
	s_cselect_b32 s36, s56, s57
	v_lshl_add_u64 v[156:157], s[34:35], 0, v[140:141]
	s_add_i32 m0, s31, 0xc000
	ds_read_b128 v[170:173], v163
	ds_read_b128 v[174:177], v163 offset:1024
	ds_read_b128 v[178:181], v163 offset:2048
	ds_read_b128 v[182:185], v163 offset:3072
	ds_read_b128 v[190:193], v163 offset:4096
	ds_read_b128 v[194:197], v163 offset:5120
	ds_read_b128 v[198:201], v163 offset:6144
	ds_read_b128 v[202:205], v163 offset:7168
	global_load_lds_dwordx4 v[156:157], off
	s_add_i32 m0, s31, 0xe000
	v_lshl_add_u64 v[156:157], s[34:35], 0, v[142:143]
	global_load_lds_dwordx4 v[156:157], off
	s_waitcnt lgkmcnt(8)
	s_barrier
	s_waitcnt lgkmcnt(0)
	v_mfma_f32_16x16x32_bf16 v[124:127], v[128:131], v[170:173], v[124:127]
	v_mfma_f32_16x16x32_bf16 v[120:123], v[152:155], v[170:173], v[120:123]
	v_mfma_f32_16x16x32_bf16 v[108:111], v[128:131], v[178:181], v[108:111]
	v_mfma_f32_16x16x32_bf16 v[104:107], v[152:155], v[178:181], v[104:107]
	v_mfma_f32_16x16x32_bf16 v[92:95], v[128:131], v[190:193], v[92:95]
	v_mfma_f32_16x16x32_bf16 v[88:91], v[152:155], v[190:193], v[88:91]
	v_mfma_f32_16x16x32_bf16 v[76:79], v[128:131], v[198:201], v[76:79]
	v_mfma_f32_16x16x32_bf16 v[72:75], v[152:155], v[198:201], v[72:75]
	v_mfma_f32_16x16x32_bf16 v[124:127], v[148:151], v[174:177], v[124:127]
	v_mfma_f32_16x16x32_bf16 v[120:123], v[166:169], v[174:177], v[120:123]
	v_mfma_f32_16x16x32_bf16 v[108:111], v[148:151], v[182:185], v[108:111]
	v_mfma_f32_16x16x32_bf16 v[104:107], v[166:169], v[182:185], v[104:107]
	v_mfma_f32_16x16x32_bf16 v[92:95], v[148:151], v[194:197], v[92:95]
	v_mfma_f32_16x16x32_bf16 v[88:91], v[166:169], v[194:197], v[88:91]
	v_mfma_f32_16x16x32_bf16 v[76:79], v[148:151], v[202:205], v[76:79]
	v_mfma_f32_16x16x32_bf16 v[72:75], v[166:169], v[202:205], v[72:75]
	s_barrier
	s_add_i32 s60, s52, s44
	v_lshl_add_u64 v[156:157], s[36:37], 0, v[134:135]
	s_mov_b32 m0, s60
	ds_read_b128 v[206:209], v164
	ds_read_b128 v[210:213], v164 offset:1024
	ds_read_b128 v[214:217], v164 offset:2048
	ds_read_b128 v[218:221], v164 offset:3072
	global_load_lds_dwordx4 v[156:157], off
	s_add_i32 m0, s60, 0x2000
	v_lshl_add_u64 v[186:187], s[36:37], 0, v[138:139]
	global_load_lds_dwordx4 v[186:187], off
	s_barrier
	s_waitcnt lgkmcnt(0)
	v_mfma_f32_16x16x32_bf16 v[116:119], v[206:209], v[170:173], v[116:119]
	v_mfma_f32_16x16x32_bf16 v[112:115], v[214:217], v[170:173], v[112:115]
	v_mfma_f32_16x16x32_bf16 v[100:103], v[206:209], v[178:181], v[100:103]
	v_mfma_f32_16x16x32_bf16 v[96:99], v[214:217], v[178:181], v[96:99]
	v_mfma_f32_16x16x32_bf16 v[84:87], v[206:209], v[190:193], v[84:87]
	v_mfma_f32_16x16x32_bf16 v[80:83], v[214:217], v[190:193], v[80:83]
	v_mfma_f32_16x16x32_bf16 v[68:71], v[206:209], v[198:201], v[68:71]
	v_mfma_f32_16x16x32_bf16 v[64:67], v[214:217], v[198:201], v[64:67]
	v_mfma_f32_16x16x32_bf16 v[116:119], v[210:213], v[174:177], v[116:119]
	v_mfma_f32_16x16x32_bf16 v[112:115], v[218:221], v[174:177], v[112:115]
	v_mfma_f32_16x16x32_bf16 v[100:103], v[210:213], v[182:185], v[100:103]
	v_mfma_f32_16x16x32_bf16 v[96:99], v[218:221], v[182:185], v[96:99]
	v_mfma_f32_16x16x32_bf16 v[84:87], v[210:213], v[194:197], v[84:87]
	v_mfma_f32_16x16x32_bf16 v[80:83], v[218:221], v[194:197], v[80:83]
	v_mfma_f32_16x16x32_bf16 v[68:71], v[210:213], v[202:205], v[68:71]
	v_mfma_f32_16x16x32_bf16 v[64:67], v[218:221], v[202:205], v[64:67]
	s_mov_b32 m0, s31
	v_lshl_add_u64 v[222:223], s[38:39], 0, v[132:133]
	s_barrier
	ds_read_b128 v[170:173], v163 offset:16384
	ds_read_b128 v[174:177], v163 offset:17408
	ds_read_b128 v[178:181], v163 offset:18432
	ds_read_b128 v[182:185], v163 offset:19456
	ds_read_b128 v[190:193], v163 offset:20480
	ds_read_b128 v[194:197], v163 offset:21504
	ds_read_b128 v[198:201], v163 offset:22528
	ds_read_b128 v[202:205], v163 offset:23552
	global_load_lds_dwordx4 v[222:223], off
	s_mov_b32 m0, s45
	v_lshl_add_u64 v[224:225], s[38:39], 0, v[136:137]
	global_load_lds_dwordx4 v[224:225], off
	s_barrier
	s_waitcnt lgkmcnt(0)
	v_mfma_f32_16x16x32_bf16 v[60:63], v[128:131], v[170:173], v[60:63]
	v_mfma_f32_16x16x32_bf16 v[56:59], v[152:155], v[170:173], v[56:59]
	v_mfma_f32_16x16x32_bf16 v[44:47], v[128:131], v[178:181], v[44:47]
	v_mfma_f32_16x16x32_bf16 v[40:43], v[152:155], v[178:181], v[40:43]
	v_mfma_f32_16x16x32_bf16 v[28:31], v[128:131], v[190:193], v[28:31]
	v_mfma_f32_16x16x32_bf16 v[24:27], v[152:155], v[190:193], v[24:27]
	v_mfma_f32_16x16x32_bf16 v[12:15], v[128:131], v[198:201], v[12:15]
	v_mfma_f32_16x16x32_bf16 v[8:11], v[152:155], v[198:201], v[8:11]
	v_mfma_f32_16x16x32_bf16 v[60:63], v[148:151], v[174:177], v[60:63]
	v_mfma_f32_16x16x32_bf16 v[56:59], v[166:169], v[174:177], v[56:59]
	v_mfma_f32_16x16x32_bf16 v[44:47], v[148:151], v[182:185], v[44:47]
	v_mfma_f32_16x16x32_bf16 v[40:43], v[166:169], v[182:185], v[40:43]
	v_mfma_f32_16x16x32_bf16 v[28:31], v[148:151], v[194:197], v[28:31]
	v_mfma_f32_16x16x32_bf16 v[24:27], v[166:169], v[194:197], v[24:27]
	v_mfma_f32_16x16x32_bf16 v[12:15], v[148:151], v[202:205], v[12:15]
	v_mfma_f32_16x16x32_bf16 v[8:11], v[166:169], v[202:205], v[8:11]
	s_barrier
	s_add_u32 s60, s36, 0x40000
	s_addc_u32 s61, s37, 0
	s_add_i32 s62, s53, s44
	s_mov_b32 m0, s62
	v_lshl_add_u64 v[128:129], s[60:61], 0, v[134:135]
	global_load_lds_dwordx4 v[128:129], off
	s_add_i32 m0, s62, 0x2000
	v_lshl_add_u64 v[128:129], s[60:61], 0, v[138:139]
	global_load_lds_dwordx4 v[128:129], off
	s_waitcnt vmcnt(6)
	s_barrier
	v_mfma_f32_16x16x32_bf16 v[52:55], v[206:209], v[170:173], v[52:55]
	v_mfma_f32_16x16x32_bf16 v[48:51], v[214:217], v[170:173], v[48:51]
	v_mfma_f32_16x16x32_bf16 v[36:39], v[206:209], v[178:181], v[36:39]
	v_mfma_f32_16x16x32_bf16 v[32:35], v[214:217], v[178:181], v[32:35]
	v_mfma_f32_16x16x32_bf16 v[20:23], v[206:209], v[190:193], v[20:23]
	v_mfma_f32_16x16x32_bf16 v[16:19], v[214:217], v[190:193], v[16:19]
	v_mfma_f32_16x16x32_bf16 v[4:7], v[206:209], v[198:201], v[4:7]
	v_mfma_f32_16x16x32_bf16 v[0:3], v[214:217], v[198:201], v[0:3]
	v_mfma_f32_16x16x32_bf16 v[52:55], v[210:213], v[174:177], v[52:55]
	v_mfma_f32_16x16x32_bf16 v[48:51], v[218:221], v[174:177], v[48:51]
	v_mfma_f32_16x16x32_bf16 v[36:39], v[210:213], v[182:185], v[36:39]
	v_mfma_f32_16x16x32_bf16 v[32:35], v[218:221], v[182:185], v[32:35]
	v_mfma_f32_16x16x32_bf16 v[20:23], v[210:213], v[194:197], v[20:23]
	v_mfma_f32_16x16x32_bf16 v[16:19], v[218:221], v[194:197], v[16:19]
	v_mfma_f32_16x16x32_bf16 v[4:7], v[210:213], v[202:205], v[4:7]
	v_mfma_f32_16x16x32_bf16 v[0:3], v[218:221], v[202:205], v[0:3]
	s_add_i32 s60, 0, 0x18000
	v_add_u32_e32 v158, s60, v160
	s_barrier
	ds_read_b128 v[128:131], v158
	ds_read_b128 v[148:151], v158 offset:1024
	ds_read_b128 v[152:155], v158 offset:2048
	ds_read_b128 v[166:169], v158 offset:3072
	s_add_u32 s38, s38, 0x40000
	s_addc_u32 s39, s39, 0
	s_mov_b32 m0, s46
	v_lshl_add_u64 v[206:207], s[38:39], 0, v[132:133]
	ds_read_b128 v[170:173], v163 offset:32768
	ds_read_b128 v[174:177], v163 offset:33792
	ds_read_b128 v[178:181], v163 offset:34816
	ds_read_b128 v[182:185], v163 offset:35840
	ds_read_b128 v[190:193], v163 offset:36864
	ds_read_b128 v[194:197], v163 offset:37888
	ds_read_b128 v[198:201], v163 offset:38912
	ds_read_b128 v[202:205], v163 offset:39936
	global_load_lds_dwordx4 v[206:207], off
	s_mov_b32 m0, s47
	v_lshl_add_u64 v[206:207], s[38:39], 0, v[136:137]
	global_load_lds_dwordx4 v[206:207], off
	s_waitcnt lgkmcnt(8)
	s_barrier
	s_waitcnt lgkmcnt(0)
	v_mfma_f32_16x16x32_bf16 v[124:127], v[128:131], v[170:173], v[124:127]
	v_mfma_f32_16x16x32_bf16 v[120:123], v[152:155], v[170:173], v[120:123]
	v_mfma_f32_16x16x32_bf16 v[108:111], v[128:131], v[178:181], v[108:111]
	v_mfma_f32_16x16x32_bf16 v[104:107], v[152:155], v[178:181], v[104:107]
	v_mfma_f32_16x16x32_bf16 v[92:95], v[128:131], v[190:193], v[92:95]
	v_mfma_f32_16x16x32_bf16 v[88:91], v[152:155], v[190:193], v[88:91]
	v_mfma_f32_16x16x32_bf16 v[76:79], v[128:131], v[198:201], v[76:79]
	v_mfma_f32_16x16x32_bf16 v[72:75], v[152:155], v[198:201], v[72:75]
	v_mfma_f32_16x16x32_bf16 v[124:127], v[148:151], v[174:177], v[124:127]
	v_mfma_f32_16x16x32_bf16 v[120:123], v[166:169], v[174:177], v[120:123]
	v_mfma_f32_16x16x32_bf16 v[108:111], v[148:151], v[182:185], v[108:111]
	v_mfma_f32_16x16x32_bf16 v[104:107], v[166:169], v[182:185], v[104:107]
	v_mfma_f32_16x16x32_bf16 v[92:95], v[148:151], v[194:197], v[92:95]
	v_mfma_f32_16x16x32_bf16 v[88:91], v[166:169], v[194:197], v[88:91]
	v_mfma_f32_16x16x32_bf16 v[76:79], v[148:151], v[202:205], v[76:79]
	v_mfma_f32_16x16x32_bf16 v[72:75], v[166:169], v[202:205], v[72:75]
	s_barrier
	s_add_i32 s38, 0, 0x1c000
	s_add_i32 s39, s60, s44
	v_add_u32_e32 v158, s38, v160
	v_lshl_add_u64 v[156:157], v[156:157], 0, s[8:9]
	s_mov_b32 m0, s39
	ds_read_b128 v[206:209], v158
	ds_read_b128 v[210:213], v158 offset:1024
	ds_read_b128 v[214:217], v158 offset:2048
	ds_read_b128 v[218:221], v158 offset:3072
	global_load_lds_dwordx4 v[156:157], off
	s_add_i32 m0, s39, 0x2000
	v_lshl_add_u64 v[156:157], v[186:187], 0, s[8:9]
	global_load_lds_dwordx4 v[156:157], off
	s_barrier
	s_waitcnt lgkmcnt(0)
	v_mfma_f32_16x16x32_bf16 v[116:119], v[206:209], v[170:173], v[116:119]
	v_mfma_f32_16x16x32_bf16 v[112:115], v[214:217], v[170:173], v[112:115]
	v_mfma_f32_16x16x32_bf16 v[100:103], v[206:209], v[178:181], v[100:103]
	v_mfma_f32_16x16x32_bf16 v[96:99], v[214:217], v[178:181], v[96:99]
	v_mfma_f32_16x16x32_bf16 v[84:87], v[206:209], v[190:193], v[84:87]
	v_mfma_f32_16x16x32_bf16 v[80:83], v[214:217], v[190:193], v[80:83]
	v_mfma_f32_16x16x32_bf16 v[68:71], v[206:209], v[198:201], v[68:71]
	v_mfma_f32_16x16x32_bf16 v[64:67], v[214:217], v[198:201], v[64:67]
	v_mfma_f32_16x16x32_bf16 v[116:119], v[210:213], v[174:177], v[116:119]
	v_mfma_f32_16x16x32_bf16 v[112:115], v[218:221], v[174:177], v[112:115]
	v_mfma_f32_16x16x32_bf16 v[100:103], v[210:213], v[182:185], v[100:103]
	v_mfma_f32_16x16x32_bf16 v[96:99], v[218:221], v[182:185], v[96:99]
	v_mfma_f32_16x16x32_bf16 v[84:87], v[210:213], v[194:197], v[84:87]
	v_mfma_f32_16x16x32_bf16 v[80:83], v[218:221], v[194:197], v[80:83]
	v_mfma_f32_16x16x32_bf16 v[68:71], v[210:213], v[202:205], v[68:71]
	v_mfma_f32_16x16x32_bf16 v[64:67], v[218:221], v[202:205], v[64:67]
	s_mov_b32 m0, s49
	v_lshl_add_u64 v[156:157], v[222:223], 0, s[8:9]
	s_barrier
	ds_read_b128 v[170:173], v163 offset:49152
	ds_read_b128 v[174:177], v163 offset:50176
	ds_read_b128 v[178:181], v163 offset:51200
	ds_read_b128 v[182:185], v163 offset:52224
	ds_read_b128 v[190:193], v163 offset:53248
	ds_read_b128 v[194:197], v163 offset:54272
	ds_read_b128 v[198:201], v163 offset:55296
	ds_read_b128 v[202:205], v163 offset:56320
	global_load_lds_dwordx4 v[156:157], off
	s_mov_b32 m0, s50
	v_lshl_add_u64 v[156:157], v[224:225], 0, s[8:9]
	global_load_lds_dwordx4 v[156:157], off
	s_barrier
	s_waitcnt lgkmcnt(0)
	v_mfma_f32_16x16x32_bf16 v[60:63], v[128:131], v[170:173], v[60:63]
	v_mfma_f32_16x16x32_bf16 v[56:59], v[152:155], v[170:173], v[56:59]
	v_mfma_f32_16x16x32_bf16 v[44:47], v[128:131], v[178:181], v[44:47]
	v_mfma_f32_16x16x32_bf16 v[40:43], v[152:155], v[178:181], v[40:43]
	v_mfma_f32_16x16x32_bf16 v[28:31], v[128:131], v[190:193], v[28:31]
	v_mfma_f32_16x16x32_bf16 v[24:27], v[152:155], v[190:193], v[24:27]
	v_mfma_f32_16x16x32_bf16 v[12:15], v[128:131], v[198:201], v[12:15]
	v_mfma_f32_16x16x32_bf16 v[8:11], v[152:155], v[198:201], v[8:11]
	v_mfma_f32_16x16x32_bf16 v[60:63], v[148:151], v[174:177], v[60:63]
	v_mfma_f32_16x16x32_bf16 v[56:59], v[166:169], v[174:177], v[56:59]
	v_mfma_f32_16x16x32_bf16 v[44:47], v[148:151], v[182:185], v[44:47]
	v_mfma_f32_16x16x32_bf16 v[40:43], v[166:169], v[182:185], v[40:43]
	v_mfma_f32_16x16x32_bf16 v[28:31], v[148:151], v[194:197], v[28:31]
	v_mfma_f32_16x16x32_bf16 v[24:27], v[166:169], v[194:197], v[24:27]
	v_mfma_f32_16x16x32_bf16 v[12:15], v[148:151], v[202:205], v[12:15]
	v_mfma_f32_16x16x32_bf16 v[8:11], v[166:169], v[202:205], v[8:11]
	s_barrier
	s_add_u32 s36, s36, 0x40080
	s_addc_u32 s37, s37, 0
	s_add_i32 s38, s38, s44
	s_mov_b32 m0, s38
	v_lshl_add_u64 v[128:129], s[36:37], 0, v[134:135]
	global_load_lds_dwordx4 v[128:129], off
	s_add_i32 m0, s38, 0x2000
	v_lshl_add_u64 v[128:129], s[36:37], 0, v[138:139]
	global_load_lds_dwordx4 v[128:129], off
	s_waitcnt vmcnt(6)
	s_barrier
	v_mfma_f32_16x16x32_bf16 v[52:55], v[206:209], v[170:173], v[52:55]
	v_mfma_f32_16x16x32_bf16 v[48:51], v[214:217], v[170:173], v[48:51]
	v_mfma_f32_16x16x32_bf16 v[36:39], v[206:209], v[178:181], v[36:39]
	v_mfma_f32_16x16x32_bf16 v[32:35], v[214:217], v[178:181], v[32:35]
	v_mfma_f32_16x16x32_bf16 v[20:23], v[206:209], v[190:193], v[20:23]
	v_mfma_f32_16x16x32_bf16 v[16:19], v[214:217], v[190:193], v[16:19]
	v_mfma_f32_16x16x32_bf16 v[4:7], v[206:209], v[198:201], v[4:7]
	v_mfma_f32_16x16x32_bf16 v[0:3], v[214:217], v[198:201], v[0:3]
	v_mfma_f32_16x16x32_bf16 v[52:55], v[210:213], v[174:177], v[52:55]
	v_mfma_f32_16x16x32_bf16 v[48:51], v[218:221], v[174:177], v[48:51]
	v_mfma_f32_16x16x32_bf16 v[36:39], v[210:213], v[182:185], v[36:39]
	v_mfma_f32_16x16x32_bf16 v[32:35], v[218:221], v[182:185], v[32:35]
	v_mfma_f32_16x16x32_bf16 v[20:23], v[210:213], v[194:197], v[20:23]
	v_mfma_f32_16x16x32_bf16 v[16:19], v[218:221], v[194:197], v[16:19]
	v_mfma_f32_16x16x32_bf16 v[4:7], v[210:213], v[202:205], v[4:7]
	v_mfma_f32_16x16x32_bf16 v[0:3], v[218:221], v[202:205], v[0:3]
	s_add_i32 s59, s59, 2
	s_add_u32 s34, s34, 0x100
	s_addc_u32 s35, s35, 0
	s_add_u32 s57, s57, 0x100
	s_addc_u32 s58, s58, 0
	s_cmp_gt_u32 s59, 13
	s_barrier
	s_cbranch_scc0 .LBB0_286
	v_lshl_add_u32 v128, s30, 8, v159
	v_or_b32_e32 v156, 16, v128
	v_lshl_or_b32 v130, s54, 8, v161
	v_ashrrev_i32_e32 v129, 31, v128
	v_ashrrev_i32_e32 v157, 31, v156
	v_ashrrev_i32_e32 v131, 31, v130
	v_lshl_add_u64 v[152:153], v[128:129], 2, s[10:11]
	v_lshlrev_b64 v[154:155], 11, v[128:129]
	v_lshl_add_u64 v[170:171], v[156:157], 2, s[10:11]
	v_lshlrev_b64 v[186:187], 11, v[156:157]
	v_or_b32_e32 v156, 32, v128
	v_or_b32_e32 v128, 48, v128
	v_lshlrev_b64 v[148:149], 1, v[130:131]
	v_ashrrev_i32_e32 v157, 31, v156
	v_ashrrev_i32_e32 v129, 31, v128
	v_lshl_add_u64 v[150:151], s[0:1], 0, v[148:149]
	v_lshl_add_u64 v[182:183], v[156:157], 2, s[10:11]
	v_lshlrev_b64 v[198:199], 11, v[156:157]
	v_lshlrev_b64 v[156:157], 11, v[128:129]
	v_lshl_add_u64 v[130:131], v[150:151], 0, v[154:155]
	v_lshl_add_u64 v[178:179], v[150:151], 0, v[186:187]
	v_lshl_add_u64 v[190:191], v[150:151], 0, v[198:199]
	v_lshl_add_u64 v[192:193], v[128:129], 2, s[10:11]
	v_lshl_add_u64 v[128:129], v[150:151], 0, v[156:157]
	global_load_dword v200, v[152:153], off
	global_load_dwordx4 v[166:169], v[130:131], off
	global_load_dword v202, v[170:171], off
	s_nop 0
	global_load_dwordx4 v[170:173], v[130:131], off offset:256
	global_load_dwordx4 v[174:177], v[178:179], off
	s_nop 0
	global_load_dwordx4 v[178:181], v[178:179], off offset:256
	s_nop 0
	global_load_dword v204, v[182:183], off
	s_nop 0
	global_load_dwordx4 v[182:185], v[190:191], off
	global_load_dword v158, v[192:193], off
	s_nop 0
	global_load_dwordx4 v[190:193], v[190:191], off offset:256
	s_nop 0
	global_load_dwordx4 v[194:197], v[128:129], off
	s_nop 0
	global_load_dwordx4 v[128:131], v[128:129], off offset:256
	global_load_dword v216, v[152:153], off offset:512
	global_load_dword v218, v[152:153], off offset:576
	global_load_dword v220, v[152:153], off offset:640
	v_lshl_add_u64 v[252:253], v[154:155], 0, s[6:7]
	v_lshl_add_u64 v[252:253], v[150:151], 0, v[252:253]
	global_load_dwordx4 v[236:239], v[252:253], off
	global_load_dwordx4 v[240:243], v[252:253], off offset:256
	v_lshl_add_u64 v[252:253], v[154:155], 0, s[12:13]
	v_lshl_add_u64 v[252:253], v[150:151], 0, v[252:253]
	global_load_dwordx4 v[244:247], v[252:253], off
	global_load_dwordx4 v[248:251], v[252:253], off offset:256
	v_lshl_add_u64 v[252:253], v[154:155], 0, s[14:15]
	v_lshl_add_u64 v[252:253], v[150:151], 0, v[252:253]
	global_load_dwordx4 v[208:211], v[252:253], off
	global_load_dwordx4 v[212:215], v[252:253], off offset:256
	global_load_dword v252, v[152:153], off offset:704
	s_waitcnt vmcnt(10)
	v_pk_mul_f32 v[124:125], v[124:125], v[200:201] op_sel_hi:[1,0]
	v_pk_mul_f32 v[206:207], v[122:123], v[200:201] op_sel_hi:[1,0]
	v_pk_mul_f32 v[122:123], v[120:121], v[200:201] op_sel_hi:[1,0]
	v_lshlrev_b32_e32 v120, 16, v166
	v_and_b32_e32 v121, 0xffff0000, v166
	v_mul_f32_e32 v120, v124, v120
	v_mul_f32_e32 v121, v125, v121
	v_pk_mul_f32 v[126:127], v[126:127], v[200:201] op_sel_hi:[1,0]
	v_cvt_pk_bf16_f32 v120, v120, v121
	v_lshlrev_b32_e32 v121, 16, v167
	v_and_b32_e32 v124, 0xffff0000, v167
	v_mul_f32_e32 v121, v126, v121
	v_mul_f32_e32 v124, v127, v124
	v_cvt_pk_bf16_f32 v121, v121, v124
	v_lshlrev_b32_e32 v124, 16, v168
	v_mul_f32_e32 v122, v122, v124
	v_and_b32_e32 v124, 0xffff0000, v168
	v_mul_f32_e32 v123, v123, v124
	v_cvt_pk_bf16_f32 v122, v122, v123
	v_lshlrev_b32_e32 v123, 16, v169
	v_and_b32_e32 v124, 0xffff0000, v169
	v_mul_f32_e32 v123, v206, v123
	v_mul_f32_e32 v124, v207, v124
	v_cvt_pk_bf16_f32 v123, v123, v124
	v_lshl_add_u64 v[124:125], s[26:27], 0, v[154:155]
	v_lshl_add_u64 v[124:125], v[124:125], 0, v[148:149]
	global_store_dwordx4 v[124:125], v[120:123], off
	v_pk_mul_f32 v[116:117], v[116:117], v[200:201] op_sel_hi:[1,0]
	v_pk_mul_f32 v[118:119], v[118:119], v[200:201] op_sel_hi:[1,0]
	v_pk_mul_f32 v[120:121], v[114:115], v[200:201] op_sel_hi:[1,0]
	v_pk_mul_f32 v[114:115], v[112:113], v[200:201] op_sel_hi:[1,0]
	v_lshlrev_b32_e32 v112, 16, v170
	v_and_b32_e32 v113, 0xffff0000, v170
	v_mul_f32_e32 v112, v116, v112
	v_mul_f32_e32 v113, v117, v113
	v_cvt_pk_bf16_f32 v112, v112, v113
	v_lshlrev_b32_e32 v113, 16, v171
	v_and_b32_e32 v116, 0xffff0000, v171
	v_mul_f32_e32 v113, v118, v113
	v_mul_f32_e32 v116, v119, v116
	v_cvt_pk_bf16_f32 v113, v113, v116
	v_lshlrev_b32_e32 v116, 16, v172
	v_mul_f32_e32 v114, v114, v116
	v_and_b32_e32 v116, 0xffff0000, v172
	v_mul_f32_e32 v115, v115, v116
	v_cvt_pk_bf16_f32 v114, v114, v115
	v_lshlrev_b32_e32 v115, 16, v173
	v_mul_f32_e32 v115, v120, v115
	v_and_b32_e32 v116, 0xffff0000, v173
	v_mul_f32_e32 v116, v121, v116
	v_cvt_pk_bf16_f32 v115, v115, v116
	global_store_dwordx4 v[124:125], v[112:115], off offset:256
	v_pk_mul_f32 v[108:109], v[108:109], v[202:203] op_sel_hi:[1,0]
	v_pk_mul_f32 v[110:111], v[110:111], v[202:203] op_sel_hi:[1,0]
	v_pk_mul_f32 v[112:113], v[106:107], v[202:203] op_sel_hi:[1,0]
	v_pk_mul_f32 v[106:107], v[104:105], v[202:203] op_sel_hi:[1,0]
	v_lshlrev_b32_e32 v104, 16, v174
	v_and_b32_e32 v105, 0xffff0000, v174
	v_mul_f32_e32 v104, v108, v104
	v_mul_f32_e32 v105, v109, v105
	v_cvt_pk_bf16_f32 v104, v104, v105
	v_lshlrev_b32_e32 v105, 16, v175
	v_and_b32_e32 v108, 0xffff0000, v175
	v_mul_f32_e32 v105, v110, v105
	v_mul_f32_e32 v108, v111, v108
	v_cvt_pk_bf16_f32 v105, v105, v108
	v_lshlrev_b32_e32 v108, 16, v176
	v_mul_f32_e32 v106, v106, v108
	v_and_b32_e32 v108, 0xffff0000, v176
	v_mul_f32_e32 v107, v107, v108
	v_cvt_pk_bf16_f32 v106, v106, v107
	v_lshlrev_b32_e32 v107, 16, v177
	v_and_b32_e32 v108, 0xffff0000, v177
	v_mul_f32_e32 v107, v112, v107
	v_mul_f32_e32 v108, v113, v108
	v_cvt_pk_bf16_f32 v107, v107, v108
	v_lshl_add_u64 v[108:109], s[26:27], 0, v[186:187]
	v_lshl_add_u64 v[108:109], v[108:109], 0, v[148:149]
	global_store_dwordx4 v[108:109], v[104:107], off
	v_pk_mul_f32 v[100:101], v[100:101], v[202:203] op_sel_hi:[1,0]
	v_pk_mul_f32 v[102:103], v[102:103], v[202:203] op_sel_hi:[1,0]
	v_pk_mul_f32 v[104:105], v[98:99], v[202:203] op_sel_hi:[1,0]
	v_pk_mul_f32 v[98:99], v[96:97], v[202:203] op_sel_hi:[1,0]
	v_lshlrev_b32_e32 v96, 16, v178
	v_and_b32_e32 v97, 0xffff0000, v178
	v_mul_f32_e32 v96, v100, v96
	v_mul_f32_e32 v97, v101, v97
	v_cvt_pk_bf16_f32 v96, v96, v97
	v_lshlrev_b32_e32 v97, 16, v179
	v_and_b32_e32 v100, 0xffff0000, v179
	v_mul_f32_e32 v97, v102, v97
	v_mul_f32_e32 v100, v103, v100
	v_cvt_pk_bf16_f32 v97, v97, v100
	v_lshlrev_b32_e32 v100, 16, v180
	v_mul_f32_e32 v98, v98, v100
	v_and_b32_e32 v100, 0xffff0000, v180
	v_mul_f32_e32 v99, v99, v100
	v_cvt_pk_bf16_f32 v98, v98, v99
	v_lshlrev_b32_e32 v99, 16, v181
	v_mul_f32_e32 v99, v104, v99
	v_and_b32_e32 v100, 0xffff0000, v181
	v_mul_f32_e32 v100, v105, v100
	v_cvt_pk_bf16_f32 v99, v99, v100
	global_store_dwordx4 v[108:109], v[96:99], off offset:256
	v_pk_mul_f32 v[92:93], v[92:93], v[204:205] op_sel_hi:[1,0]
	v_pk_mul_f32 v[94:95], v[94:95], v[204:205] op_sel_hi:[1,0]
	v_pk_mul_f32 v[96:97], v[90:91], v[204:205] op_sel_hi:[1,0]
	v_pk_mul_f32 v[90:91], v[88:89], v[204:205] op_sel_hi:[1,0]
	v_lshlrev_b32_e32 v88, 16, v182
	v_and_b32_e32 v89, 0xffff0000, v182
	v_mul_f32_e32 v88, v92, v88
	v_mul_f32_e32 v89, v93, v89
	v_cvt_pk_bf16_f32 v88, v88, v89
	v_lshlrev_b32_e32 v89, 16, v183
	v_and_b32_e32 v92, 0xffff0000, v183
	v_mul_f32_e32 v89, v94, v89
	v_mul_f32_e32 v92, v95, v92
	v_cvt_pk_bf16_f32 v89, v89, v92
	v_lshlrev_b32_e32 v92, 16, v184
	v_mul_f32_e32 v90, v90, v92
	v_and_b32_e32 v92, 0xffff0000, v184
	v_mul_f32_e32 v91, v91, v92
	v_cvt_pk_bf16_f32 v90, v90, v91
	v_lshlrev_b32_e32 v91, 16, v185
	v_and_b32_e32 v92, 0xffff0000, v185
	v_mul_f32_e32 v91, v96, v91
	v_mul_f32_e32 v92, v97, v92
	v_cvt_pk_bf16_f32 v91, v91, v92
	v_lshl_add_u64 v[92:93], s[26:27], 0, v[198:199]
	v_lshl_add_u64 v[92:93], v[92:93], 0, v[148:149]
	global_store_dwordx4 v[92:93], v[88:91], off
	v_pk_mul_f32 v[84:85], v[84:85], v[204:205] op_sel_hi:[1,0]
	v_pk_mul_f32 v[86:87], v[86:87], v[204:205] op_sel_hi:[1,0]
	v_pk_mul_f32 v[88:89], v[82:83], v[204:205] op_sel_hi:[1,0]
	v_pk_mul_f32 v[82:83], v[80:81], v[204:205] op_sel_hi:[1,0]
	v_lshlrev_b32_e32 v80, 16, v190
	v_and_b32_e32 v81, 0xffff0000, v190
	v_mul_f32_e32 v80, v84, v80
	v_mul_f32_e32 v81, v85, v81
	v_cvt_pk_bf16_f32 v80, v80, v81
	v_lshlrev_b32_e32 v81, 16, v191
	v_and_b32_e32 v84, 0xffff0000, v191
	v_mul_f32_e32 v81, v86, v81
	v_mul_f32_e32 v84, v87, v84
	v_cvt_pk_bf16_f32 v81, v81, v84
	v_lshlrev_b32_e32 v84, 16, v192
	v_mul_f32_e32 v82, v82, v84
	v_and_b32_e32 v84, 0xffff0000, v192
	v_mul_f32_e32 v83, v83, v84
	v_cvt_pk_bf16_f32 v82, v82, v83
	v_lshlrev_b32_e32 v83, 16, v193
	v_mul_f32_e32 v83, v88, v83
	v_and_b32_e32 v84, 0xffff0000, v193
	v_mul_f32_e32 v84, v89, v84
	v_cvt_pk_bf16_f32 v83, v83, v84
	global_store_dwordx4 v[92:93], v[80:83], off offset:256
	v_pk_mul_f32 v[76:77], v[76:77], v[158:159] op_sel_hi:[1,0]
	v_pk_mul_f32 v[78:79], v[78:79], v[158:159] op_sel_hi:[1,0]
	v_pk_mul_f32 v[80:81], v[74:75], v[158:159] op_sel_hi:[1,0]
	v_pk_mul_f32 v[74:75], v[72:73], v[158:159] op_sel_hi:[1,0]
	v_lshlrev_b32_e32 v72, 16, v194
	v_and_b32_e32 v73, 0xffff0000, v194
	v_mul_f32_e32 v72, v76, v72
	v_mul_f32_e32 v73, v77, v73
	v_cvt_pk_bf16_f32 v72, v72, v73
	v_lshlrev_b32_e32 v73, 16, v195
	v_and_b32_e32 v76, 0xffff0000, v195
	v_mul_f32_e32 v73, v78, v73
	v_mul_f32_e32 v76, v79, v76
	v_cvt_pk_bf16_f32 v73, v73, v76
	v_lshlrev_b32_e32 v76, 16, v196
	v_mul_f32_e32 v74, v74, v76
	v_and_b32_e32 v76, 0xffff0000, v196
	v_mul_f32_e32 v75, v75, v76
	v_cvt_pk_bf16_f32 v74, v74, v75
	v_lshlrev_b32_e32 v75, 16, v197
	v_and_b32_e32 v76, 0xffff0000, v197
	v_mul_f32_e32 v75, v80, v75
	v_mul_f32_e32 v76, v81, v76
	v_cvt_pk_bf16_f32 v75, v75, v76
	v_lshl_add_u64 v[76:77], s[26:27], 0, v[156:157]
	v_lshl_add_u64 v[76:77], v[76:77], 0, v[148:149]
	global_store_dwordx4 v[76:77], v[72:75], off
	v_pk_mul_f32 v[68:69], v[68:69], v[158:159] op_sel_hi:[1,0]
	v_pk_mul_f32 v[70:71], v[70:71], v[158:159] op_sel_hi:[1,0]
	v_pk_mul_f32 v[72:73], v[66:67], v[158:159] op_sel_hi:[1,0]
	v_pk_mul_f32 v[66:67], v[64:65], v[158:159] op_sel_hi:[1,0]
	v_lshlrev_b32_e32 v64, 16, v128
	v_and_b32_e32 v65, 0xffff0000, v128
	v_mul_f32_e32 v64, v68, v64
	v_mul_f32_e32 v65, v69, v65
	v_cvt_pk_bf16_f32 v64, v64, v65
	v_lshlrev_b32_e32 v65, 16, v129
	v_and_b32_e32 v68, 0xffff0000, v129
	v_mul_f32_e32 v65, v70, v65
	v_mul_f32_e32 v68, v71, v68
	v_cvt_pk_bf16_f32 v65, v65, v68
	v_lshlrev_b32_e32 v68, 16, v130
	v_mul_f32_e32 v66, v66, v68
	v_and_b32_e32 v68, 0xffff0000, v130
	v_mul_f32_e32 v67, v67, v68
	v_cvt_pk_bf16_f32 v66, v66, v67
	v_lshlrev_b32_e32 v67, 16, v131
	v_mul_f32_e32 v67, v72, v67
	v_and_b32_e32 v68, 0xffff0000, v131
	v_mul_f32_e32 v68, v73, v68
	v_cvt_pk_bf16_f32 v67, v67, v68
	v_lshl_add_u64 v[100:101], v[154:155], 0, s[6:7]
	v_lshl_add_u64 v[102:103], v[154:155], 0, s[12:13]
	v_lshl_add_u64 v[104:105], v[154:155], 0, s[14:15]
	global_store_dwordx4 v[76:77], v[64:67], off offset:256
	v_lshl_add_u64 v[92:93], v[150:151], 0, v[104:105]
	v_lshl_add_u64 v[70:71], v[154:155], 0, s[18:19]
	v_lshl_add_u64 v[64:65], v[150:151], 0, v[100:101]
	v_lshl_add_u64 v[66:67], v[150:151], 0, v[102:103]
	v_lshl_add_u64 v[112:113], v[150:151], 0, v[70:71]
	s_nop 0
	s_nop 0
	global_load_dwordx4 v[96:99], v[112:113], off
	global_load_dwordx4 v[64:67], v[112:113], off offset:256
	s_waitcnt vmcnt(10)
	v_pk_mul_f32 v[60:61], v[60:61], v[216:217] op_sel_hi:[1,0]
	v_pk_mul_f32 v[112:113], v[58:59], v[216:217] op_sel_hi:[1,0]
	v_pk_mul_f32 v[58:59], v[56:57], v[216:217] op_sel_hi:[1,0]
	v_lshlrev_b32_e32 v56, 16, v236
	v_and_b32_e32 v57, 0xffff0000, v236
	v_mul_f32_e32 v56, v60, v56
	v_mul_f32_e32 v57, v61, v57
	v_pk_mul_f32 v[62:63], v[62:63], v[216:217] op_sel_hi:[1,0]
	v_cvt_pk_bf16_f32 v56, v56, v57
	v_lshlrev_b32_e32 v57, 16, v237
	v_and_b32_e32 v60, 0xffff0000, v237
	v_mul_f32_e32 v57, v62, v57
	v_mul_f32_e32 v60, v63, v60
	v_cvt_pk_bf16_f32 v57, v57, v60
	v_lshlrev_b32_e32 v60, 16, v238
	v_mul_f32_e32 v58, v58, v60
	v_and_b32_e32 v60, 0xffff0000, v238
	v_mul_f32_e32 v59, v59, v60
	v_cvt_pk_bf16_f32 v58, v58, v59
	v_lshlrev_b32_e32 v59, 16, v239
	v_and_b32_e32 v60, 0xffff0000, v239
	v_mul_f32_e32 v59, v112, v59
	v_mul_f32_e32 v60, v113, v60
	v_cvt_pk_bf16_f32 v59, v59, v60
	v_lshl_add_u64 v[60:61], s[26:27], 0, v[100:101]
	v_lshl_add_u64 v[60:61], v[60:61], 0, v[148:149]
	global_store_dwordx4 v[60:61], v[56:59], off
	v_pk_mul_f32 v[52:53], v[52:53], v[216:217] op_sel_hi:[1,0]
	v_pk_mul_f32 v[54:55], v[54:55], v[216:217] op_sel_hi:[1,0]
	v_pk_mul_f32 v[56:57], v[50:51], v[216:217] op_sel_hi:[1,0]
	v_pk_mul_f32 v[50:51], v[48:49], v[216:217] op_sel_hi:[1,0]
	v_lshlrev_b32_e32 v48, 16, v240
	v_and_b32_e32 v49, 0xffff0000, v240
	v_mul_f32_e32 v48, v52, v48
	v_mul_f32_e32 v49, v53, v49
	v_cvt_pk_bf16_f32 v48, v48, v49
	v_lshlrev_b32_e32 v49, 16, v241
	v_and_b32_e32 v52, 0xffff0000, v241
	v_mul_f32_e32 v49, v54, v49
	v_mul_f32_e32 v52, v55, v52
	v_cvt_pk_bf16_f32 v49, v49, v52
	v_lshlrev_b32_e32 v52, 16, v242
	v_mul_f32_e32 v50, v50, v52
	v_and_b32_e32 v52, 0xffff0000, v242
	v_mul_f32_e32 v51, v51, v52
	v_cvt_pk_bf16_f32 v50, v50, v51
	v_lshlrev_b32_e32 v51, 16, v243
	v_mul_f32_e32 v51, v56, v51
	v_and_b32_e32 v52, 0xffff0000, v243
	v_mul_f32_e32 v52, v57, v52
	v_cvt_pk_bf16_f32 v51, v51, v52
	global_store_dwordx4 v[60:61], v[48:51], off offset:256
	v_pk_mul_f32 v[44:45], v[44:45], v[218:219] op_sel_hi:[1,0]
	v_pk_mul_f32 v[46:47], v[46:47], v[218:219] op_sel_hi:[1,0]
	v_pk_mul_f32 v[48:49], v[42:43], v[218:219] op_sel_hi:[1,0]
	v_pk_mul_f32 v[42:43], v[40:41], v[218:219] op_sel_hi:[1,0]
	v_lshlrev_b32_e32 v40, 16, v244
	v_and_b32_e32 v41, 0xffff0000, v244
	v_mul_f32_e32 v40, v44, v40
	v_mul_f32_e32 v41, v45, v41
	v_cvt_pk_bf16_f32 v40, v40, v41
	v_lshlrev_b32_e32 v41, 16, v245
	v_and_b32_e32 v44, 0xffff0000, v245
	v_mul_f32_e32 v41, v46, v41
	v_mul_f32_e32 v44, v47, v44
	v_cvt_pk_bf16_f32 v41, v41, v44
	v_lshlrev_b32_e32 v44, 16, v246
	v_mul_f32_e32 v42, v42, v44
	v_and_b32_e32 v44, 0xffff0000, v246
	v_mul_f32_e32 v43, v43, v44
	v_cvt_pk_bf16_f32 v42, v42, v43
	v_lshlrev_b32_e32 v43, 16, v247
	v_and_b32_e32 v44, 0xffff0000, v247
	v_mul_f32_e32 v43, v48, v43
	v_mul_f32_e32 v44, v49, v44
	v_cvt_pk_bf16_f32 v43, v43, v44
	v_lshl_add_u64 v[44:45], s[26:27], 0, v[102:103]
	v_lshl_add_u64 v[44:45], v[44:45], 0, v[148:149]
	global_store_dwordx4 v[44:45], v[40:43], off
	v_pk_mul_f32 v[36:37], v[36:37], v[218:219] op_sel_hi:[1,0]
	v_pk_mul_f32 v[38:39], v[38:39], v[218:219] op_sel_hi:[1,0]
	v_pk_mul_f32 v[40:41], v[34:35], v[218:219] op_sel_hi:[1,0]
	v_pk_mul_f32 v[34:35], v[32:33], v[218:219] op_sel_hi:[1,0]
	v_lshlrev_b32_e32 v32, 16, v248
	v_and_b32_e32 v33, 0xffff0000, v248
	v_mul_f32_e32 v32, v36, v32
	v_mul_f32_e32 v33, v37, v33
	v_cvt_pk_bf16_f32 v32, v32, v33
	v_lshlrev_b32_e32 v33, 16, v249
	v_and_b32_e32 v36, 0xffff0000, v249
	v_mul_f32_e32 v33, v38, v33
	v_mul_f32_e32 v36, v39, v36
	v_cvt_pk_bf16_f32 v33, v33, v36
	v_lshlrev_b32_e32 v36, 16, v250
	v_mul_f32_e32 v34, v34, v36
	v_and_b32_e32 v36, 0xffff0000, v250
	v_mul_f32_e32 v35, v35, v36
	v_cvt_pk_bf16_f32 v34, v34, v35
	v_lshlrev_b32_e32 v35, 16, v251
	v_mul_f32_e32 v35, v40, v35
	v_and_b32_e32 v36, 0xffff0000, v251
	v_mul_f32_e32 v36, v41, v36
	v_cvt_pk_bf16_f32 v35, v35, v36
	global_store_dwordx4 v[44:45], v[32:35], off offset:256
	v_pk_mul_f32 v[28:29], v[28:29], v[220:221] op_sel_hi:[1,0]
	v_pk_mul_f32 v[30:31], v[30:31], v[220:221] op_sel_hi:[1,0]
	v_pk_mul_f32 v[32:33], v[26:27], v[220:221] op_sel_hi:[1,0]
	v_pk_mul_f32 v[26:27], v[24:25], v[220:221] op_sel_hi:[1,0]
	v_lshlrev_b32_e32 v24, 16, v208
	v_and_b32_e32 v25, 0xffff0000, v208
	v_mul_f32_e32 v24, v28, v24
	v_mul_f32_e32 v25, v29, v25
	v_cvt_pk_bf16_f32 v24, v24, v25
	v_lshlrev_b32_e32 v25, 16, v209
	v_and_b32_e32 v28, 0xffff0000, v209
	v_mul_f32_e32 v25, v30, v25
	v_mul_f32_e32 v28, v31, v28
	v_cvt_pk_bf16_f32 v25, v25, v28
	v_lshlrev_b32_e32 v28, 16, v210
	v_mul_f32_e32 v26, v26, v28
	v_and_b32_e32 v28, 0xffff0000, v210
	v_mul_f32_e32 v27, v27, v28
	v_cvt_pk_bf16_f32 v26, v26, v27
	v_lshlrev_b32_e32 v27, 16, v211
	v_and_b32_e32 v28, 0xffff0000, v211
	v_mul_f32_e32 v27, v32, v27
	v_mul_f32_e32 v28, v33, v28
	v_cvt_pk_bf16_f32 v27, v27, v28
	v_lshl_add_u64 v[28:29], s[26:27], 0, v[104:105]
	v_lshl_add_u64 v[28:29], v[28:29], 0, v[148:149]
	global_store_dwordx4 v[28:29], v[24:27], off
	v_pk_mul_f32 v[20:21], v[20:21], v[220:221] op_sel_hi:[1,0]
	v_pk_mul_f32 v[22:23], v[22:23], v[220:221] op_sel_hi:[1,0]
	v_pk_mul_f32 v[24:25], v[18:19], v[220:221] op_sel_hi:[1,0]
	v_pk_mul_f32 v[18:19], v[16:17], v[220:221] op_sel_hi:[1,0]
	v_lshlrev_b32_e32 v16, 16, v212
	v_and_b32_e32 v17, 0xffff0000, v212
	v_mul_f32_e32 v16, v20, v16
	v_mul_f32_e32 v17, v21, v17
	v_cvt_pk_bf16_f32 v16, v16, v17
	v_lshlrev_b32_e32 v17, 16, v213
	v_and_b32_e32 v20, 0xffff0000, v213
	v_mul_f32_e32 v17, v22, v17
	v_mul_f32_e32 v20, v23, v20
	v_cvt_pk_bf16_f32 v17, v17, v20
	v_lshlrev_b32_e32 v20, 16, v214
	v_mul_f32_e32 v18, v18, v20
	v_and_b32_e32 v20, 0xffff0000, v214
	v_mul_f32_e32 v19, v19, v20
	v_cvt_pk_bf16_f32 v18, v18, v19
	v_lshlrev_b32_e32 v19, 16, v215
	v_mul_f32_e32 v19, v24, v19
	v_and_b32_e32 v20, 0xffff0000, v215
	v_mul_f32_e32 v20, v25, v20
	v_cvt_pk_bf16_f32 v19, v19, v20
	global_store_dwordx4 v[28:29], v[16:19], off offset:256
	s_waitcnt vmcnt(6)
	v_pk_mul_f32 v[12:13], v[12:13], v[252:253] op_sel_hi:[1,0]
	v_pk_mul_f32 v[14:15], v[14:15], v[252:253] op_sel_hi:[1,0]
	v_pk_mul_f32 v[16:17], v[10:11], v[252:253] op_sel_hi:[1,0]
	v_pk_mul_f32 v[10:11], v[8:9], v[252:253] op_sel_hi:[1,0]
	v_lshlrev_b32_e32 v8, 16, v96
	v_and_b32_e32 v9, 0xffff0000, v96
	v_mul_f32_e32 v8, v12, v8
	v_mul_f32_e32 v9, v13, v9
	v_cvt_pk_bf16_f32 v8, v8, v9
	v_lshlrev_b32_e32 v9, 16, v97
	v_and_b32_e32 v12, 0xffff0000, v97
	v_mul_f32_e32 v9, v14, v9
	v_mul_f32_e32 v12, v15, v12
	v_cvt_pk_bf16_f32 v9, v9, v12
	v_lshlrev_b32_e32 v12, 16, v98
	v_mul_f32_e32 v10, v10, v12
	v_and_b32_e32 v12, 0xffff0000, v98
	v_mul_f32_e32 v11, v11, v12
	v_cvt_pk_bf16_f32 v10, v10, v11
	v_lshlrev_b32_e32 v11, 16, v99
	v_and_b32_e32 v12, 0xffff0000, v99
	v_mul_f32_e32 v11, v16, v11
	v_mul_f32_e32 v12, v17, v12
	v_cvt_pk_bf16_f32 v11, v11, v12
	v_lshl_add_u64 v[12:13], s[26:27], 0, v[70:71]
	v_lshl_add_u64 v[12:13], v[12:13], 0, v[148:149]
	global_store_dwordx4 v[12:13], v[8:11], off
	v_pk_mul_f32 v[4:5], v[4:5], v[252:253] op_sel_hi:[1,0]
	v_pk_mul_f32 v[6:7], v[6:7], v[252:253] op_sel_hi:[1,0]
	v_pk_mul_f32 v[8:9], v[2:3], v[252:253] op_sel_hi:[1,0]
	v_pk_mul_f32 v[2:3], v[0:1], v[252:253] op_sel_hi:[1,0]
	v_lshlrev_b32_e32 v0, 16, v64
	v_and_b32_e32 v1, 0xffff0000, v64
	v_mul_f32_e32 v0, v4, v0
	v_mul_f32_e32 v1, v5, v1
	v_cvt_pk_bf16_f32 v0, v0, v1
	v_lshlrev_b32_e32 v1, 16, v65
	v_and_b32_e32 v4, 0xffff0000, v65
	v_mul_f32_e32 v1, v6, v1
	v_mul_f32_e32 v4, v7, v4
	v_cvt_pk_bf16_f32 v1, v1, v4
	v_lshlrev_b32_e32 v4, 16, v66
	v_mul_f32_e32 v2, v2, v4
	v_and_b32_e32 v4, 0xffff0000, v66
	v_mul_f32_e32 v3, v3, v4
	v_cvt_pk_bf16_f32 v2, v2, v3
	v_lshlrev_b32_e32 v3, 16, v67
	v_mul_f32_e32 v3, v8, v3
	v_and_b32_e32 v4, 0xffff0000, v67
	s_and_b64 vcc, exec, s[2:3]
	s_mov_b32 s54, s20
	s_mov_b32 s30, s22
	s_mov_b64 s[36:37], s[28:29]
	s_mov_b64 s[34:35], s[24:25]
	v_mul_f32_e32 v4, v9, v4
	v_cvt_pk_bf16_f32 v3, v3, v4
	global_store_dwordx4 v[12:13], v[0:3], off offset:256
	s_cbranch_vccz .LBB0_279
	s_waitcnt vmcnt(0)
	s_cmpk_gt_u32 s40, 0xff
	s_cbranch_scc1 .LBB0_290
	s_barrier

.LBB0_364:
	ds_read_b128 v[128:131], v208
	ds_read_b128 v[132:135], v208 offset:1024
	ds_read_b128 v[136:139], v208 offset:2048
	ds_read_b128 v[140:143], v208 offset:3072
	s_add_u32 s24, s22, 0xfffc0080
	s_addc_u32 s25, s23, -1
	s_cmp_eq_u32 s51, 12
	s_cselect_b32 s29, s13, s25
	s_cselect_b32 s28, s21, s24
	s_cselect_b32 s25, s11, s50
	s_cselect_b32 s24, s48, s49
	v_lshl_add_u64 v[194:195], s[22:23], 0, v[184:185]
	s_add_i32 m0, s36, 0xc000
	ds_read_b128 v[144:147], v209
	ds_read_b128 v[148:151], v209 offset:1024
	ds_read_b128 v[152:155], v209 offset:2048
	ds_read_b128 v[156:159], v209 offset:3072
	ds_read_b128 v[160:163], v209 offset:4096
	ds_read_b128 v[164:167], v209 offset:5120
	ds_read_b128 v[168:171], v209 offset:6144
	ds_read_b128 v[172:175], v209 offset:7168
	global_load_lds_dwordx4 v[194:195], off
	s_add_i32 m0, s36, 0xe000
	v_lshl_add_u64 v[194:195], s[22:23], 0, v[186:187]
	global_load_lds_dwordx4 v[194:195], off
	s_waitcnt lgkmcnt(8)
	s_barrier
	s_waitcnt lgkmcnt(0)
	v_mfma_f32_16x16x32_bf16 v[124:127], v[128:131], v[144:147], v[124:127]
	v_mfma_f32_16x16x32_bf16 v[120:123], v[136:139], v[144:147], v[120:123]
	v_mfma_f32_16x16x32_bf16 v[108:111], v[128:131], v[152:155], v[108:111]
	v_mfma_f32_16x16x32_bf16 v[104:107], v[136:139], v[152:155], v[104:107]
	v_mfma_f32_16x16x32_bf16 v[92:95], v[128:131], v[160:163], v[92:95]
	v_mfma_f32_16x16x32_bf16 v[88:91], v[136:139], v[160:163], v[88:91]
	v_mfma_f32_16x16x32_bf16 v[76:79], v[128:131], v[168:171], v[76:79]
	v_mfma_f32_16x16x32_bf16 v[72:75], v[136:139], v[168:171], v[72:75]
	v_mfma_f32_16x16x32_bf16 v[124:127], v[132:135], v[148:151], v[124:127]
	v_mfma_f32_16x16x32_bf16 v[120:123], v[140:143], v[148:151], v[120:123]
	v_mfma_f32_16x16x32_bf16 v[108:111], v[132:135], v[156:159], v[108:111]
	v_mfma_f32_16x16x32_bf16 v[104:107], v[140:143], v[156:159], v[104:107]
	v_mfma_f32_16x16x32_bf16 v[92:95], v[132:135], v[164:167], v[92:95]
	v_mfma_f32_16x16x32_bf16 v[88:91], v[140:143], v[164:167], v[88:91]
	v_mfma_f32_16x16x32_bf16 v[76:79], v[132:135], v[172:175], v[76:79]
	v_mfma_f32_16x16x32_bf16 v[72:75], v[140:143], v[172:175], v[72:75]
	s_barrier
	s_add_i32 s52, s45, s35
	v_lshl_add_u64 v[216:217], s[24:25], 0, v[178:179]
	s_mov_b32 m0, s52
	ds_read_b128 v[194:197], v210
	ds_read_b128 v[198:201], v210 offset:1024
	ds_read_b128 v[202:205], v210 offset:2048
	ds_read_b128 v[212:215], v210 offset:3072
	global_load_lds_dwordx4 v[216:217], off
	s_add_i32 m0, s52, 0x2000
	v_lshl_add_u64 v[218:219], s[24:25], 0, v[182:183]
	global_load_lds_dwordx4 v[218:219], off
	s_barrier
	s_waitcnt lgkmcnt(0)
	v_mfma_f32_16x16x32_bf16 v[116:119], v[194:197], v[144:147], v[116:119]
	v_mfma_f32_16x16x32_bf16 v[112:115], v[202:205], v[144:147], v[112:115]
	v_mfma_f32_16x16x32_bf16 v[100:103], v[194:197], v[152:155], v[100:103]
	v_mfma_f32_16x16x32_bf16 v[96:99], v[202:205], v[152:155], v[96:99]
	v_mfma_f32_16x16x32_bf16 v[84:87], v[194:197], v[160:163], v[84:87]
	v_mfma_f32_16x16x32_bf16 v[80:83], v[202:205], v[160:163], v[80:83]
	v_mfma_f32_16x16x32_bf16 v[68:71], v[194:197], v[168:171], v[68:71]
	v_mfma_f32_16x16x32_bf16 v[64:67], v[202:205], v[168:171], v[64:67]
	v_mfma_f32_16x16x32_bf16 v[116:119], v[198:201], v[148:151], v[116:119]
	v_mfma_f32_16x16x32_bf16 v[112:115], v[212:215], v[148:151], v[112:115]
	v_mfma_f32_16x16x32_bf16 v[100:103], v[198:201], v[156:159], v[100:103]
	v_mfma_f32_16x16x32_bf16 v[96:99], v[212:215], v[156:159], v[96:99]
	v_mfma_f32_16x16x32_bf16 v[84:87], v[198:201], v[164:167], v[84:87]
	v_mfma_f32_16x16x32_bf16 v[80:83], v[212:215], v[164:167], v[80:83]
	v_mfma_f32_16x16x32_bf16 v[68:71], v[198:201], v[172:175], v[68:71]
	v_mfma_f32_16x16x32_bf16 v[64:67], v[212:215], v[172:175], v[64:67]
	s_mov_b32 m0, s36
	v_lshl_add_u64 v[220:221], s[28:29], 0, v[176:177]
	s_barrier
	ds_read_b128 v[144:147], v209 offset:16384
	ds_read_b128 v[148:151], v209 offset:17408
	ds_read_b128 v[152:155], v209 offset:18432
	ds_read_b128 v[156:159], v209 offset:19456
	ds_read_b128 v[160:163], v209 offset:20480
	ds_read_b128 v[164:167], v209 offset:21504
	ds_read_b128 v[168:171], v209 offset:22528
	ds_read_b128 v[172:175], v209 offset:23552
	global_load_lds_dwordx4 v[220:221], off
	s_mov_b32 m0, s37
	v_lshl_add_u64 v[222:223], s[28:29], 0, v[180:181]
	global_load_lds_dwordx4 v[222:223], off
	s_barrier
	s_waitcnt lgkmcnt(0)
	v_mfma_f32_16x16x32_bf16 v[60:63], v[128:131], v[144:147], v[60:63]
	v_mfma_f32_16x16x32_bf16 v[56:59], v[136:139], v[144:147], v[56:59]
	v_mfma_f32_16x16x32_bf16 v[44:47], v[128:131], v[152:155], v[44:47]
	v_mfma_f32_16x16x32_bf16 v[40:43], v[136:139], v[152:155], v[40:43]
	v_mfma_f32_16x16x32_bf16 v[28:31], v[128:131], v[160:163], v[28:31]
	v_mfma_f32_16x16x32_bf16 v[24:27], v[136:139], v[160:163], v[24:27]
	v_mfma_f32_16x16x32_bf16 v[12:15], v[128:131], v[168:171], v[12:15]
	v_mfma_f32_16x16x32_bf16 v[8:11], v[136:139], v[168:171], v[8:11]
	v_mfma_f32_16x16x32_bf16 v[60:63], v[132:135], v[148:151], v[60:63]
	v_mfma_f32_16x16x32_bf16 v[56:59], v[140:143], v[148:151], v[56:59]
	v_mfma_f32_16x16x32_bf16 v[44:47], v[132:135], v[156:159], v[44:47]
	v_mfma_f32_16x16x32_bf16 v[40:43], v[140:143], v[156:159], v[40:43]
	v_mfma_f32_16x16x32_bf16 v[28:31], v[132:135], v[164:167], v[28:31]
	v_mfma_f32_16x16x32_bf16 v[24:27], v[140:143], v[164:167], v[24:27]
	v_mfma_f32_16x16x32_bf16 v[12:15], v[132:135], v[172:175], v[12:15]
	v_mfma_f32_16x16x32_bf16 v[8:11], v[140:143], v[172:175], v[8:11]
	s_barrier
	s_add_u32 s52, s24, 0x40000
	s_addc_u32 s53, s25, 0
	s_add_i32 s54, s46, s35
	s_mov_b32 m0, s54
	v_lshl_add_u64 v[128:129], s[52:53], 0, v[178:179]
	global_load_lds_dwordx4 v[128:129], off
	s_add_i32 m0, s54, 0x2000
	v_lshl_add_u64 v[128:129], s[52:53], 0, v[182:183]
	global_load_lds_dwordx4 v[128:129], off
	s_waitcnt vmcnt(6)
	s_barrier
	v_mfma_f32_16x16x32_bf16 v[52:55], v[194:197], v[144:147], v[52:55]
	v_mfma_f32_16x16x32_bf16 v[48:51], v[202:205], v[144:147], v[48:51]
	v_mfma_f32_16x16x32_bf16 v[36:39], v[194:197], v[152:155], v[36:39]
	v_mfma_f32_16x16x32_bf16 v[32:35], v[202:205], v[152:155], v[32:35]
	v_mfma_f32_16x16x32_bf16 v[20:23], v[194:197], v[160:163], v[20:23]
	v_mfma_f32_16x16x32_bf16 v[16:19], v[202:205], v[160:163], v[16:19]
	v_mfma_f32_16x16x32_bf16 v[4:7], v[194:197], v[168:171], v[4:7]
	v_mfma_f32_16x16x32_bf16 v[0:3], v[202:205], v[168:171], v[0:3]
	v_mfma_f32_16x16x32_bf16 v[52:55], v[198:201], v[148:151], v[52:55]
	v_mfma_f32_16x16x32_bf16 v[48:51], v[212:215], v[148:151], v[48:51]
	v_mfma_f32_16x16x32_bf16 v[36:39], v[198:201], v[156:159], v[36:39]
	v_mfma_f32_16x16x32_bf16 v[32:35], v[212:215], v[156:159], v[32:35]
	v_mfma_f32_16x16x32_bf16 v[20:23], v[198:201], v[164:167], v[20:23]
	v_mfma_f32_16x16x32_bf16 v[16:19], v[212:215], v[164:167], v[16:19]
	v_mfma_f32_16x16x32_bf16 v[4:7], v[198:201], v[172:175], v[4:7]
	v_mfma_f32_16x16x32_bf16 v[0:3], v[212:215], v[172:175], v[0:3]
	s_add_i32 s52, 0, 0x18000
	v_add_u32_e32 v140, s52, v206
	s_barrier
	ds_read_b128 v[128:131], v140
	ds_read_b128 v[132:135], v140 offset:1024
	ds_read_b128 v[136:139], v140 offset:2048
	ds_read_b128 v[140:143], v140 offset:3072
	s_add_u32 s28, s28, 0x40000
	s_addc_u32 s29, s29, 0
	s_mov_b32 m0, s38
	v_lshl_add_u64 v[194:195], s[28:29], 0, v[176:177]
	ds_read_b128 v[144:147], v209 offset:32768
	ds_read_b128 v[148:151], v209 offset:33792
	ds_read_b128 v[152:155], v209 offset:34816
	ds_read_b128 v[156:159], v209 offset:35840
	ds_read_b128 v[160:163], v209 offset:36864
	ds_read_b128 v[164:167], v209 offset:37888
	ds_read_b128 v[168:171], v209 offset:38912
	ds_read_b128 v[172:175], v209 offset:39936
	global_load_lds_dwordx4 v[194:195], off
	s_mov_b32 m0, s39
	v_lshl_add_u64 v[194:195], s[28:29], 0, v[180:181]
	global_load_lds_dwordx4 v[194:195], off
	s_waitcnt lgkmcnt(8)
	s_barrier
	s_waitcnt lgkmcnt(0)
	v_mfma_f32_16x16x32_bf16 v[124:127], v[128:131], v[144:147], v[124:127]
	v_mfma_f32_16x16x32_bf16 v[120:123], v[136:139], v[144:147], v[120:123]
	v_mfma_f32_16x16x32_bf16 v[108:111], v[128:131], v[152:155], v[108:111]
	v_mfma_f32_16x16x32_bf16 v[104:107], v[136:139], v[152:155], v[104:107]
	v_mfma_f32_16x16x32_bf16 v[92:95], v[128:131], v[160:163], v[92:95]
	v_mfma_f32_16x16x32_bf16 v[88:91], v[136:139], v[160:163], v[88:91]
	v_mfma_f32_16x16x32_bf16 v[76:79], v[128:131], v[168:171], v[76:79]
	v_mfma_f32_16x16x32_bf16 v[72:75], v[136:139], v[168:171], v[72:75]
	v_mfma_f32_16x16x32_bf16 v[124:127], v[132:135], v[148:151], v[124:127]
	v_mfma_f32_16x16x32_bf16 v[120:123], v[140:143], v[148:151], v[120:123]
	v_mfma_f32_16x16x32_bf16 v[108:111], v[132:135], v[156:159], v[108:111]
	v_mfma_f32_16x16x32_bf16 v[104:107], v[140:143], v[156:159], v[104:107]
	v_mfma_f32_16x16x32_bf16 v[92:95], v[132:135], v[164:167], v[92:95]
	v_mfma_f32_16x16x32_bf16 v[88:91], v[140:143], v[164:167], v[88:91]
	v_mfma_f32_16x16x32_bf16 v[76:79], v[132:135], v[172:175], v[76:79]
	v_mfma_f32_16x16x32_bf16 v[72:75], v[140:143], v[172:175], v[72:75]
	s_barrier
	s_add_i32 s28, 0, 0x1c000
	s_add_i32 s29, s52, s35
	v_add_u32_e32 v212, s28, v206
	v_lshl_add_u64 v[216:217], v[216:217], 0, s[8:9]
	s_mov_b32 m0, s29
	ds_read_b128 v[194:197], v212
	ds_read_b128 v[198:201], v212 offset:1024
	ds_read_b128 v[202:205], v212 offset:2048
	ds_read_b128 v[212:215], v212 offset:3072
	global_load_lds_dwordx4 v[216:217], off
	s_add_i32 m0, s29, 0x2000
	v_lshl_add_u64 v[216:217], v[218:219], 0, s[8:9]
	global_load_lds_dwordx4 v[216:217], off
	s_barrier
	s_waitcnt lgkmcnt(0)
	v_mfma_f32_16x16x32_bf16 v[116:119], v[194:197], v[144:147], v[116:119]
	v_mfma_f32_16x16x32_bf16 v[112:115], v[202:205], v[144:147], v[112:115]
	v_mfma_f32_16x16x32_bf16 v[100:103], v[194:197], v[152:155], v[100:103]
	v_mfma_f32_16x16x32_bf16 v[96:99], v[202:205], v[152:155], v[96:99]
	v_mfma_f32_16x16x32_bf16 v[84:87], v[194:197], v[160:163], v[84:87]
	v_mfma_f32_16x16x32_bf16 v[80:83], v[202:205], v[160:163], v[80:83]
	v_mfma_f32_16x16x32_bf16 v[68:71], v[194:197], v[168:171], v[68:71]
	v_mfma_f32_16x16x32_bf16 v[64:67], v[202:205], v[168:171], v[64:67]
	v_mfma_f32_16x16x32_bf16 v[116:119], v[198:201], v[148:151], v[116:119]
	v_mfma_f32_16x16x32_bf16 v[112:115], v[212:215], v[148:151], v[112:115]
	v_mfma_f32_16x16x32_bf16 v[100:103], v[198:201], v[156:159], v[100:103]
	v_mfma_f32_16x16x32_bf16 v[96:99], v[212:215], v[156:159], v[96:99]
	v_mfma_f32_16x16x32_bf16 v[84:87], v[198:201], v[164:167], v[84:87]
	v_mfma_f32_16x16x32_bf16 v[80:83], v[212:215], v[164:167], v[80:83]
	v_mfma_f32_16x16x32_bf16 v[68:71], v[198:201], v[172:175], v[68:71]
	v_mfma_f32_16x16x32_bf16 v[64:67], v[212:215], v[172:175], v[64:67]
	s_mov_b32 m0, s41
	v_lshl_add_u64 v[216:217], v[220:221], 0, s[8:9]
	s_barrier
	ds_read_b128 v[144:147], v209 offset:49152
	ds_read_b128 v[148:151], v209 offset:50176
	ds_read_b128 v[152:155], v209 offset:51200
	ds_read_b128 v[156:159], v209 offset:52224
	ds_read_b128 v[160:163], v209 offset:53248
	ds_read_b128 v[164:167], v209 offset:54272
	ds_read_b128 v[168:171], v209 offset:55296
	ds_read_b128 v[172:175], v209 offset:56320
	global_load_lds_dwordx4 v[216:217], off
	s_mov_b32 m0, s42
	v_lshl_add_u64 v[216:217], v[222:223], 0, s[8:9]
	global_load_lds_dwordx4 v[216:217], off
	s_barrier
	s_waitcnt lgkmcnt(0)
	v_mfma_f32_16x16x32_bf16 v[60:63], v[128:131], v[144:147], v[60:63]
	v_mfma_f32_16x16x32_bf16 v[56:59], v[136:139], v[144:147], v[56:59]
	v_mfma_f32_16x16x32_bf16 v[44:47], v[128:131], v[152:155], v[44:47]
	v_mfma_f32_16x16x32_bf16 v[40:43], v[136:139], v[152:155], v[40:43]
	v_mfma_f32_16x16x32_bf16 v[28:31], v[128:131], v[160:163], v[28:31]
	v_mfma_f32_16x16x32_bf16 v[24:27], v[136:139], v[160:163], v[24:27]
	v_mfma_f32_16x16x32_bf16 v[12:15], v[128:131], v[168:171], v[12:15]
	v_mfma_f32_16x16x32_bf16 v[8:11], v[136:139], v[168:171], v[8:11]
	v_mfma_f32_16x16x32_bf16 v[60:63], v[132:135], v[148:151], v[60:63]
	v_mfma_f32_16x16x32_bf16 v[56:59], v[140:143], v[148:151], v[56:59]
	v_mfma_f32_16x16x32_bf16 v[44:47], v[132:135], v[156:159], v[44:47]
	v_mfma_f32_16x16x32_bf16 v[40:43], v[140:143], v[156:159], v[40:43]
	v_mfma_f32_16x16x32_bf16 v[28:31], v[132:135], v[164:167], v[28:31]
	v_mfma_f32_16x16x32_bf16 v[24:27], v[140:143], v[164:167], v[24:27]
	v_mfma_f32_16x16x32_bf16 v[12:15], v[132:135], v[172:175], v[12:15]
	v_mfma_f32_16x16x32_bf16 v[8:11], v[140:143], v[172:175], v[8:11]
	s_barrier
	s_add_u32 s24, s24, 0x40080
	s_addc_u32 s25, s25, 0
	s_add_i32 s28, s28, s35
	s_mov_b32 m0, s28
	v_lshl_add_u64 v[128:129], s[24:25], 0, v[178:179]
	global_load_lds_dwordx4 v[128:129], off
	s_add_i32 m0, s28, 0x2000
	v_lshl_add_u64 v[128:129], s[24:25], 0, v[182:183]
	global_load_lds_dwordx4 v[128:129], off
	s_waitcnt vmcnt(6)
	s_barrier
	v_mfma_f32_16x16x32_bf16 v[52:55], v[194:197], v[144:147], v[52:55]
	v_mfma_f32_16x16x32_bf16 v[48:51], v[202:205], v[144:147], v[48:51]
	v_mfma_f32_16x16x32_bf16 v[36:39], v[194:197], v[152:155], v[36:39]
	v_mfma_f32_16x16x32_bf16 v[32:35], v[202:205], v[152:155], v[32:35]
	v_mfma_f32_16x16x32_bf16 v[20:23], v[194:197], v[160:163], v[20:23]
	v_mfma_f32_16x16x32_bf16 v[16:19], v[202:205], v[160:163], v[16:19]
	v_mfma_f32_16x16x32_bf16 v[4:7], v[194:197], v[168:171], v[4:7]
	v_mfma_f32_16x16x32_bf16 v[0:3], v[202:205], v[168:171], v[0:3]
	v_mfma_f32_16x16x32_bf16 v[52:55], v[198:201], v[148:151], v[52:55]
	v_mfma_f32_16x16x32_bf16 v[48:51], v[212:215], v[148:151], v[48:51]
	v_mfma_f32_16x16x32_bf16 v[36:39], v[198:201], v[156:159], v[36:39]
	v_mfma_f32_16x16x32_bf16 v[32:35], v[212:215], v[156:159], v[32:35]
	v_mfma_f32_16x16x32_bf16 v[20:23], v[198:201], v[164:167], v[20:23]
	v_mfma_f32_16x16x32_bf16 v[16:19], v[212:215], v[164:167], v[16:19]
	v_mfma_f32_16x16x32_bf16 v[4:7], v[198:201], v[172:175], v[4:7]
	v_mfma_f32_16x16x32_bf16 v[0:3], v[212:215], v[172:175], v[0:3]
	s_add_i32 s51, s51, 2
	s_add_u32 s22, s22, 0x100
	s_addc_u32 s23, s23, 0
	s_add_u32 s49, s49, 0x100
	s_addc_u32 s50, s50, 0
	s_cmp_gt_u32 s51, 13
	s_barrier
	s_cbranch_scc0 .LBB0_364
	v_lshl_add_u32 v196, s20, 8, v189
	v_lshl_or_b32 v194, s6, 8, v207
	v_readlane_b32 s48, v235, 5
	v_ashrrev_i32_e32 v195, 31, v194
	v_readlane_b32 s49, v235, 6
	v_ashrrev_i32_e32 v197, 31, v196
	v_lshlrev_b64 v[128:129], 12, v[196:197]
	v_lshl_add_u64 v[198:199], v[194:195], 2, s[48:49]
	v_or_b32_e32 v204, 16, v196
	v_lshl_add_u64 v[128:129], v[198:199], 0, v[128:129]
	v_ashrrev_i32_e32 v205, 31, v204
	global_load_dwordx4 v[212:215], v[128:129], off offset:16 nt
	global_load_dwordx4 v[216:219], v[128:129], off nt
	global_load_dwordx4 v[220:223], v[128:129], off offset:528 nt
	global_load_dwordx4 v[224:227], v[128:129], off offset:512 nt
	v_lshlrev_b64 v[128:129], 12, v[204:205]
	v_or_b32_e32 v202, 32, v196
	v_lshl_add_u64 v[128:129], v[198:199], 0, v[128:129]
	v_ashrrev_i32_e32 v203, 31, v202
	global_load_dwordx4 v[168:171], v[128:129], off offset:16 nt
	global_load_dwordx4 v[172:175], v[128:129], off nt
	global_load_dwordx4 v[160:163], v[128:129], off offset:528 nt
	global_load_dwordx4 v[164:167], v[128:129], off offset:512 nt
	v_lshlrev_b64 v[128:129], 12, v[202:203]
	v_or_b32_e32 v200, 48, v196
	v_lshl_add_u64 v[128:129], v[198:199], 0, v[128:129]
	v_ashrrev_i32_e32 v201, 31, v200
	global_load_dwordx4 v[152:155], v[128:129], off offset:16 nt
	global_load_dwordx4 v[156:159], v[128:129], off nt
	global_load_dwordx4 v[144:147], v[128:129], off offset:528 nt
	global_load_dwordx4 v[148:151], v[128:129], off offset:512 nt
	v_lshlrev_b64 v[128:129], 12, v[200:201]
	v_lshl_add_u64 v[132:133], v[198:199], 0, v[128:129]
	global_load_dwordx4 v[136:139], v[132:133], off offset:16 nt
	global_load_dwordx4 v[140:143], v[132:133], off nt
	global_load_dwordx4 v[128:131], v[132:133], off offset:528 nt
	s_nop 0
	global_load_dwordx4 v[132:135], v[132:133], off offset:512 nt
	s_lshl_b32 s20, s6, 2
	s_ashr_i32 s21, s20, 31
	v_readlane_b32 s50, v235, 7
	v_readlane_b32 s51, v235, 8
	v_readlane_b32 s52, v235, 9
	v_readlane_b32 s53, v235, 10
	v_readlane_b32 s54, v235, 11
	v_readlane_b32 s55, v235, 12
	v_readlane_b32 s56, v235, 13
	v_readlane_b32 s57, v235, 14
	v_readlane_b32 s58, v235, 15
	v_readlane_b32 s59, v235, 16
	v_readlane_b32 s60, v235, 17
	v_readlane_b32 s61, v235, 18
	v_readlane_b32 s62, v235, 19
	v_readlane_b32 s63, v235, 20
	s_waitcnt vmcnt(0)
	v_pk_add_f32 v[126:127], v[126:127], v[218:219]
	v_pk_add_f32 v[124:125], v[124:125], v[216:217]
	v_pk_add_f32 v[214:215], v[122:123], v[214:215]
	v_mul_f32_e32 v122, v125, v125
	v_mul_f32_e32 v123, v127, v127
	v_pk_add_f32 v[120:121], v[120:121], v[212:213]
	v_fmac_f32_e32 v122, v124, v124
	v_fmac_f32_e32 v123, v126, v126
	v_add_f32_e32 v122, v122, v123
	v_mul_f32_e32 v123, v121, v121
	v_mul_f32_e32 v212, v215, v215
	v_fmac_f32_e32 v123, v120, v120
	v_fmac_f32_e32 v212, v214, v214
	v_pk_add_f32 v[118:119], v[118:119], v[226:227]
	v_pk_add_f32 v[116:117], v[116:117], v[224:225]
	v_add_f32_e32 v123, v123, v212
	v_pk_add_f32 v[212:213], v[112:113], v[220:221]
	v_mul_f32_e32 v112, v117, v117
	v_mul_f32_e32 v113, v119, v119
	v_add_f32_e32 v216, v122, v123
	v_cvt_pk_bf16_f32 v122, v124, v125
	v_cvt_pk_bf16_f32 v123, v126, v127
	v_pk_add_f32 v[126:127], v[114:115], v[222:223]
	v_fmac_f32_e32 v112, v116, v116
	v_fmac_f32_e32 v113, v118, v118
	v_add_f32_e32 v112, v112, v113
	v_mul_f32_e32 v113, v213, v213
	v_mul_f32_e32 v114, v127, v127
	v_fmac_f32_e32 v113, v212, v212
	v_fmac_f32_e32 v114, v126, v126
	v_add_f32_e32 v113, v113, v114
	v_add_f32_e32 v112, v112, v113
	v_and_b32_e32 v113, 64, v211
	v_cvt_pk_bf16_f32 v124, v120, v121
	v_add_f32_e32 v115, v216, v112
	v_xor_b32_e32 v112, 16, v211
	v_add_u32_e32 v121, 64, v113
	v_cmp_lt_i32_e32 vcc, v112, v121
	v_lshlrev_b64 v[228:229], 11, v[196:197]
	v_cvt_pk_bf16_f32 v125, v214, v215
	s_nop 0
	v_cndmask_b32_e32 v112, v211, v112, vcc
	v_lshlrev_b32_e32 v120, 2, v112
	ds_bpermute_b32 v216, v120, v115
	v_lshl_add_u64 v[112:113], s[64:65], 0, v[228:229]
	v_lshl_add_u64 v[214:215], v[194:195], 1, v[112:113]
	v_xor_b32_e32 v113, 32, v211
	v_cmp_lt_i32_e32 vcc, v113, v121
	s_waitcnt lgkmcnt(0)
	v_add_f32_e32 v112, v115, v216
	global_store_dwordx4 v[214:215], v[122:125], off
	v_cndmask_b32_e32 v113, v211, v113, vcc
	v_lshlrev_b32_e32 v121, 2, v113
	ds_bpermute_b32 v113, v121, v112
	v_cvt_pk_bf16_f32 v114, v116, v117
	v_cvt_pk_bf16_f32 v115, v118, v119
	v_cvt_pk_bf16_f32 v116, v212, v213
	v_cvt_pk_bf16_f32 v117, v126, v127
	global_store_dwordx4 v[214:215], v[114:117], off offset:256
	s_and_saveexec_b64 s[22:23], s[2:3]
	s_cbranch_execz .LBB0_367
	v_lshlrev_b64 v[114:115], 6, v[196:197]
	v_lshl_add_u64 v[114:115], s[74:75], 0, v[114:115]
	v_lshl_add_u64 v[114:115], s[20:21], 2, v[114:115]
	s_lshl_b32 s6, s40, 2
	v_lshl_add_u64 v[114:115], v[114:115], 0, s[6:7]
	s_waitcnt lgkmcnt(0)
	v_add_f32_e32 v112, v112, v113
	global_store_dword v[114:115], v112, off

.LBB0_452:
	ds_read_b128 v[16:19], v212
	ds_read_b128 v[20:23], v212 offset:1024
	ds_read_b128 v[24:27], v212 offset:2048
	ds_read_b128 v[68:71], v212 offset:3072
	s_add_u32 s34, s8, 0x100
	s_addc_u32 s35, s9, 0
	s_cmp_eq_u32 s71, 12
	s_cselect_b32 s39, s63, s35
	s_cselect_b32 s38, s67, s34
	s_cselect_b32 s37, s11, s70
	s_cselect_b32 s36, s68, s69
	v_lshl_add_u64 v[176:177], s[8:9], 0, v[204:205]
	s_add_i32 m0, s46, 0xc000
	ds_read_b128 v[96:99], v213
	ds_read_b128 v[148:151], v213 offset:1024
	ds_read_b128 v[152:155], v213 offset:2048
	ds_read_b128 v[156:159], v213 offset:3072
	ds_read_b128 v[160:163], v213 offset:4096
	ds_read_b128 v[164:167], v213 offset:5120
	ds_read_b128 v[168:171], v213 offset:6144
	ds_read_b128 v[172:175], v213 offset:7168
	global_load_lds_dwordx4 v[176:177], off
	s_add_i32 m0, s46, 0xe000
	v_lshl_add_u64 v[176:177], s[8:9], 0, v[206:207]
	global_load_lds_dwordx4 v[176:177], off
	s_waitcnt lgkmcnt(8)
	s_barrier
	s_waitcnt lgkmcnt(0)
	v_mfma_f32_16x16x32_bf16 v[112:115], v[16:19], v[96:99], v[112:115]
	v_mfma_f32_16x16x32_bf16 v[40:43], v[24:27], v[96:99], v[40:43]
	v_mfma_f32_16x16x32_bf16 v[108:111], v[16:19], v[152:155], v[108:111]
	v_mfma_f32_16x16x32_bf16 v[36:39], v[24:27], v[152:155], v[36:39]
	v_mfma_f32_16x16x32_bf16 v[144:147], v[16:19], v[160:163], v[144:147]
	v_mfma_f32_16x16x32_bf16 v[140:143], v[24:27], v[160:163], v[140:143]
	v_mfma_f32_16x16x32_bf16 v[136:139], v[16:19], v[168:171], v[136:139]
	v_mfma_f32_16x16x32_bf16 v[132:135], v[24:27], v[168:171], v[132:135]
	v_mfma_f32_16x16x32_bf16 v[112:115], v[20:23], v[148:151], v[112:115]
	v_mfma_f32_16x16x32_bf16 v[40:43], v[68:71], v[148:151], v[40:43]
	v_mfma_f32_16x16x32_bf16 v[108:111], v[20:23], v[156:159], v[108:111]
	v_mfma_f32_16x16x32_bf16 v[36:39], v[68:71], v[156:159], v[36:39]
	v_mfma_f32_16x16x32_bf16 v[144:147], v[20:23], v[164:167], v[144:147]
	v_mfma_f32_16x16x32_bf16 v[140:143], v[68:71], v[164:167], v[140:143]
	v_mfma_f32_16x16x32_bf16 v[136:139], v[20:23], v[172:175], v[136:139]
	v_mfma_f32_16x16x32_bf16 v[132:135], v[68:71], v[172:175], v[132:135]
	s_barrier
	s_add_i32 s8, s56, s45
	v_lshl_add_u64 v[222:223], s[36:37], 0, v[192:193]
	s_mov_b32 m0, s8
	ds_read_b128 v[176:179], v214
	ds_read_b128 v[180:183], v214 offset:1024
	ds_read_b128 v[184:187], v214 offset:2048
	ds_read_b128 v[218:221], v214 offset:3072
	global_load_lds_dwordx4 v[222:223], off
	s_add_i32 m0, s8, 0x2000
	v_lshl_add_u64 v[224:225], s[36:37], 0, v[198:199]
	global_load_lds_dwordx4 v[224:225], off
	s_barrier
	s_waitcnt lgkmcnt(0)
	v_mfma_f32_16x16x32_bf16 v[104:107], v[176:179], v[96:99], v[104:107]
	v_mfma_f32_16x16x32_bf16 v[32:35], v[184:187], v[96:99], v[32:35]
	v_mfma_f32_16x16x32_bf16 v[28:31], v[184:187], v[152:155], v[28:31]
	v_mfma_f32_16x16x32_bf16 v[80:83], v[176:179], v[160:163], v[80:83]
	v_mfma_f32_16x16x32_bf16 v[92:95], v[184:187], v[160:163], v[92:95]
	v_mfma_f32_16x16x32_bf16 v[84:87], v[176:179], v[168:171], v[84:87]
	v_mfma_f32_16x16x32_bf16 v[88:91], v[184:187], v[168:171], v[88:91]
	v_mfma_f32_16x16x32_bf16 v[104:107], v[180:183], v[148:151], v[104:107]
	v_mfma_f32_16x16x32_bf16 v[32:35], v[218:221], v[148:151], v[32:35]
	v_mfma_f32_16x16x32_bf16 v[96:99], v[176:179], v[152:155], v[100:103]
	v_mfma_f32_16x16x32_bf16 v[28:31], v[218:221], v[156:159], v[28:31]
	v_mfma_f32_16x16x32_bf16 v[80:83], v[180:183], v[164:167], v[80:83]
	v_mfma_f32_16x16x32_bf16 v[92:95], v[218:221], v[164:167], v[92:95]
	v_mfma_f32_16x16x32_bf16 v[84:87], v[180:183], v[172:175], v[84:87]
	v_mfma_f32_16x16x32_bf16 v[88:91], v[218:221], v[172:175], v[88:91]
	v_mfma_f32_16x16x32_bf16 v[96:99], v[180:183], v[156:159], v[96:99]
	s_mov_b32 m0, s46
	v_lshl_add_u64 v[226:227], s[38:39], 0, v[194:195]
	s_barrier
	ds_read_b128 v[100:103], v213 offset:16384
	ds_read_b128 v[148:151], v213 offset:17408
	ds_read_b128 v[152:155], v213 offset:18432
	ds_read_b128 v[156:159], v213 offset:19456
	ds_read_b128 v[160:163], v213 offset:20480
	ds_read_b128 v[164:167], v213 offset:21504
	ds_read_b128 v[168:171], v213 offset:22528
	ds_read_b128 v[172:175], v213 offset:23552
	global_load_lds_dwordx4 v[226:227], off
	s_mov_b32 m0, s47
	v_lshl_add_u64 v[228:229], s[38:39], 0, v[196:197]
	global_load_lds_dwordx4 v[228:229], off
	s_barrier
	s_waitcnt lgkmcnt(0)
	v_mfma_f32_16x16x32_bf16 v[76:79], v[16:19], v[100:103], v[76:79]
	v_mfma_f32_16x16x32_bf16 v[12:15], v[24:27], v[100:103], v[12:15]
	v_mfma_f32_16x16x32_bf16 v[72:75], v[16:19], v[152:155], v[72:75]
	v_mfma_f32_16x16x32_bf16 v[8:11], v[24:27], v[152:155], v[8:11]
	v_mfma_f32_16x16x32_bf16 v[128:131], v[16:19], v[160:163], v[128:131]
	v_mfma_f32_16x16x32_bf16 v[124:127], v[24:27], v[160:163], v[124:127]
	v_mfma_f32_16x16x32_bf16 v[16:19], v[16:19], v[168:171], v[120:123]
	v_mfma_f32_16x16x32_bf16 v[76:79], v[20:23], v[148:151], v[76:79]
	v_mfma_f32_16x16x32_bf16 v[12:15], v[68:71], v[148:151], v[12:15]
	v_mfma_f32_16x16x32_bf16 v[72:75], v[20:23], v[156:159], v[72:75]
	v_mfma_f32_16x16x32_bf16 v[8:11], v[68:71], v[156:159], v[8:11]
	v_mfma_f32_16x16x32_bf16 v[128:131], v[20:23], v[164:167], v[128:131]
	v_mfma_f32_16x16x32_bf16 v[124:127], v[68:71], v[164:167], v[124:127]
	v_mfma_f32_16x16x32_bf16 v[16:19], v[20:23], v[172:175], v[16:19]
	v_mfma_f32_16x16x32_bf16 v[20:23], v[24:27], v[168:171], v[116:119]
	v_mfma_f32_16x16x32_bf16 v[20:23], v[68:71], v[172:175], v[20:23]
	s_barrier
	s_add_u32 s8, s36, 0x40000
	s_addc_u32 s9, s37, 0
	s_add_i32 s78, s57, s45
	s_mov_b32 m0, s78
	v_lshl_add_u64 v[24:25], s[8:9], 0, v[192:193]
	global_load_lds_dwordx4 v[24:25], off
	s_add_i32 m0, s78, 0x2000
	v_lshl_add_u64 v[24:25], s[8:9], 0, v[198:199]
	global_load_lds_dwordx4 v[24:25], off
	s_waitcnt vmcnt(6)
	s_barrier
	v_mfma_f32_16x16x32_bf16 v[4:7], v[184:187], v[100:103], v[4:7]
	v_mfma_f32_16x16x32_bf16 v[60:63], v[176:179], v[152:155], v[60:63]
	v_mfma_f32_16x16x32_bf16 v[0:3], v[184:187], v[152:155], v[0:3]
	v_mfma_f32_16x16x32_bf16 v[44:47], v[176:179], v[160:163], v[44:47]
	v_mfma_f32_16x16x32_bf16 v[48:51], v[184:187], v[160:163], v[48:51]
	v_mfma_f32_16x16x32_bf16 v[52:55], v[176:179], v[168:171], v[52:55]
	v_mfma_f32_16x16x32_bf16 v[56:59], v[184:187], v[168:171], v[56:59]
	v_mfma_f32_16x16x32_bf16 v[24:27], v[176:179], v[100:103], v[64:67]
	v_mfma_f32_16x16x32_bf16 v[4:7], v[218:221], v[148:151], v[4:7]
	v_mfma_f32_16x16x32_bf16 v[60:63], v[180:183], v[156:159], v[60:63]
	v_mfma_f32_16x16x32_bf16 v[0:3], v[218:221], v[156:159], v[0:3]
	v_mfma_f32_16x16x32_bf16 v[44:47], v[180:183], v[164:167], v[44:47]
	v_mfma_f32_16x16x32_bf16 v[48:51], v[218:221], v[164:167], v[48:51]
	v_mfma_f32_16x16x32_bf16 v[52:55], v[180:183], v[172:175], v[52:55]
	v_mfma_f32_16x16x32_bf16 v[56:59], v[218:221], v[172:175], v[56:59]
	v_mfma_f32_16x16x32_bf16 v[24:27], v[180:183], v[148:151], v[24:27]
	s_add_i32 s78, 0, 0x18000
	v_add_u32_e32 v100, s78, v208
	s_barrier
	ds_read_b128 v[64:67], v100
	ds_read_b128 v[68:71], v100 offset:1024
	ds_read_b128 v[116:119], v100 offset:2048
	ds_read_b128 v[148:151], v100 offset:3072
	s_add_u32 s8, s38, 0x40000
	s_addc_u32 s9, s39, 0
	s_mov_b32 m0, s48
	v_lshl_add_u64 v[176:177], s[8:9], 0, v[194:195]
	ds_read_b128 v[100:103], v213 offset:32768
	ds_read_b128 v[120:123], v213 offset:33792
	ds_read_b128 v[152:155], v213 offset:34816
	ds_read_b128 v[156:159], v213 offset:35840
	ds_read_b128 v[160:163], v213 offset:36864
	ds_read_b128 v[164:167], v213 offset:37888
	ds_read_b128 v[168:171], v213 offset:38912
	ds_read_b128 v[172:175], v213 offset:39936
	global_load_lds_dwordx4 v[176:177], off
	s_mov_b32 m0, s49
	v_lshl_add_u64 v[176:177], s[8:9], 0, v[196:197]
	global_load_lds_dwordx4 v[176:177], off
	s_waitcnt lgkmcnt(8)
	s_barrier
	s_waitcnt lgkmcnt(0)
	v_mfma_f32_16x16x32_bf16 v[112:115], v[64:67], v[100:103], v[112:115]
	v_mfma_f32_16x16x32_bf16 v[40:43], v[116:119], v[100:103], v[40:43]
	v_mfma_f32_16x16x32_bf16 v[108:111], v[64:67], v[152:155], v[108:111]
	v_mfma_f32_16x16x32_bf16 v[36:39], v[116:119], v[152:155], v[36:39]
	v_mfma_f32_16x16x32_bf16 v[144:147], v[64:67], v[160:163], v[144:147]
	v_mfma_f32_16x16x32_bf16 v[140:143], v[116:119], v[160:163], v[140:143]
	v_mfma_f32_16x16x32_bf16 v[136:139], v[64:67], v[168:171], v[136:139]
	v_mfma_f32_16x16x32_bf16 v[132:135], v[116:119], v[168:171], v[132:135]
	v_mfma_f32_16x16x32_bf16 v[112:115], v[68:71], v[120:123], v[112:115]
	v_mfma_f32_16x16x32_bf16 v[40:43], v[148:151], v[120:123], v[40:43]
	v_mfma_f32_16x16x32_bf16 v[108:111], v[68:71], v[156:159], v[108:111]
	v_mfma_f32_16x16x32_bf16 v[36:39], v[148:151], v[156:159], v[36:39]
	v_mfma_f32_16x16x32_bf16 v[144:147], v[68:71], v[164:167], v[144:147]
	v_mfma_f32_16x16x32_bf16 v[140:143], v[148:151], v[164:167], v[140:143]
	v_mfma_f32_16x16x32_bf16 v[136:139], v[68:71], v[172:175], v[136:139]
	v_mfma_f32_16x16x32_bf16 v[132:135], v[148:151], v[172:175], v[132:135]
	s_barrier
	s_add_i32 s38, 0, 0x1c000
	s_add_i32 s8, s78, s45
	v_add_u32_e32 v217, s38, v208
	v_lshl_add_u64 v[222:223], v[222:223], 0, s[20:21]
	s_mov_b32 m0, s8
	ds_read_b128 v[176:179], v217
	ds_read_b128 v[180:183], v217 offset:1024
	ds_read_b128 v[184:187], v217 offset:2048
	ds_read_b128 v[218:221], v217 offset:3072
	global_load_lds_dwordx4 v[222:223], off
	s_add_i32 m0, s8, 0x2000
	v_lshl_add_u64 v[222:223], v[224:225], 0, s[20:21]
	global_load_lds_dwordx4 v[222:223], off
	s_barrier
	s_waitcnt lgkmcnt(0)
	v_mfma_f32_16x16x32_bf16 v[104:107], v[176:179], v[100:103], v[104:107]
	v_mfma_f32_16x16x32_bf16 v[32:35], v[184:187], v[100:103], v[32:35]
	v_mfma_f32_16x16x32_bf16 v[96:99], v[176:179], v[152:155], v[96:99]
	v_mfma_f32_16x16x32_bf16 v[28:31], v[184:187], v[152:155], v[28:31]
	v_mfma_f32_16x16x32_bf16 v[80:83], v[176:179], v[160:163], v[80:83]
	v_mfma_f32_16x16x32_bf16 v[92:95], v[184:187], v[160:163], v[92:95]
	v_mfma_f32_16x16x32_bf16 v[84:87], v[176:179], v[168:171], v[84:87]
	v_mfma_f32_16x16x32_bf16 v[88:91], v[184:187], v[168:171], v[88:91]
	v_mfma_f32_16x16x32_bf16 v[104:107], v[180:183], v[120:123], v[104:107]
	v_mfma_f32_16x16x32_bf16 v[32:35], v[218:221], v[120:123], v[32:35]
	v_mfma_f32_16x16x32_bf16 v[100:103], v[180:183], v[156:159], v[96:99]
	v_mfma_f32_16x16x32_bf16 v[28:31], v[218:221], v[156:159], v[28:31]
	v_mfma_f32_16x16x32_bf16 v[80:83], v[180:183], v[164:167], v[80:83]
	v_mfma_f32_16x16x32_bf16 v[92:95], v[218:221], v[164:167], v[92:95]
	v_mfma_f32_16x16x32_bf16 v[84:87], v[180:183], v[172:175], v[84:87]
	v_mfma_f32_16x16x32_bf16 v[88:91], v[218:221], v[172:175], v[88:91]
	s_mov_b32 m0, s53
	v_lshl_add_u64 v[120:121], v[226:227], 0, s[20:21]
	s_barrier
	ds_read_b128 v[96:99], v213 offset:49152
	ds_read_b128 v[152:155], v213 offset:50176
	ds_read_b128 v[156:159], v213 offset:51200
	ds_read_b128 v[160:163], v213 offset:52224
	ds_read_b128 v[164:167], v213 offset:53248
	ds_read_b128 v[168:171], v213 offset:54272
	ds_read_b128 v[172:175], v213 offset:55296
	ds_read_b128 v[222:225], v213 offset:56320
	global_load_lds_dwordx4 v[120:121], off
	s_mov_b32 m0, s54
	v_lshl_add_u64 v[120:121], v[228:229], 0, s[20:21]
	global_load_lds_dwordx4 v[120:121], off
	s_barrier
	s_waitcnt lgkmcnt(0)
	v_mfma_f32_16x16x32_bf16 v[120:123], v[64:67], v[164:167], v[128:131]
	v_mfma_f32_16x16x32_bf16 v[128:131], v[68:71], v[168:171], v[120:123]
	v_mfma_f32_16x16x32_bf16 v[120:123], v[116:119], v[164:167], v[124:127]
	v_mfma_f32_16x16x32_bf16 v[16:19], v[64:67], v[172:175], v[16:19]
	v_mfma_f32_16x16x32_bf16 v[76:79], v[64:67], v[96:99], v[76:79]
	v_mfma_f32_16x16x32_bf16 v[12:15], v[116:119], v[96:99], v[12:15]
	v_mfma_f32_16x16x32_bf16 v[72:75], v[64:67], v[156:159], v[72:75]
	v_mfma_f32_16x16x32_bf16 v[8:11], v[116:119], v[156:159], v[8:11]
	v_mfma_f32_16x16x32_bf16 v[124:127], v[148:151], v[168:171], v[120:123]
	v_mfma_f32_16x16x32_bf16 v[120:123], v[68:71], v[222:225], v[16:19]
	v_mfma_f32_16x16x32_bf16 v[16:19], v[116:119], v[172:175], v[20:23]
	v_mfma_f32_16x16x32_bf16 v[76:79], v[68:71], v[152:155], v[76:79]
	v_mfma_f32_16x16x32_bf16 v[12:15], v[148:151], v[152:155], v[12:15]
	v_mfma_f32_16x16x32_bf16 v[72:75], v[68:71], v[160:163], v[72:75]
	v_mfma_f32_16x16x32_bf16 v[8:11], v[148:151], v[160:163], v[8:11]
	v_mfma_f32_16x16x32_bf16 v[116:119], v[148:151], v[222:225], v[16:19]
	s_barrier
	s_add_u32 s8, s36, 0x40080
	s_addc_u32 s9, s37, 0
	s_add_i32 s36, s38, s45
	s_mov_b32 m0, s36
	v_lshl_add_u64 v[16:17], s[8:9], 0, v[192:193]
	global_load_lds_dwordx4 v[16:17], off
	s_add_i32 m0, s36, 0x2000
	v_lshl_add_u64 v[16:17], s[8:9], 0, v[198:199]
	global_load_lds_dwordx4 v[16:17], off
	s_waitcnt vmcnt(6)
	s_barrier
	v_mfma_f32_16x16x32_bf16 v[16:19], v[176:179], v[96:99], v[24:27]
	v_mfma_f32_16x16x32_bf16 v[64:67], v[180:183], v[152:155], v[16:19]
	v_mfma_f32_16x16x32_bf16 v[16:19], v[176:179], v[156:159], v[60:63]
	v_mfma_f32_16x16x32_bf16 v[60:63], v[180:183], v[160:163], v[16:19]
	v_mfma_f32_16x16x32_bf16 v[16:19], v[176:179], v[164:167], v[44:47]
	v_mfma_f32_16x16x32_bf16 v[44:47], v[180:183], v[168:171], v[16:19]
	v_mfma_f32_16x16x32_bf16 v[16:19], v[184:187], v[164:167], v[48:51]
	v_mfma_f32_16x16x32_bf16 v[48:51], v[218:221], v[168:171], v[16:19]
	v_mfma_f32_16x16x32_bf16 v[16:19], v[176:179], v[172:175], v[52:55]
	v_mfma_f32_16x16x32_bf16 v[4:7], v[184:187], v[96:99], v[4:7]
	v_mfma_f32_16x16x32_bf16 v[0:3], v[184:187], v[156:159], v[0:3]
	v_mfma_f32_16x16x32_bf16 v[52:55], v[180:183], v[222:225], v[16:19]
	v_mfma_f32_16x16x32_bf16 v[16:19], v[184:187], v[172:175], v[56:59]
	v_mfma_f32_16x16x32_bf16 v[4:7], v[218:221], v[152:155], v[4:7]
	v_mfma_f32_16x16x32_bf16 v[0:3], v[218:221], v[160:163], v[0:3]
	v_mfma_f32_16x16x32_bf16 v[56:59], v[218:221], v[222:225], v[16:19]
	s_add_i32 s71, s71, 2
	s_add_u32 s69, s69, 0x100
	s_addc_u32 s70, s70, 0
	s_cmp_gt_u32 s71, 13
	s_mov_b64 s[8:9], s[34:35]
	s_barrier
	s_cbranch_scc0 .LBB0_452
	v_cndmask_b32_e64 v16, 0, 1, s[30:31]
	v_cmp_ne_u32_e64 s[8:9], 1, v16
	s_andn2_b64 vcc, exec, s[30:31]
	s_cbranch_vccnz .LBB0_457
	v_mov_b32_e32 v16, 0
	v_mov_b32_e32 v17, 0
	v_mov_b32_e32 v18, 0
	v_mov_b32_e32 v19, 0
	s_and_saveexec_b64 s[30:31], s[2:3]
	s_cbranch_execz .LBB0_456
	s_lshl_b32 s34, s10, 7
	s_ashr_i32 s35, s34, 31
	v_lshl_add_u64 v[16:17], s[34:35], 2, v[202:203]
	global_load_dwordx4 v[16:19], v[16:17], off

.LBB0_554:
	ds_read_b128 v[128:131], v190
	ds_read_b128 v[132:135], v190 offset:1024
	ds_read_b128 v[136:139], v190 offset:2048
	ds_read_b128 v[140:143], v190 offset:3072
	s_add_u32 s18, s14, 0x100
	s_addc_u32 s19, s15, 0
	s_cmp_eq_u32 s51, 40
	s_cselect_b32 s23, s1, s19
	s_cselect_b32 s22, s0, s18
	s_cselect_b32 s21, s7, s50
	s_cselect_b32 s20, s6, s49
	v_lshl_add_u64 v[184:185], s[14:15], 0, v[160:161]
	s_add_i32 m0, s34, 0xc000
	ds_read_b128 v[144:147], v191
	ds_read_b128 v[148:151], v191 offset:1024
	ds_read_b128 v[168:171], v191 offset:2048
	ds_read_b128 v[172:175], v191 offset:3072
	ds_read_b128 v[176:179], v191 offset:4096
	ds_read_b128 v[180:183], v191 offset:5120
	ds_read_b128 v[194:197], v191 offset:6144
	ds_read_b128 v[198:201], v191 offset:7168
	global_load_lds_dwordx4 v[184:185], off
	s_add_i32 m0, s34, 0xe000
	v_lshl_add_u64 v[184:185], s[14:15], 0, v[162:163]
	global_load_lds_dwordx4 v[184:185], off
	s_waitcnt lgkmcnt(8)
	s_barrier
	s_waitcnt lgkmcnt(0)
	v_mfma_f32_16x16x32_bf16 v[124:127], v[128:131], v[144:147], v[124:127]
	v_mfma_f32_16x16x32_bf16 v[120:123], v[136:139], v[144:147], v[120:123]
	v_mfma_f32_16x16x32_bf16 v[108:111], v[128:131], v[168:171], v[108:111]
	v_mfma_f32_16x16x32_bf16 v[104:107], v[136:139], v[168:171], v[104:107]
	v_mfma_f32_16x16x32_bf16 v[92:95], v[128:131], v[176:179], v[92:95]
	v_mfma_f32_16x16x32_bf16 v[88:91], v[136:139], v[176:179], v[88:91]
	v_mfma_f32_16x16x32_bf16 v[76:79], v[128:131], v[194:197], v[76:79]
	v_mfma_f32_16x16x32_bf16 v[72:75], v[136:139], v[194:197], v[72:75]
	v_mfma_f32_16x16x32_bf16 v[124:127], v[132:135], v[148:151], v[124:127]
	v_mfma_f32_16x16x32_bf16 v[120:123], v[140:143], v[148:151], v[120:123]
	v_mfma_f32_16x16x32_bf16 v[108:111], v[132:135], v[172:175], v[108:111]
	v_mfma_f32_16x16x32_bf16 v[104:107], v[140:143], v[172:175], v[104:107]
	v_mfma_f32_16x16x32_bf16 v[92:95], v[132:135], v[180:183], v[92:95]
	v_mfma_f32_16x16x32_bf16 v[88:91], v[140:143], v[180:183], v[88:91]
	v_mfma_f32_16x16x32_bf16 v[76:79], v[132:135], v[198:201], v[76:79]
	v_mfma_f32_16x16x32_bf16 v[72:75], v[140:143], v[198:201], v[72:75]
	s_barrier
	s_add_i32 s14, s43, s31
	v_lshl_add_u64 v[184:185], s[20:21], 0, v[154:155]
	s_mov_b32 m0, s14
	ds_read_b128 v[202:205], v192
	ds_read_b128 v[206:209], v192 offset:1024
	ds_read_b128 v[210:213], v192 offset:2048
	ds_read_b128 v[214:217], v192 offset:3072
	global_load_lds_dwordx4 v[184:185], off
	s_add_i32 m0, s14, 0x2000
	v_lshl_add_u64 v[218:219], s[20:21], 0, v[158:159]
	global_load_lds_dwordx4 v[218:219], off
	s_barrier
	s_waitcnt lgkmcnt(0)
	v_mfma_f32_16x16x32_bf16 v[116:119], v[202:205], v[144:147], v[116:119]
	v_mfma_f32_16x16x32_bf16 v[112:115], v[210:213], v[144:147], v[112:115]
	v_mfma_f32_16x16x32_bf16 v[100:103], v[202:205], v[168:171], v[100:103]
	v_mfma_f32_16x16x32_bf16 v[96:99], v[210:213], v[168:171], v[96:99]
	v_mfma_f32_16x16x32_bf16 v[84:87], v[202:205], v[176:179], v[84:87]
	v_mfma_f32_16x16x32_bf16 v[80:83], v[210:213], v[176:179], v[80:83]
	v_mfma_f32_16x16x32_bf16 v[68:71], v[202:205], v[194:197], v[68:71]
	v_mfma_f32_16x16x32_bf16 v[64:67], v[210:213], v[194:197], v[64:67]
	v_mfma_f32_16x16x32_bf16 v[116:119], v[206:209], v[148:151], v[116:119]
	v_mfma_f32_16x16x32_bf16 v[112:115], v[214:217], v[148:151], v[112:115]
	v_mfma_f32_16x16x32_bf16 v[100:103], v[206:209], v[172:175], v[100:103]
	v_mfma_f32_16x16x32_bf16 v[96:99], v[214:217], v[172:175], v[96:99]
	v_mfma_f32_16x16x32_bf16 v[84:87], v[206:209], v[180:183], v[84:87]
	v_mfma_f32_16x16x32_bf16 v[80:83], v[214:217], v[180:183], v[80:83]
	v_mfma_f32_16x16x32_bf16 v[68:71], v[206:209], v[198:201], v[68:71]
	v_mfma_f32_16x16x32_bf16 v[64:67], v[214:217], v[198:201], v[64:67]
	s_mov_b32 m0, s34
	v_lshl_add_u64 v[220:221], s[22:23], 0, v[152:153]
	s_barrier
	ds_read_b128 v[144:147], v191 offset:16384
	ds_read_b128 v[148:151], v191 offset:17408
	ds_read_b128 v[168:171], v191 offset:18432
	ds_read_b128 v[172:175], v191 offset:19456
	ds_read_b128 v[176:179], v191 offset:20480
	ds_read_b128 v[180:183], v191 offset:21504
	ds_read_b128 v[194:197], v191 offset:22528
	ds_read_b128 v[198:201], v191 offset:23552
	global_load_lds_dwordx4 v[220:221], off
	s_mov_b32 m0, s35
	v_lshl_add_u64 v[222:223], s[22:23], 0, v[156:157]
	global_load_lds_dwordx4 v[222:223], off
	s_barrier
	s_waitcnt lgkmcnt(0)
	v_mfma_f32_16x16x32_bf16 v[60:63], v[128:131], v[144:147], v[60:63]
	v_mfma_f32_16x16x32_bf16 v[56:59], v[136:139], v[144:147], v[56:59]
	v_mfma_f32_16x16x32_bf16 v[44:47], v[128:131], v[168:171], v[44:47]
	v_mfma_f32_16x16x32_bf16 v[40:43], v[136:139], v[168:171], v[40:43]
	v_mfma_f32_16x16x32_bf16 v[28:31], v[128:131], v[176:179], v[28:31]
	v_mfma_f32_16x16x32_bf16 v[24:27], v[136:139], v[176:179], v[24:27]
	v_mfma_f32_16x16x32_bf16 v[12:15], v[128:131], v[194:197], v[12:15]
	v_mfma_f32_16x16x32_bf16 v[8:11], v[136:139], v[194:197], v[8:11]
	v_mfma_f32_16x16x32_bf16 v[60:63], v[132:135], v[148:151], v[60:63]
	v_mfma_f32_16x16x32_bf16 v[56:59], v[140:143], v[148:151], v[56:59]
	v_mfma_f32_16x16x32_bf16 v[44:47], v[132:135], v[172:175], v[44:47]
	v_mfma_f32_16x16x32_bf16 v[40:43], v[140:143], v[172:175], v[40:43]
	v_mfma_f32_16x16x32_bf16 v[28:31], v[132:135], v[180:183], v[28:31]
	v_mfma_f32_16x16x32_bf16 v[24:27], v[140:143], v[180:183], v[24:27]
	v_mfma_f32_16x16x32_bf16 v[12:15], v[132:135], v[198:201], v[12:15]
	v_mfma_f32_16x16x32_bf16 v[8:11], v[140:143], v[198:201], v[8:11]
	s_barrier
	s_add_u32 s14, s20, 0xb0000
	s_addc_u32 s15, s21, 0
	s_add_i32 s52, s44, s31
	s_mov_b32 m0, s52
	v_lshl_add_u64 v[128:129], s[14:15], 0, v[154:155]
	global_load_lds_dwordx4 v[128:129], off
	s_add_i32 m0, s52, 0x2000
	v_lshl_add_u64 v[128:129], s[14:15], 0, v[158:159]
	global_load_lds_dwordx4 v[128:129], off
	s_waitcnt vmcnt(6)
	s_barrier
	v_mfma_f32_16x16x32_bf16 v[52:55], v[202:205], v[144:147], v[52:55]
	v_mfma_f32_16x16x32_bf16 v[48:51], v[210:213], v[144:147], v[48:51]
	v_mfma_f32_16x16x32_bf16 v[36:39], v[202:205], v[168:171], v[36:39]
	v_mfma_f32_16x16x32_bf16 v[32:35], v[210:213], v[168:171], v[32:35]
	v_mfma_f32_16x16x32_bf16 v[20:23], v[202:205], v[176:179], v[20:23]
	v_mfma_f32_16x16x32_bf16 v[16:19], v[210:213], v[176:179], v[16:19]
	v_mfma_f32_16x16x32_bf16 v[4:7], v[202:205], v[194:197], v[4:7]
	v_mfma_f32_16x16x32_bf16 v[0:3], v[210:213], v[194:197], v[0:3]
	v_mfma_f32_16x16x32_bf16 v[52:55], v[206:209], v[148:151], v[52:55]
	v_mfma_f32_16x16x32_bf16 v[48:51], v[214:217], v[148:151], v[48:51]
	v_mfma_f32_16x16x32_bf16 v[36:39], v[206:209], v[172:175], v[36:39]
	v_mfma_f32_16x16x32_bf16 v[32:35], v[214:217], v[172:175], v[32:35]
	v_mfma_f32_16x16x32_bf16 v[20:23], v[206:209], v[180:183], v[20:23]
	v_mfma_f32_16x16x32_bf16 v[16:19], v[214:217], v[180:183], v[16:19]
	v_mfma_f32_16x16x32_bf16 v[4:7], v[206:209], v[198:201], v[4:7]
	v_mfma_f32_16x16x32_bf16 v[0:3], v[214:217], v[198:201], v[0:3]
	s_add_i32 s52, 0, 0x18000
	v_add_u32_e32 v140, s52, v187
	s_barrier
	ds_read_b128 v[128:131], v140
	ds_read_b128 v[132:135], v140 offset:1024
	ds_read_b128 v[136:139], v140 offset:2048
	ds_read_b128 v[140:143], v140 offset:3072
	s_add_u32 s14, s22, 0xb0000
	s_addc_u32 s15, s23, 0
	s_mov_b32 m0, s36
	v_lshl_add_u64 v[202:203], s[14:15], 0, v[152:153]
	ds_read_b128 v[144:147], v191 offset:32768
	ds_read_b128 v[148:151], v191 offset:33792
	ds_read_b128 v[168:171], v191 offset:34816
	ds_read_b128 v[172:175], v191 offset:35840
	ds_read_b128 v[176:179], v191 offset:36864
	ds_read_b128 v[180:183], v191 offset:37888
	ds_read_b128 v[194:197], v191 offset:38912
	ds_read_b128 v[198:201], v191 offset:39936
	global_load_lds_dwordx4 v[202:203], off
	s_mov_b32 m0, s37
	v_lshl_add_u64 v[202:203], s[14:15], 0, v[156:157]
	global_load_lds_dwordx4 v[202:203], off
	s_waitcnt lgkmcnt(8)
	s_barrier
	s_waitcnt lgkmcnt(0)
	v_mfma_f32_16x16x32_bf16 v[124:127], v[128:131], v[144:147], v[124:127]
	v_mfma_f32_16x16x32_bf16 v[120:123], v[136:139], v[144:147], v[120:123]
	v_mfma_f32_16x16x32_bf16 v[108:111], v[128:131], v[168:171], v[108:111]
	v_mfma_f32_16x16x32_bf16 v[104:107], v[136:139], v[168:171], v[104:107]
	v_mfma_f32_16x16x32_bf16 v[92:95], v[128:131], v[176:179], v[92:95]
	v_mfma_f32_16x16x32_bf16 v[88:91], v[136:139], v[176:179], v[88:91]
	v_mfma_f32_16x16x32_bf16 v[76:79], v[128:131], v[194:197], v[76:79]
	v_mfma_f32_16x16x32_bf16 v[72:75], v[136:139], v[194:197], v[72:75]
	v_mfma_f32_16x16x32_bf16 v[124:127], v[132:135], v[148:151], v[124:127]
	v_mfma_f32_16x16x32_bf16 v[120:123], v[140:143], v[148:151], v[120:123]
	v_mfma_f32_16x16x32_bf16 v[108:111], v[132:135], v[172:175], v[108:111]
	v_mfma_f32_16x16x32_bf16 v[104:107], v[140:143], v[172:175], v[104:107]
	v_mfma_f32_16x16x32_bf16 v[92:95], v[132:135], v[180:183], v[92:95]
	v_mfma_f32_16x16x32_bf16 v[88:91], v[140:143], v[180:183], v[88:91]
	v_mfma_f32_16x16x32_bf16 v[76:79], v[132:135], v[198:201], v[76:79]
	v_mfma_f32_16x16x32_bf16 v[72:75], v[140:143], v[198:201], v[72:75]
	s_barrier
	s_add_i32 s22, 0, 0x1c000
	s_add_i32 s14, s52, s31
	v_add_u32_e32 v214, s22, v187
	v_lshl_add_u64 v[184:185], v[184:185], 0, s[12:13]
	s_mov_b32 m0, s14
	ds_read_b128 v[202:205], v214
	ds_read_b128 v[206:209], v214 offset:1024
	ds_read_b128 v[210:213], v214 offset:2048
	ds_read_b128 v[214:217], v214 offset:3072
	global_load_lds_dwordx4 v[184:185], off
	s_add_i32 m0, s14, 0x2000
	v_lshl_add_u64 v[184:185], v[218:219], 0, s[12:13]
	global_load_lds_dwordx4 v[184:185], off
	s_barrier
	s_waitcnt lgkmcnt(0)
	v_mfma_f32_16x16x32_bf16 v[116:119], v[202:205], v[144:147], v[116:119]
	v_mfma_f32_16x16x32_bf16 v[112:115], v[210:213], v[144:147], v[112:115]
	v_mfma_f32_16x16x32_bf16 v[100:103], v[202:205], v[168:171], v[100:103]
	v_mfma_f32_16x16x32_bf16 v[96:99], v[210:213], v[168:171], v[96:99]
	v_mfma_f32_16x16x32_bf16 v[84:87], v[202:205], v[176:179], v[84:87]
	v_mfma_f32_16x16x32_bf16 v[80:83], v[210:213], v[176:179], v[80:83]
	v_mfma_f32_16x16x32_bf16 v[68:71], v[202:205], v[194:197], v[68:71]
	v_mfma_f32_16x16x32_bf16 v[64:67], v[210:213], v[194:197], v[64:67]
	v_mfma_f32_16x16x32_bf16 v[116:119], v[206:209], v[148:151], v[116:119]
	v_mfma_f32_16x16x32_bf16 v[112:115], v[214:217], v[148:151], v[112:115]
	v_mfma_f32_16x16x32_bf16 v[100:103], v[206:209], v[172:175], v[100:103]
	v_mfma_f32_16x16x32_bf16 v[96:99], v[214:217], v[172:175], v[96:99]
	v_mfma_f32_16x16x32_bf16 v[84:87], v[206:209], v[180:183], v[84:87]
	v_mfma_f32_16x16x32_bf16 v[80:83], v[214:217], v[180:183], v[80:83]
	v_mfma_f32_16x16x32_bf16 v[68:71], v[206:209], v[198:201], v[68:71]
	v_mfma_f32_16x16x32_bf16 v[64:67], v[214:217], v[198:201], v[64:67]
	s_mov_b32 m0, s39
	v_lshl_add_u64 v[184:185], v[220:221], 0, s[12:13]
	s_barrier
	ds_read_b128 v[144:147], v191 offset:49152
	ds_read_b128 v[148:151], v191 offset:50176
	ds_read_b128 v[168:171], v191 offset:51200
	ds_read_b128 v[172:175], v191 offset:52224
	ds_read_b128 v[176:179], v191 offset:53248
	ds_read_b128 v[180:183], v191 offset:54272
	ds_read_b128 v[194:197], v191 offset:55296
	ds_read_b128 v[198:201], v191 offset:56320
	global_load_lds_dwordx4 v[184:185], off
	s_mov_b32 m0, s40
	v_lshl_add_u64 v[184:185], v[222:223], 0, s[12:13]
	global_load_lds_dwordx4 v[184:185], off
	s_barrier
	s_waitcnt lgkmcnt(0)
	v_mfma_f32_16x16x32_bf16 v[60:63], v[128:131], v[144:147], v[60:63]
	v_mfma_f32_16x16x32_bf16 v[56:59], v[136:139], v[144:147], v[56:59]
	v_mfma_f32_16x16x32_bf16 v[44:47], v[128:131], v[168:171], v[44:47]
	v_mfma_f32_16x16x32_bf16 v[40:43], v[136:139], v[168:171], v[40:43]
	v_mfma_f32_16x16x32_bf16 v[28:31], v[128:131], v[176:179], v[28:31]
	v_mfma_f32_16x16x32_bf16 v[24:27], v[136:139], v[176:179], v[24:27]
	v_mfma_f32_16x16x32_bf16 v[12:15], v[128:131], v[194:197], v[12:15]
	v_mfma_f32_16x16x32_bf16 v[8:11], v[136:139], v[194:197], v[8:11]
	v_mfma_f32_16x16x32_bf16 v[60:63], v[132:135], v[148:151], v[60:63]
	v_mfma_f32_16x16x32_bf16 v[56:59], v[140:143], v[148:151], v[56:59]
	v_mfma_f32_16x16x32_bf16 v[44:47], v[132:135], v[172:175], v[44:47]
	v_mfma_f32_16x16x32_bf16 v[40:43], v[140:143], v[172:175], v[40:43]
	v_mfma_f32_16x16x32_bf16 v[28:31], v[132:135], v[180:183], v[28:31]
	v_mfma_f32_16x16x32_bf16 v[24:27], v[140:143], v[180:183], v[24:27]
	v_mfma_f32_16x16x32_bf16 v[12:15], v[132:135], v[198:201], v[12:15]
	v_mfma_f32_16x16x32_bf16 v[8:11], v[140:143], v[198:201], v[8:11]
	s_barrier
	s_add_u32 s14, s20, 0xb0080
	s_addc_u32 s15, s21, 0
	s_add_i32 s20, s22, s31
	s_mov_b32 m0, s20
	v_lshl_add_u64 v[128:129], s[14:15], 0, v[154:155]
	global_load_lds_dwordx4 v[128:129], off
	s_add_i32 m0, s20, 0x2000
	v_lshl_add_u64 v[128:129], s[14:15], 0, v[158:159]
	global_load_lds_dwordx4 v[128:129], off
	s_waitcnt vmcnt(6)
	s_barrier
	v_mfma_f32_16x16x32_bf16 v[52:55], v[202:205], v[144:147], v[52:55]
	v_mfma_f32_16x16x32_bf16 v[48:51], v[210:213], v[144:147], v[48:51]
	v_mfma_f32_16x16x32_bf16 v[36:39], v[202:205], v[168:171], v[36:39]
	v_mfma_f32_16x16x32_bf16 v[32:35], v[210:213], v[168:171], v[32:35]
	v_mfma_f32_16x16x32_bf16 v[20:23], v[202:205], v[176:179], v[20:23]
	v_mfma_f32_16x16x32_bf16 v[16:19], v[210:213], v[176:179], v[16:19]
	v_mfma_f32_16x16x32_bf16 v[4:7], v[202:205], v[194:197], v[4:7]
	v_mfma_f32_16x16x32_bf16 v[0:3], v[210:213], v[194:197], v[0:3]
	v_mfma_f32_16x16x32_bf16 v[52:55], v[206:209], v[148:151], v[52:55]
	v_mfma_f32_16x16x32_bf16 v[48:51], v[214:217], v[148:151], v[48:51]
	v_mfma_f32_16x16x32_bf16 v[36:39], v[206:209], v[172:175], v[36:39]
	v_mfma_f32_16x16x32_bf16 v[32:35], v[214:217], v[172:175], v[32:35]
	v_mfma_f32_16x16x32_bf16 v[20:23], v[206:209], v[180:183], v[20:23]
	v_mfma_f32_16x16x32_bf16 v[16:19], v[214:217], v[180:183], v[16:19]
	v_mfma_f32_16x16x32_bf16 v[4:7], v[206:209], v[198:201], v[4:7]
	v_mfma_f32_16x16x32_bf16 v[0:3], v[214:217], v[198:201], v[0:3]
	s_add_i32 s51, s51, 2
	s_add_u32 s49, s49, 0x100
	s_addc_u32 s50, s50, 0
	s_cmp_gt_u32 s51, 41
	s_mov_b64 s[14:15], s[18:19]
	s_barrier
	s_cbranch_scc0 .LBB0_554
	v_lshl_or_b32 v168, s10, 8, v189
	v_lshl_add_u32 v170, s48, 8, v186
	v_ashrrev_i32_e32 v169, 31, v168
	v_lshlrev_b64 v[202:203], 1, v[168:169]
	v_ashrrev_i32_e32 v171, 31, v170
	v_or_b32_e32 v182, 16, v170
	v_lshl_add_u64 v[172:173], s[64:65], 0, v[202:203]
	v_lshlrev_b64 v[204:205], 11, v[170:171]
	v_ashrrev_i32_e32 v183, 31, v182
	v_or_b32_e32 v178, 32, v170
	v_lshl_add_u64 v[128:129], v[172:173], 0, v[204:205]
	v_lshlrev_b64 v[184:185], 11, v[182:183]
	v_ashrrev_i32_e32 v179, 31, v178
	v_or_b32_e32 v174, 48, v170
	global_load_dwordx4 v[194:197], v[128:129], off
	global_load_dwordx4 v[198:201], v[128:129], off offset:256
	v_lshl_add_u64 v[128:129], v[172:173], 0, v[184:185]
	v_lshlrev_b64 v[180:181], 11, v[178:179]
	v_ashrrev_i32_e32 v175, 31, v174
	global_load_dwordx4 v[148:151], v[128:129], off
	global_load_dwordx4 v[144:147], v[128:129], off offset:256
	v_lshl_add_u64 v[128:129], v[172:173], 0, v[180:181]
	v_lshlrev_b64 v[176:177], 11, v[174:175]
	global_load_dwordx4 v[140:143], v[128:129], off
	global_load_dwordx4 v[136:139], v[128:129], off offset:256
	v_lshl_add_u64 v[128:129], v[172:173], 0, v[176:177]
	global_load_dwordx4 v[132:135], v[128:129], off
	s_nop 0
	global_load_dwordx4 v[128:131], v[128:129], off offset:256
	s_lshl_b32 s14, s10, 2
	s_ashr_i32 s15, s14, 31
	v_add_u32_e32 v252, 0x80, v170
	v_ashrrev_i32_e32 v253, 31, v252
	v_lshlrev_b64 v[252:253], 11, v[252:253]
	v_lshl_add_u64 v[252:253], v[172:173], 0, v[252:253]
	global_load_dwordx4 v[236:239], v[252:253], off
	global_load_dwordx4 v[240:243], v[252:253], off offset:256
	v_add_u32_e32 v252, 0x90, v170
	v_ashrrev_i32_e32 v253, 31, v252
	v_lshlrev_b64 v[252:253], 11, v[252:253]
	v_lshl_add_u64 v[252:253], v[172:173], 0, v[252:253]
	global_load_dwordx4 v[244:247], v[252:253], off
	global_load_dwordx4 v[248:251], v[252:253], off offset:256
	v_add_u32_e32 v252, 0xa0, v170
	v_ashrrev_i32_e32 v253, 31, v252
	v_lshlrev_b64 v[252:253], 11, v[252:253]
	v_lshl_add_u64 v[252:253], v[172:173], 0, v[252:253]
	global_load_dwordx4 v[210:213], v[252:253], off
	global_load_dwordx4 v[214:217], v[252:253], off offset:256
	s_waitcnt vmcnt(6)
	v_lshlrev_b32_e32 v206, 16, v194
	v_and_b32_e32 v207, 0xffff0000, v194
	v_lshlrev_b32_e32 v194, 16, v195
	v_and_b32_e32 v195, 0xffff0000, v195
	v_lshlrev_b32_e32 v208, 16, v196
	v_and_b32_e32 v209, 0xffff0000, v196
	v_lshlrev_b32_e32 v196, 16, v197
	v_and_b32_e32 v197, 0xffff0000, v197
	v_pk_add_f32 v[126:127], v[126:127], v[194:195]
	v_pk_add_f32 v[124:125], v[124:125], v[206:207]
	v_pk_add_f32 v[194:195], v[122:123], v[196:197]
	v_pk_add_f32 v[122:123], v[120:121], v[208:209]
	v_mul_f32_e32 v120, v125, v125
	v_mul_f32_e32 v121, v127, v127
	v_fmac_f32_e32 v120, v124, v124
	v_fmac_f32_e32 v121, v126, v126
	v_add_f32_e32 v120, v120, v121
	v_mul_f32_e32 v121, v123, v123
	v_mul_f32_e32 v196, v195, v195
	v_fmac_f32_e32 v121, v122, v122
	v_fmac_f32_e32 v196, v194, v194
	v_add_f32_e32 v121, v121, v196
	v_add_f32_e32 v206, v120, v121
	v_cvt_pk_bf16_f32 v120, v124, v125
	v_cvt_pk_bf16_f32 v121, v126, v127
	v_lshlrev_b32_e32 v124, 16, v198
	v_and_b32_e32 v125, 0xffff0000, v198
	v_lshlrev_b32_e32 v126, 16, v199
	v_and_b32_e32 v127, 0xffff0000, v199
	v_cvt_pk_bf16_f32 v122, v122, v123
	v_cvt_pk_bf16_f32 v123, v194, v195
	v_lshlrev_b32_e32 v194, 16, v200
	v_and_b32_e32 v195, 0xffff0000, v200
	v_pk_add_f32 v[118:119], v[118:119], v[126:127]
	v_pk_add_f32 v[116:117], v[116:117], v[124:125]
	v_lshlrev_b32_e32 v196, 16, v201
	v_and_b32_e32 v197, 0xffff0000, v201
	v_pk_add_f32 v[126:127], v[112:113], v[194:195]
	v_mul_f32_e32 v112, v117, v117
	v_mul_f32_e32 v113, v119, v119
	v_pk_add_f32 v[124:125], v[114:115], v[196:197]
	v_fmac_f32_e32 v112, v116, v116
	v_fmac_f32_e32 v113, v118, v118
	v_add_f32_e32 v112, v112, v113
	v_mul_f32_e32 v113, v127, v127
	v_mul_f32_e32 v114, v125, v125
	v_fmac_f32_e32 v113, v126, v126
	v_fmac_f32_e32 v114, v124, v124
	v_add_f32_e32 v113, v113, v114
	v_add_f32_e32 v112, v112, v113
	v_and_b32_e32 v114, 64, v193
	v_add_f32_e32 v113, v206, v112
	v_xor_b32_e32 v112, 16, v193
	v_add_u32_e32 v196, 64, v114
	v_cmp_lt_i32_e32 vcc, v112, v196
	v_lshl_add_u64 v[114:115], s[64:65], 0, v[204:205]
	v_lshl_add_u64 v[194:195], v[114:115], 0, v[202:203]
	v_cndmask_b32_e32 v112, v193, v112, vcc
	v_lshlrev_b32_e32 v112, 2, v112
	ds_bpermute_b32 v197, v112, v113
	global_store_dwordx4 v[194:195], v[120:123], off
	v_cvt_pk_bf16_f32 v116, v116, v117
	v_cvt_pk_bf16_f32 v117, v118, v119
	v_cvt_pk_bf16_f32 v118, v126, v127
	s_waitcnt lgkmcnt(0)
	v_add_f32_e32 v114, v113, v197
	v_xor_b32_e32 v113, 32, v193
	v_cmp_lt_i32_e32 vcc, v113, v196
	v_cvt_pk_bf16_f32 v119, v124, v125
	global_store_dwordx4 v[194:195], v[116:119], off offset:256
	s_nop 0
	v_cndmask_b32_e32 v113, v193, v113, vcc
	v_lshlrev_b32_e32 v113, 2, v113
	ds_bpermute_b32 v115, v113, v114
	s_and_saveexec_b64 s[18:19], s[2:3]
	s_cbranch_execz .LBB0_557
	s_waitcnt lgkmcnt(0)
	v_add_f32_e32 v116, v114, v115
	v_lshlrev_b64 v[114:115], 6, v[170:171]
	v_lshl_add_u64 v[114:115], s[74:75], 0, v[114:115]
	v_lshl_add_u64 v[114:115], s[14:15], 2, v[114:115]
	s_lshl_b32 s10, s38, 2
	v_lshl_add_u64 v[114:115], v[114:115], 0, s[10:11]
	global_store_dword v[114:115], v116, off

.LBB0_642:
	ds_read_b128 v[24:27], v178
	ds_read_b128 v[28:31], v178 offset:1024
	ds_read_b128 v[160:163], v178 offset:2048
	ds_read_b128 v[164:167], v178 offset:3072
	s_add_u32 s38, s6, 0xfffc0080
	s_addc_u32 s39, s7, -1
	s_cmp_eq_u32 s68, 12
	s_cselect_b32 s41, s42, s39
	s_cselect_b32 s40, s43, s38
	s_cselect_b32 s39, s23, s67
	s_cselect_b32 s38, s44, s45
	v_lshl_add_u64 v[172:173], s[6:7], 0, v[152:153]
	s_add_i32 m0, s49, 0xc000
	ds_read_b128 v[168:171], v179
	ds_read_b128 v[182:185], v179 offset:1024
	ds_read_b128 v[190:193], v179 offset:2048
	ds_read_b128 v[194:197], v179 offset:3072
	ds_read_b128 v[198:201], v179 offset:4096
	ds_read_b128 v[202:205], v179 offset:5120
	ds_read_b128 v[206:209], v179 offset:6144
	ds_read_b128 v[210:213], v179 offset:7168
	global_load_lds_dwordx4 v[172:173], off
	s_add_i32 m0, s49, 0xe000
	v_lshl_add_u64 v[172:173], s[6:7], 0, v[154:155]
	global_load_lds_dwordx4 v[172:173], off
	s_waitcnt lgkmcnt(8)
	s_barrier
	s_waitcnt lgkmcnt(0)
	v_mfma_f32_16x16x32_bf16 v[132:135], v[24:27], v[168:171], v[132:135]
	v_mfma_f32_16x16x32_bf16 v[128:131], v[160:163], v[168:171], v[128:131]
	v_mfma_f32_16x16x32_bf16 v[116:119], v[24:27], v[190:193], v[116:119]
	v_mfma_f32_16x16x32_bf16 v[112:115], v[160:163], v[190:193], v[112:115]
	v_mfma_f32_16x16x32_bf16 v[100:103], v[24:27], v[198:201], v[100:103]
	v_mfma_f32_16x16x32_bf16 v[96:99], v[160:163], v[198:201], v[96:99]
	v_mfma_f32_16x16x32_bf16 v[84:87], v[24:27], v[206:209], v[84:87]
	v_mfma_f32_16x16x32_bf16 v[80:83], v[160:163], v[206:209], v[80:83]
	v_mfma_f32_16x16x32_bf16 v[132:135], v[28:31], v[182:185], v[132:135]
	v_mfma_f32_16x16x32_bf16 v[128:131], v[164:167], v[182:185], v[128:131]
	v_mfma_f32_16x16x32_bf16 v[116:119], v[28:31], v[194:197], v[116:119]
	v_mfma_f32_16x16x32_bf16 v[112:115], v[164:167], v[194:197], v[112:115]
	v_mfma_f32_16x16x32_bf16 v[100:103], v[28:31], v[202:205], v[100:103]
	v_mfma_f32_16x16x32_bf16 v[96:99], v[164:167], v[202:205], v[96:99]
	v_mfma_f32_16x16x32_bf16 v[84:87], v[28:31], v[210:213], v[84:87]
	v_mfma_f32_16x16x32_bf16 v[80:83], v[164:167], v[210:213], v[80:83]
	s_barrier
	s_add_i32 s69, s59, s48
	v_lshl_add_u64 v[172:173], s[38:39], 0, v[136:137]
	s_mov_b32 m0, s69
	ds_read_b128 v[214:217], v180
	ds_read_b128 v[218:221], v180 offset:1024
	ds_read_b128 v[222:225], v180 offset:2048
	ds_read_b128 v[226:229], v180 offset:3072
	global_load_lds_dwordx4 v[172:173], off
	s_add_i32 m0, s69, 0x2000
	v_lshl_add_u64 v[186:187], s[38:39], 0, v[144:145]
	global_load_lds_dwordx4 v[186:187], off
	s_barrier
	s_waitcnt lgkmcnt(0)
	v_mfma_f32_16x16x32_bf16 v[124:127], v[214:217], v[168:171], v[124:127]
	v_mfma_f32_16x16x32_bf16 v[120:123], v[222:225], v[168:171], v[120:123]
	v_mfma_f32_16x16x32_bf16 v[108:111], v[214:217], v[190:193], v[108:111]
	v_mfma_f32_16x16x32_bf16 v[104:107], v[222:225], v[190:193], v[104:107]
	v_mfma_f32_16x16x32_bf16 v[92:95], v[214:217], v[198:201], v[92:95]
	v_mfma_f32_16x16x32_bf16 v[88:91], v[222:225], v[198:201], v[88:91]
	v_mfma_f32_16x16x32_bf16 v[76:79], v[214:217], v[206:209], v[76:79]
	v_mfma_f32_16x16x32_bf16 v[72:75], v[222:225], v[206:209], v[72:75]
	v_mfma_f32_16x16x32_bf16 v[124:127], v[218:221], v[182:185], v[124:127]
	v_mfma_f32_16x16x32_bf16 v[120:123], v[226:229], v[182:185], v[120:123]
	v_mfma_f32_16x16x32_bf16 v[108:111], v[218:221], v[194:197], v[108:111]
	v_mfma_f32_16x16x32_bf16 v[104:107], v[226:229], v[194:197], v[104:107]
	v_mfma_f32_16x16x32_bf16 v[92:95], v[218:221], v[202:205], v[92:95]
	v_mfma_f32_16x16x32_bf16 v[88:91], v[226:229], v[202:205], v[88:91]
	v_mfma_f32_16x16x32_bf16 v[76:79], v[218:221], v[210:213], v[76:79]
	v_mfma_f32_16x16x32_bf16 v[72:75], v[226:229], v[210:213], v[72:75]
	s_mov_b32 m0, s49
	v_lshl_add_u64 v[230:231], s[40:41], 0, v[140:141]
	s_barrier
	ds_read_b128 v[168:171], v179 offset:16384
	ds_read_b128 v[182:185], v179 offset:17408
	ds_read_b128 v[190:193], v179 offset:18432
	ds_read_b128 v[194:197], v179 offset:19456
	ds_read_b128 v[198:201], v179 offset:20480
	ds_read_b128 v[202:205], v179 offset:21504
	ds_read_b128 v[206:209], v179 offset:22528
	ds_read_b128 v[210:213], v179 offset:23552
	global_load_lds_dwordx4 v[230:231], off
	s_mov_b32 m0, s50
	v_lshl_add_u64 v[232:233], s[40:41], 0, v[142:143]
	global_load_lds_dwordx4 v[232:233], off
	s_barrier
	s_waitcnt lgkmcnt(0)
	v_mfma_f32_16x16x32_bf16 v[68:71], v[24:27], v[168:171], v[68:71]
	v_mfma_f32_16x16x32_bf16 v[64:67], v[160:163], v[168:171], v[64:67]
	v_mfma_f32_16x16x32_bf16 v[52:55], v[24:27], v[190:193], v[52:55]
	v_mfma_f32_16x16x32_bf16 v[48:51], v[160:163], v[190:193], v[48:51]
	v_mfma_f32_16x16x32_bf16 v[36:39], v[24:27], v[198:201], v[36:39]
	v_mfma_f32_16x16x32_bf16 v[32:35], v[160:163], v[198:201], v[32:35]
	v_mfma_f32_16x16x32_bf16 v[12:15], v[24:27], v[206:209], v[12:15]
	v_mfma_f32_16x16x32_bf16 v[8:11], v[160:163], v[206:209], v[8:11]
	v_mfma_f32_16x16x32_bf16 v[68:71], v[28:31], v[182:185], v[68:71]
	v_mfma_f32_16x16x32_bf16 v[64:67], v[164:167], v[182:185], v[64:67]
	v_mfma_f32_16x16x32_bf16 v[52:55], v[28:31], v[194:197], v[52:55]
	v_mfma_f32_16x16x32_bf16 v[48:51], v[164:167], v[194:197], v[48:51]
	v_mfma_f32_16x16x32_bf16 v[36:39], v[28:31], v[202:205], v[36:39]
	v_mfma_f32_16x16x32_bf16 v[32:35], v[164:167], v[202:205], v[32:35]
	v_mfma_f32_16x16x32_bf16 v[12:15], v[28:31], v[210:213], v[12:15]
	v_mfma_f32_16x16x32_bf16 v[8:11], v[164:167], v[210:213], v[8:11]
	s_barrier
	s_add_u32 s70, s38, 0x40000
	s_addc_u32 s71, s39, 0
	s_add_i32 s69, s60, s48
	s_mov_b32 m0, s69
	v_lshl_add_u64 v[24:25], s[70:71], 0, v[136:137]
	global_load_lds_dwordx4 v[24:25], off
	s_add_i32 m0, s69, 0x2000
	v_lshl_add_u64 v[24:25], s[70:71], 0, v[144:145]
	global_load_lds_dwordx4 v[24:25], off
	s_waitcnt vmcnt(6)
	s_barrier
	v_mfma_f32_16x16x32_bf16 v[44:47], v[214:217], v[190:193], v[44:47]
	v_mfma_f32_16x16x32_bf16 v[40:43], v[222:225], v[190:193], v[40:43]
	v_mfma_f32_16x16x32_bf16 v[20:23], v[214:217], v[198:201], v[20:23]
	v_mfma_f32_16x16x32_bf16 v[16:19], v[222:225], v[198:201], v[16:19]
	v_mfma_f32_16x16x32_bf16 v[4:7], v[214:217], v[206:209], v[4:7]
	v_mfma_f32_16x16x32_bf16 v[0:3], v[222:225], v[206:209], v[0:3]
	v_mfma_f32_16x16x32_bf16 v[24:27], v[214:217], v[168:171], v[60:63]
	v_mfma_f32_16x16x32_bf16 v[28:31], v[222:225], v[168:171], v[56:59]
	v_mfma_f32_16x16x32_bf16 v[44:47], v[218:221], v[194:197], v[44:47]
	v_mfma_f32_16x16x32_bf16 v[40:43], v[226:229], v[194:197], v[40:43]
	v_mfma_f32_16x16x32_bf16 v[20:23], v[218:221], v[202:205], v[20:23]
	v_mfma_f32_16x16x32_bf16 v[16:19], v[226:229], v[202:205], v[16:19]
	v_mfma_f32_16x16x32_bf16 v[4:7], v[218:221], v[210:213], v[4:7]
	v_mfma_f32_16x16x32_bf16 v[0:3], v[226:229], v[210:213], v[0:3]
	v_mfma_f32_16x16x32_bf16 v[24:27], v[218:221], v[182:185], v[24:27]
	v_mfma_f32_16x16x32_bf16 v[28:31], v[226:229], v[182:185], v[28:31]
	s_add_i32 s69, 0, 0x18000
	v_add_u32_e32 v138, s69, v175
	s_barrier
	ds_read_b128 v[56:59], v138
	ds_read_b128 v[60:63], v138 offset:1024
	ds_read_b128 v[160:163], v138 offset:2048
	ds_read_b128 v[164:167], v138 offset:3072
	s_add_u32 s40, s40, 0x40000
	s_addc_u32 s41, s41, 0
	s_mov_b32 m0, s51
	v_lshl_add_u64 v[214:215], s[40:41], 0, v[140:141]
	ds_read_b128 v[168:171], v179 offset:32768
	ds_read_b128 v[182:185], v179 offset:33792
	ds_read_b128 v[190:193], v179 offset:34816
	ds_read_b128 v[194:197], v179 offset:35840
	ds_read_b128 v[198:201], v179 offset:36864
	ds_read_b128 v[202:205], v179 offset:37888
	ds_read_b128 v[206:209], v179 offset:38912
	ds_read_b128 v[210:213], v179 offset:39936
	global_load_lds_dwordx4 v[214:215], off
	s_mov_b32 m0, s52
	v_lshl_add_u64 v[214:215], s[40:41], 0, v[142:143]
	global_load_lds_dwordx4 v[214:215], off
	s_waitcnt lgkmcnt(8)
	s_barrier
	s_waitcnt lgkmcnt(0)
	v_mfma_f32_16x16x32_bf16 v[132:135], v[56:59], v[168:171], v[132:135]
	v_mfma_f32_16x16x32_bf16 v[128:131], v[160:163], v[168:171], v[128:131]
	v_mfma_f32_16x16x32_bf16 v[116:119], v[56:59], v[190:193], v[116:119]
	v_mfma_f32_16x16x32_bf16 v[112:115], v[160:163], v[190:193], v[112:115]
	v_mfma_f32_16x16x32_bf16 v[100:103], v[56:59], v[198:201], v[100:103]
	v_mfma_f32_16x16x32_bf16 v[96:99], v[160:163], v[198:201], v[96:99]
	v_mfma_f32_16x16x32_bf16 v[84:87], v[56:59], v[206:209], v[84:87]
	v_mfma_f32_16x16x32_bf16 v[80:83], v[160:163], v[206:209], v[80:83]
	v_mfma_f32_16x16x32_bf16 v[132:135], v[60:63], v[182:185], v[132:135]
	v_mfma_f32_16x16x32_bf16 v[128:131], v[164:167], v[182:185], v[128:131]
	v_mfma_f32_16x16x32_bf16 v[116:119], v[60:63], v[194:197], v[116:119]
	v_mfma_f32_16x16x32_bf16 v[112:115], v[164:167], v[194:197], v[112:115]
	v_mfma_f32_16x16x32_bf16 v[100:103], v[60:63], v[202:205], v[100:103]
	v_mfma_f32_16x16x32_bf16 v[96:99], v[164:167], v[202:205], v[96:99]
	v_mfma_f32_16x16x32_bf16 v[84:87], v[60:63], v[210:213], v[84:87]
	v_mfma_f32_16x16x32_bf16 v[80:83], v[164:167], v[210:213], v[80:83]
	s_barrier
	s_add_i32 s40, 0, 0x1c000
	s_add_i32 s41, s69, s48
	v_add_u32_e32 v138, s40, v175
	v_lshl_add_u64 v[172:173], v[172:173], 0, s[12:13]
	s_mov_b32 m0, s41
	ds_read_b128 v[214:217], v138
	ds_read_b128 v[218:221], v138 offset:1024
	ds_read_b128 v[222:225], v138 offset:2048
	ds_read_b128 v[226:229], v138 offset:3072
	global_load_lds_dwordx4 v[172:173], off
	s_add_i32 m0, s41, 0x2000
	v_lshl_add_u64 v[172:173], v[186:187], 0, s[12:13]
	global_load_lds_dwordx4 v[172:173], off
	s_barrier
	s_waitcnt lgkmcnt(0)
	v_mfma_f32_16x16x32_bf16 v[124:127], v[214:217], v[168:171], v[124:127]
	v_mfma_f32_16x16x32_bf16 v[120:123], v[222:225], v[168:171], v[120:123]
	v_mfma_f32_16x16x32_bf16 v[108:111], v[214:217], v[190:193], v[108:111]
	v_mfma_f32_16x16x32_bf16 v[104:107], v[222:225], v[190:193], v[104:107]
	v_mfma_f32_16x16x32_bf16 v[92:95], v[214:217], v[198:201], v[92:95]
	v_mfma_f32_16x16x32_bf16 v[88:91], v[222:225], v[198:201], v[88:91]
	v_mfma_f32_16x16x32_bf16 v[76:79], v[214:217], v[206:209], v[76:79]
	v_mfma_f32_16x16x32_bf16 v[72:75], v[222:225], v[206:209], v[72:75]
	v_mfma_f32_16x16x32_bf16 v[124:127], v[218:221], v[182:185], v[124:127]
	v_mfma_f32_16x16x32_bf16 v[120:123], v[226:229], v[182:185], v[120:123]
	v_mfma_f32_16x16x32_bf16 v[108:111], v[218:221], v[194:197], v[108:111]
	v_mfma_f32_16x16x32_bf16 v[104:107], v[226:229], v[194:197], v[104:107]
	v_mfma_f32_16x16x32_bf16 v[92:95], v[218:221], v[202:205], v[92:95]
	v_mfma_f32_16x16x32_bf16 v[88:91], v[226:229], v[202:205], v[88:91]
	v_mfma_f32_16x16x32_bf16 v[76:79], v[218:221], v[210:213], v[76:79]
	v_mfma_f32_16x16x32_bf16 v[72:75], v[226:229], v[210:213], v[72:75]
	s_mov_b32 m0, s54
	v_lshl_add_u64 v[172:173], v[230:231], 0, s[12:13]
	s_barrier
	ds_read_b128 v[168:171], v179 offset:49152
	ds_read_b128 v[182:185], v179 offset:50176
	ds_read_b128 v[190:193], v179 offset:51200
	ds_read_b128 v[194:197], v179 offset:52224
	ds_read_b128 v[198:201], v179 offset:53248
	ds_read_b128 v[202:205], v179 offset:54272
	ds_read_b128 v[206:209], v179 offset:55296
	ds_read_b128 v[210:213], v179 offset:56320
	global_load_lds_dwordx4 v[172:173], off
	s_mov_b32 m0, s55
	v_lshl_add_u64 v[172:173], v[232:233], 0, s[12:13]
	global_load_lds_dwordx4 v[172:173], off
	s_barrier
	s_waitcnt lgkmcnt(0)
	v_mfma_f32_16x16x32_bf16 v[68:71], v[56:59], v[168:171], v[68:71]
	v_mfma_f32_16x16x32_bf16 v[64:67], v[160:163], v[168:171], v[64:67]
	v_mfma_f32_16x16x32_bf16 v[52:55], v[56:59], v[190:193], v[52:55]
	v_mfma_f32_16x16x32_bf16 v[48:51], v[160:163], v[190:193], v[48:51]
	v_mfma_f32_16x16x32_bf16 v[36:39], v[56:59], v[198:201], v[36:39]
	v_mfma_f32_16x16x32_bf16 v[32:35], v[160:163], v[198:201], v[32:35]
	v_mfma_f32_16x16x32_bf16 v[12:15], v[56:59], v[206:209], v[12:15]
	v_mfma_f32_16x16x32_bf16 v[8:11], v[160:163], v[206:209], v[8:11]
	v_mfma_f32_16x16x32_bf16 v[68:71], v[60:63], v[182:185], v[68:71]
	v_mfma_f32_16x16x32_bf16 v[64:67], v[164:167], v[182:185], v[64:67]
	v_mfma_f32_16x16x32_bf16 v[52:55], v[60:63], v[194:197], v[52:55]
	v_mfma_f32_16x16x32_bf16 v[48:51], v[164:167], v[194:197], v[48:51]
	v_mfma_f32_16x16x32_bf16 v[36:39], v[60:63], v[202:205], v[36:39]
	v_mfma_f32_16x16x32_bf16 v[32:35], v[164:167], v[202:205], v[32:35]
	v_mfma_f32_16x16x32_bf16 v[12:15], v[60:63], v[210:213], v[12:15]
	v_mfma_f32_16x16x32_bf16 v[8:11], v[164:167], v[210:213], v[8:11]
	s_barrier
	s_add_u32 s38, s38, 0x40080
	s_addc_u32 s39, s39, 0
	s_add_i32 s40, s40, s48
	s_mov_b32 m0, s40
	v_lshl_add_u64 v[56:57], s[38:39], 0, v[136:137]
	global_load_lds_dwordx4 v[56:57], off
	s_add_i32 m0, s40, 0x2000
	v_lshl_add_u64 v[56:57], s[38:39], 0, v[144:145]
	global_load_lds_dwordx4 v[56:57], off
	s_waitcnt vmcnt(6)
	s_barrier
	v_mfma_f32_16x16x32_bf16 v[24:27], v[214:217], v[168:171], v[24:27]
	v_mfma_f32_16x16x32_bf16 v[60:63], v[218:221], v[182:185], v[24:27]
	v_mfma_f32_16x16x32_bf16 v[24:27], v[222:225], v[168:171], v[28:31]
	v_mfma_f32_16x16x32_bf16 v[56:59], v[226:229], v[182:185], v[24:27]
	v_mfma_f32_16x16x32_bf16 v[24:27], v[214:217], v[190:193], v[44:47]
	v_mfma_f32_16x16x32_bf16 v[44:47], v[218:221], v[194:197], v[24:27]
	v_mfma_f32_16x16x32_bf16 v[24:27], v[222:225], v[190:193], v[40:43]
	v_mfma_f32_16x16x32_bf16 v[20:23], v[214:217], v[198:201], v[20:23]
	v_mfma_f32_16x16x32_bf16 v[16:19], v[222:225], v[198:201], v[16:19]
	v_mfma_f32_16x16x32_bf16 v[4:7], v[214:217], v[206:209], v[4:7]
	v_mfma_f32_16x16x32_bf16 v[0:3], v[222:225], v[206:209], v[0:3]
	v_mfma_f32_16x16x32_bf16 v[40:43], v[226:229], v[194:197], v[24:27]
	v_mfma_f32_16x16x32_bf16 v[20:23], v[218:221], v[202:205], v[20:23]
	v_mfma_f32_16x16x32_bf16 v[16:19], v[226:229], v[202:205], v[16:19]
	v_mfma_f32_16x16x32_bf16 v[4:7], v[218:221], v[210:213], v[4:7]
	v_mfma_f32_16x16x32_bf16 v[0:3], v[226:229], v[210:213], v[0:3]
	s_add_i32 s68, s68, 2
	s_add_u32 s6, s6, 0x100
	s_addc_u32 s7, s7, 0
	s_add_u32 s45, s45, 0x100
	s_addc_u32 s67, s67, 0
	s_cmp_gt_u32 s68, 13
	s_barrier
	s_cbranch_scc0 .LBB0_642
	v_cndmask_b32_e64 v24, 0, 1, s[8:9]
	v_cmp_ne_u32_e64 s[6:7], 1, v24
	s_andn2_b64 vcc, exec, s[8:9]
	s_cbranch_vccnz .LBB0_645
	s_lshl_b64 s[8:9], s[28:29], 14
	v_lshl_add_u64 v[28:29], v[148:149], 0, s[8:9]
	global_load_dwordx4 v[24:27], v[28:29], off offset:16
	s_nop 0
	global_load_dwordx4 v[28:31], v[28:29], off

.LBB0_870:
	v_add_u32_e32 v80, s60, v94
	ds_read_b128 v[8:11], v80
	ds_read_b128 v[16:19], v80 offset:1024
	ds_read_b128 v[98:101], v80 offset:2048
	ds_read_b128 v[102:105], v80 offset:3072
	s_and_b64 s[0:1], exec, s[0:1]
	s_cselect_b32 s1, s21, s78
	s_cselect_b32 s0, s31, s71
	v_lshl_add_u64 v[138:139], s[34:35], 0, v[86:87]
	s_add_i32 m0, s42, 0xc000
	ds_read_b128 v[106:109], v95
	ds_read_b128 v[110:113], v95 offset:1024
	ds_read_b128 v[114:117], v95 offset:2048
	ds_read_b128 v[118:121], v95 offset:3072
	ds_read_b128 v[122:125], v95 offset:4096
	ds_read_b128 v[126:129], v95 offset:5120
	ds_read_b128 v[130:133], v95 offset:6144
	ds_read_b128 v[134:137], v95 offset:7168
	global_load_lds_dwordx4 v[138:139], off
	s_add_i32 m0, s42, 0xe000
	v_lshl_add_u64 v[138:139], s[34:35], 0, v[88:89]
	global_load_lds_dwordx4 v[138:139], off
	s_waitcnt lgkmcnt(8)
	s_barrier
	s_waitcnt lgkmcnt(0)
	v_mfma_f32_16x16x32_bf16 v[68:71], v[8:11], v[106:109], v[68:71]
	v_mfma_f32_16x16x32_bf16 v[64:67], v[98:101], v[106:109], v[64:67]
	v_mfma_f32_16x16x32_bf16 v[60:63], v[8:11], v[114:117], v[60:63]
	v_mfma_f32_16x16x32_bf16 v[56:59], v[98:101], v[114:117], v[56:59]
	v_mfma_f32_16x16x32_bf16 v[52:55], v[8:11], v[122:125], v[52:55]
	v_mfma_f32_16x16x32_bf16 v[48:51], v[98:101], v[122:125], v[48:51]
	v_mfma_f32_16x16x32_bf16 v[44:47], v[8:11], v[130:133], v[44:47]
	v_mfma_f32_16x16x32_bf16 v[40:43], v[98:101], v[130:133], v[40:43]
	v_mfma_f32_16x16x32_bf16 v[68:71], v[16:19], v[110:113], v[68:71]
	v_mfma_f32_16x16x32_bf16 v[64:67], v[102:105], v[110:113], v[64:67]
	v_mfma_f32_16x16x32_bf16 v[60:63], v[16:19], v[118:121], v[60:63]
	v_mfma_f32_16x16x32_bf16 v[56:59], v[102:105], v[118:121], v[56:59]
	v_mfma_f32_16x16x32_bf16 v[52:55], v[16:19], v[126:129], v[52:55]
	v_mfma_f32_16x16x32_bf16 v[48:51], v[102:105], v[126:129], v[48:51]
	v_mfma_f32_16x16x32_bf16 v[44:47], v[16:19], v[134:137], v[44:47]
	v_mfma_f32_16x16x32_bf16 v[40:43], v[102:105], v[134:137], v[40:43]
	s_barrier
	s_add_i32 s80, s60, s41
	v_lshl_add_u64 v[138:139], s[0:1], 0, v[74:75]
	s_mov_b32 m0, s80
	v_lshl_add_u64 v[140:141], s[0:1], 0, v[78:79]
	global_load_lds_dwordx4 v[138:139], off
	s_add_i32 m0, s80, 0x2000
	s_nop 0
	global_load_lds_dwordx4 v[140:141], off
	s_barrier
	s_waitcnt lgkmcnt(0)
	s_mov_b32 m0, s42
	v_lshl_add_u64 v[142:143], s[36:37], 0, v[72:73]
	s_barrier
	ds_read_b128 v[106:109], v95 offset:16384
	ds_read_b128 v[110:113], v95 offset:17408
	ds_read_b128 v[114:117], v95 offset:18432
	ds_read_b128 v[118:121], v95 offset:19456
	ds_read_b128 v[122:125], v95 offset:20480
	ds_read_b128 v[126:129], v95 offset:21504
	ds_read_b128 v[130:133], v95 offset:22528
	ds_read_b128 v[134:137], v95 offset:23552
	global_load_lds_dwordx4 v[142:143], off
	s_mov_b32 m0, s43
	v_lshl_add_u64 v[144:145], s[36:37], 0, v[76:77]
	global_load_lds_dwordx4 v[144:145], off
	s_barrier
	s_waitcnt lgkmcnt(0)
	v_mfma_f32_16x16x32_bf16 v[36:39], v[8:11], v[106:109], v[36:39]
	v_mfma_f32_16x16x32_bf16 v[32:35], v[98:101], v[106:109], v[32:35]
	v_mfma_f32_16x16x32_bf16 v[28:31], v[8:11], v[114:117], v[28:31]
	v_mfma_f32_16x16x32_bf16 v[24:27], v[98:101], v[114:117], v[24:27]
	v_mfma_f32_16x16x32_bf16 v[20:23], v[8:11], v[122:125], v[20:23]
	v_mfma_f32_16x16x32_bf16 v[12:15], v[98:101], v[122:125], v[12:15]
	v_mfma_f32_16x16x32_bf16 v[4:7], v[8:11], v[130:133], v[4:7]
	v_mfma_f32_16x16x32_bf16 v[0:3], v[98:101], v[130:133], v[0:3]
	v_mfma_f32_16x16x32_bf16 v[36:39], v[16:19], v[110:113], v[36:39]
	v_mfma_f32_16x16x32_bf16 v[32:35], v[102:105], v[110:113], v[32:35]
	v_mfma_f32_16x16x32_bf16 v[28:31], v[16:19], v[118:121], v[28:31]
	v_mfma_f32_16x16x32_bf16 v[24:27], v[102:105], v[118:121], v[24:27]
	v_mfma_f32_16x16x32_bf16 v[20:23], v[16:19], v[126:129], v[20:23]
	v_mfma_f32_16x16x32_bf16 v[12:15], v[102:105], v[126:129], v[12:15]
	v_mfma_f32_16x16x32_bf16 v[4:7], v[16:19], v[134:137], v[4:7]
	v_mfma_f32_16x16x32_bf16 v[0:3], v[102:105], v[134:137], v[0:3]
	s_barrier
	s_add_u32 s80, s0, 0x80000
	s_addc_u32 s81, s1, 0
	s_mov_b32 m0, s44
	v_lshl_add_u64 v[8:9], s[80:81], 0, v[74:75]
	global_load_lds_dwordx4 v[8:9], off
	s_mov_b32 m0, s45
	v_lshl_add_u64 v[8:9], s[80:81], 0, v[78:79]
	global_load_lds_dwordx4 v[8:9], off
	s_waitcnt vmcnt(6)
	s_barrier
	s_add_i32 s80, 0, 0x18000
	v_add_u32_e32 v80, s80, v94
	s_barrier
	ds_read_b128 v[8:11], v80
	ds_read_b128 v[16:19], v80 offset:1024
	ds_read_b128 v[98:101], v80 offset:2048
	ds_read_b128 v[102:105], v80 offset:3072
	s_add_u32 s36, s36, 0x180000
	s_addc_u32 s37, s37, 0
	s_mov_b32 m0, s46
	v_lshl_add_u64 v[146:147], s[36:37], 0, v[72:73]
	ds_read_b128 v[106:109], v95 offset:32768
	ds_read_b128 v[110:113], v95 offset:33792
	ds_read_b128 v[114:117], v95 offset:34816
	ds_read_b128 v[118:121], v95 offset:35840
	ds_read_b128 v[122:125], v95 offset:36864
	ds_read_b128 v[126:129], v95 offset:37888
	ds_read_b128 v[130:133], v95 offset:38912
	ds_read_b128 v[134:137], v95 offset:39936
	global_load_lds_dwordx4 v[146:147], off
	s_mov_b32 m0, s47
	v_lshl_add_u64 v[146:147], s[36:37], 0, v[76:77]
	global_load_lds_dwordx4 v[146:147], off
	s_waitcnt lgkmcnt(8)
	s_barrier
	s_waitcnt lgkmcnt(0)
	v_mfma_f32_16x16x32_bf16 v[68:71], v[8:11], v[106:109], v[68:71]
	v_mfma_f32_16x16x32_bf16 v[64:67], v[98:101], v[106:109], v[64:67]
	v_mfma_f32_16x16x32_bf16 v[60:63], v[8:11], v[114:117], v[60:63]
	v_mfma_f32_16x16x32_bf16 v[56:59], v[98:101], v[114:117], v[56:59]
	v_mfma_f32_16x16x32_bf16 v[52:55], v[8:11], v[122:125], v[52:55]
	v_mfma_f32_16x16x32_bf16 v[48:51], v[98:101], v[122:125], v[48:51]
	v_mfma_f32_16x16x32_bf16 v[44:47], v[8:11], v[130:133], v[44:47]
	v_mfma_f32_16x16x32_bf16 v[40:43], v[98:101], v[130:133], v[40:43]
	v_mfma_f32_16x16x32_bf16 v[68:71], v[16:19], v[110:113], v[68:71]
	v_mfma_f32_16x16x32_bf16 v[64:67], v[102:105], v[110:113], v[64:67]
	v_mfma_f32_16x16x32_bf16 v[60:63], v[16:19], v[118:121], v[60:63]
	v_mfma_f32_16x16x32_bf16 v[56:59], v[102:105], v[118:121], v[56:59]
	v_mfma_f32_16x16x32_bf16 v[52:55], v[16:19], v[126:129], v[52:55]
	v_mfma_f32_16x16x32_bf16 v[48:51], v[102:105], v[126:129], v[48:51]
	v_mfma_f32_16x16x32_bf16 v[44:47], v[16:19], v[134:137], v[44:47]
	v_mfma_f32_16x16x32_bf16 v[40:43], v[102:105], v[134:137], v[40:43]
	s_barrier
	s_add_i32 s36, s80, s41
	s_mov_b32 m0, s36
	v_lshl_add_u64 v[106:107], v[138:139], 0, s[6:7]
	global_load_lds_dwordx4 v[106:107], off
	s_add_i32 m0, s36, 0x2000
	v_lshl_add_u64 v[106:107], v[140:141], 0, s[6:7]
	global_load_lds_dwordx4 v[106:107], off
	s_barrier
	s_waitcnt lgkmcnt(0)
	s_mov_b32 m0, s54
	v_lshl_add_u64 v[138:139], v[142:143], 0, s[8:9]
	s_barrier
	ds_read_b128 v[106:109], v95 offset:49152
	ds_read_b128 v[110:113], v95 offset:50176
	ds_read_b128 v[114:117], v95 offset:51200
	ds_read_b128 v[118:121], v95 offset:52224
	ds_read_b128 v[122:125], v95 offset:53248
	ds_read_b128 v[126:129], v95 offset:54272
	ds_read_b128 v[130:133], v95 offset:55296
	ds_read_b128 v[134:137], v95 offset:56320
	global_load_lds_dwordx4 v[138:139], off
	s_mov_b32 m0, s55
	v_lshl_add_u64 v[138:139], v[144:145], 0, s[8:9]
	global_load_lds_dwordx4 v[138:139], off
	s_barrier
	s_waitcnt lgkmcnt(0)
	v_mfma_f32_16x16x32_bf16 v[36:39], v[8:11], v[106:109], v[36:39]
	v_mfma_f32_16x16x32_bf16 v[32:35], v[98:101], v[106:109], v[32:35]
	v_mfma_f32_16x16x32_bf16 v[28:31], v[8:11], v[114:117], v[28:31]
	v_mfma_f32_16x16x32_bf16 v[24:27], v[98:101], v[114:117], v[24:27]
	v_mfma_f32_16x16x32_bf16 v[20:23], v[8:11], v[122:125], v[20:23]
	v_mfma_f32_16x16x32_bf16 v[12:15], v[98:101], v[122:125], v[12:15]
	v_mfma_f32_16x16x32_bf16 v[4:7], v[8:11], v[130:133], v[4:7]
	v_mfma_f32_16x16x32_bf16 v[0:3], v[98:101], v[130:133], v[0:3]
	v_mfma_f32_16x16x32_bf16 v[36:39], v[16:19], v[110:113], v[36:39]
	v_mfma_f32_16x16x32_bf16 v[32:35], v[102:105], v[110:113], v[32:35]
	v_mfma_f32_16x16x32_bf16 v[28:31], v[16:19], v[118:121], v[28:31]
	v_mfma_f32_16x16x32_bf16 v[24:27], v[102:105], v[118:121], v[24:27]
	v_mfma_f32_16x16x32_bf16 v[20:23], v[16:19], v[126:129], v[20:23]
	v_mfma_f32_16x16x32_bf16 v[12:15], v[102:105], v[126:129], v[12:15]
	v_mfma_f32_16x16x32_bf16 v[4:7], v[16:19], v[134:137], v[4:7]
	v_mfma_f32_16x16x32_bf16 v[0:3], v[102:105], v[134:137], v[0:3]
	s_barrier
	s_add_u32 s0, s0, 0x80080
	s_addc_u32 s1, s1, 0
	s_mov_b32 m0, s56
	v_lshl_add_u64 v[8:9], s[0:1], 0, v[74:75]
	global_load_lds_dwordx4 v[8:9], off
	s_mov_b32 m0, s57
	v_lshl_add_u64 v[8:9], s[0:1], 0, v[78:79]
	global_load_lds_dwordx4 v[8:9], off
	s_waitcnt vmcnt(6)
	s_barrier
	s_add_i32 s79, s79, 2
	s_add_u32 s71, s71, 0x100
	s_addc_u32 s78, s78, 0
	s_add_u32 s34, s34, 0x1800
	s_addc_u32 s35, s35, 0
	s_cmp_gt_u32 s79, 29
	s_barrier
	s_cbranch_scc1 .LBB0_875

.LBB0_1551:
	ds_read_b128 v[128:131], v190
	ds_read_b128 v[132:135], v190 offset:1024
	ds_read_b128 v[136:139], v190 offset:2048
	ds_read_b128 v[140:143], v190 offset:3072
	s_add_u32 s22, s20, 0xfffc0080
	s_addc_u32 s23, s21, -1
	s_cmp_eq_u32 s51, 12
	s_cselect_b32 s29, s13, s23
	s_cselect_b32 s28, s19, s22
	s_cselect_b32 s23, s11, s50
	s_cselect_b32 s22, s48, s49
	v_lshl_add_u64 v[184:185], s[20:21], 0, v[160:161]
	s_add_i32 m0, s36, 0xc000
	ds_read_b128 v[144:147], v191
	ds_read_b128 v[148:151], v191 offset:1024
	ds_read_b128 v[168:171], v191 offset:2048
	ds_read_b128 v[172:175], v191 offset:3072
	ds_read_b128 v[176:179], v191 offset:4096
	ds_read_b128 v[180:183], v191 offset:5120
	ds_read_b128 v[194:197], v191 offset:6144
	ds_read_b128 v[198:201], v191 offset:7168
	global_load_lds_dwordx4 v[184:185], off
	s_add_i32 m0, s36, 0xe000
	v_lshl_add_u64 v[184:185], s[20:21], 0, v[162:163]
	global_load_lds_dwordx4 v[184:185], off
	s_waitcnt lgkmcnt(8)
	s_barrier
	s_waitcnt lgkmcnt(0)
	v_mfma_f32_16x16x32_bf16 v[124:127], v[128:131], v[144:147], v[124:127]
	v_mfma_f32_16x16x32_bf16 v[120:123], v[136:139], v[144:147], v[120:123]
	v_mfma_f32_16x16x32_bf16 v[108:111], v[128:131], v[168:171], v[108:111]
	v_mfma_f32_16x16x32_bf16 v[104:107], v[136:139], v[168:171], v[104:107]
	v_mfma_f32_16x16x32_bf16 v[92:95], v[128:131], v[176:179], v[92:95]
	v_mfma_f32_16x16x32_bf16 v[88:91], v[136:139], v[176:179], v[88:91]
	v_mfma_f32_16x16x32_bf16 v[76:79], v[128:131], v[194:197], v[76:79]
	v_mfma_f32_16x16x32_bf16 v[72:75], v[136:139], v[194:197], v[72:75]
	v_mfma_f32_16x16x32_bf16 v[124:127], v[132:135], v[148:151], v[124:127]
	v_mfma_f32_16x16x32_bf16 v[120:123], v[140:143], v[148:151], v[120:123]
	v_mfma_f32_16x16x32_bf16 v[108:111], v[132:135], v[172:175], v[108:111]
	v_mfma_f32_16x16x32_bf16 v[104:107], v[140:143], v[172:175], v[104:107]
	v_mfma_f32_16x16x32_bf16 v[92:95], v[132:135], v[180:183], v[92:95]
	v_mfma_f32_16x16x32_bf16 v[88:91], v[140:143], v[180:183], v[88:91]
	v_mfma_f32_16x16x32_bf16 v[76:79], v[132:135], v[198:201], v[76:79]
	v_mfma_f32_16x16x32_bf16 v[72:75], v[140:143], v[198:201], v[72:75]
	s_barrier
	s_add_i32 s52, s45, s35
	v_lshl_add_u64 v[184:185], s[22:23], 0, v[154:155]
	s_mov_b32 m0, s52
	ds_read_b128 v[202:205], v192
	ds_read_b128 v[206:209], v192 offset:1024
	ds_read_b128 v[210:213], v192 offset:2048
	ds_read_b128 v[214:217], v192 offset:3072
	global_load_lds_dwordx4 v[184:185], off
	s_add_i32 m0, s52, 0x2000
	v_lshl_add_u64 v[218:219], s[22:23], 0, v[158:159]
	global_load_lds_dwordx4 v[218:219], off
	s_barrier
	s_waitcnt lgkmcnt(0)
	v_mfma_f32_16x16x32_bf16 v[116:119], v[202:205], v[144:147], v[116:119]
	v_mfma_f32_16x16x32_bf16 v[112:115], v[210:213], v[144:147], v[112:115]
	v_mfma_f32_16x16x32_bf16 v[100:103], v[202:205], v[168:171], v[100:103]
	v_mfma_f32_16x16x32_bf16 v[96:99], v[210:213], v[168:171], v[96:99]
	v_mfma_f32_16x16x32_bf16 v[84:87], v[202:205], v[176:179], v[84:87]
	v_mfma_f32_16x16x32_bf16 v[80:83], v[210:213], v[176:179], v[80:83]
	v_mfma_f32_16x16x32_bf16 v[68:71], v[202:205], v[194:197], v[68:71]
	v_mfma_f32_16x16x32_bf16 v[64:67], v[210:213], v[194:197], v[64:67]
	v_mfma_f32_16x16x32_bf16 v[116:119], v[206:209], v[148:151], v[116:119]
	v_mfma_f32_16x16x32_bf16 v[112:115], v[214:217], v[148:151], v[112:115]
	v_mfma_f32_16x16x32_bf16 v[100:103], v[206:209], v[172:175], v[100:103]
	v_mfma_f32_16x16x32_bf16 v[96:99], v[214:217], v[172:175], v[96:99]
	v_mfma_f32_16x16x32_bf16 v[84:87], v[206:209], v[180:183], v[84:87]
	v_mfma_f32_16x16x32_bf16 v[80:83], v[214:217], v[180:183], v[80:83]
	v_mfma_f32_16x16x32_bf16 v[68:71], v[206:209], v[198:201], v[68:71]
	v_mfma_f32_16x16x32_bf16 v[64:67], v[214:217], v[198:201], v[64:67]
	s_mov_b32 m0, s36
	v_lshl_add_u64 v[220:221], s[28:29], 0, v[152:153]
	s_barrier
	ds_read_b128 v[144:147], v191 offset:16384
	ds_read_b128 v[148:151], v191 offset:17408
	ds_read_b128 v[168:171], v191 offset:18432
	ds_read_b128 v[172:175], v191 offset:19456
	ds_read_b128 v[176:179], v191 offset:20480
	ds_read_b128 v[180:183], v191 offset:21504
	ds_read_b128 v[194:197], v191 offset:22528
	ds_read_b128 v[198:201], v191 offset:23552
	global_load_lds_dwordx4 v[220:221], off
	s_mov_b32 m0, s37
	v_lshl_add_u64 v[222:223], s[28:29], 0, v[156:157]
	global_load_lds_dwordx4 v[222:223], off
	s_barrier
	s_waitcnt lgkmcnt(0)
	v_mfma_f32_16x16x32_bf16 v[60:63], v[128:131], v[144:147], v[60:63]
	v_mfma_f32_16x16x32_bf16 v[56:59], v[136:139], v[144:147], v[56:59]
	v_mfma_f32_16x16x32_bf16 v[44:47], v[128:131], v[168:171], v[44:47]
	v_mfma_f32_16x16x32_bf16 v[40:43], v[136:139], v[168:171], v[40:43]
	v_mfma_f32_16x16x32_bf16 v[28:31], v[128:131], v[176:179], v[28:31]
	v_mfma_f32_16x16x32_bf16 v[24:27], v[136:139], v[176:179], v[24:27]
	v_mfma_f32_16x16x32_bf16 v[12:15], v[128:131], v[194:197], v[12:15]
	v_mfma_f32_16x16x32_bf16 v[8:11], v[136:139], v[194:197], v[8:11]
	v_mfma_f32_16x16x32_bf16 v[60:63], v[132:135], v[148:151], v[60:63]
	v_mfma_f32_16x16x32_bf16 v[56:59], v[140:143], v[148:151], v[56:59]
	v_mfma_f32_16x16x32_bf16 v[44:47], v[132:135], v[172:175], v[44:47]
	v_mfma_f32_16x16x32_bf16 v[40:43], v[140:143], v[172:175], v[40:43]
	v_mfma_f32_16x16x32_bf16 v[28:31], v[132:135], v[180:183], v[28:31]
	v_mfma_f32_16x16x32_bf16 v[24:27], v[140:143], v[180:183], v[24:27]
	v_mfma_f32_16x16x32_bf16 v[12:15], v[132:135], v[198:201], v[12:15]
	v_mfma_f32_16x16x32_bf16 v[8:11], v[140:143], v[198:201], v[8:11]
	s_barrier
	s_add_u32 s52, s22, 0x40000
	s_addc_u32 s53, s23, 0
	s_add_i32 s54, s46, s35
	s_mov_b32 m0, s54
	v_lshl_add_u64 v[128:129], s[52:53], 0, v[154:155]
	global_load_lds_dwordx4 v[128:129], off
	s_add_i32 m0, s54, 0x2000
	v_lshl_add_u64 v[128:129], s[52:53], 0, v[158:159]
	global_load_lds_dwordx4 v[128:129], off
	s_waitcnt vmcnt(6)
	s_barrier
	v_mfma_f32_16x16x32_bf16 v[52:55], v[202:205], v[144:147], v[52:55]
	v_mfma_f32_16x16x32_bf16 v[48:51], v[210:213], v[144:147], v[48:51]
	v_mfma_f32_16x16x32_bf16 v[36:39], v[202:205], v[168:171], v[36:39]
	v_mfma_f32_16x16x32_bf16 v[32:35], v[210:213], v[168:171], v[32:35]
	v_mfma_f32_16x16x32_bf16 v[20:23], v[202:205], v[176:179], v[20:23]
	v_mfma_f32_16x16x32_bf16 v[16:19], v[210:213], v[176:179], v[16:19]
	v_mfma_f32_16x16x32_bf16 v[4:7], v[202:205], v[194:197], v[4:7]
	v_mfma_f32_16x16x32_bf16 v[0:3], v[210:213], v[194:197], v[0:3]
	v_mfma_f32_16x16x32_bf16 v[52:55], v[206:209], v[148:151], v[52:55]
	v_mfma_f32_16x16x32_bf16 v[48:51], v[214:217], v[148:151], v[48:51]
	v_mfma_f32_16x16x32_bf16 v[36:39], v[206:209], v[172:175], v[36:39]
	v_mfma_f32_16x16x32_bf16 v[32:35], v[214:217], v[172:175], v[32:35]
	v_mfma_f32_16x16x32_bf16 v[20:23], v[206:209], v[180:183], v[20:23]
	v_mfma_f32_16x16x32_bf16 v[16:19], v[214:217], v[180:183], v[16:19]
	v_mfma_f32_16x16x32_bf16 v[4:7], v[206:209], v[198:201], v[4:7]
	v_mfma_f32_16x16x32_bf16 v[0:3], v[214:217], v[198:201], v[0:3]
	s_add_i32 s52, 0, 0x18000
	v_add_u32_e32 v140, s52, v187
	s_barrier
	ds_read_b128 v[128:131], v140
	ds_read_b128 v[132:135], v140 offset:1024
	ds_read_b128 v[136:139], v140 offset:2048
	ds_read_b128 v[140:143], v140 offset:3072
	s_add_u32 s28, s28, 0x40000
	s_addc_u32 s29, s29, 0
	s_mov_b32 m0, s38
	v_lshl_add_u64 v[202:203], s[28:29], 0, v[152:153]
	ds_read_b128 v[144:147], v191 offset:32768
	ds_read_b128 v[148:151], v191 offset:33792
	ds_read_b128 v[168:171], v191 offset:34816
	ds_read_b128 v[172:175], v191 offset:35840
	ds_read_b128 v[176:179], v191 offset:36864
	ds_read_b128 v[180:183], v191 offset:37888
	ds_read_b128 v[194:197], v191 offset:38912
	ds_read_b128 v[198:201], v191 offset:39936
	global_load_lds_dwordx4 v[202:203], off
	s_mov_b32 m0, s39
	v_lshl_add_u64 v[202:203], s[28:29], 0, v[156:157]
	global_load_lds_dwordx4 v[202:203], off
	s_waitcnt lgkmcnt(8)
	s_barrier
	s_waitcnt lgkmcnt(0)
	v_mfma_f32_16x16x32_bf16 v[124:127], v[128:131], v[144:147], v[124:127]
	v_mfma_f32_16x16x32_bf16 v[120:123], v[136:139], v[144:147], v[120:123]
	v_mfma_f32_16x16x32_bf16 v[108:111], v[128:131], v[168:171], v[108:111]
	v_mfma_f32_16x16x32_bf16 v[104:107], v[136:139], v[168:171], v[104:107]
	v_mfma_f32_16x16x32_bf16 v[92:95], v[128:131], v[176:179], v[92:95]
	v_mfma_f32_16x16x32_bf16 v[88:91], v[136:139], v[176:179], v[88:91]
	v_mfma_f32_16x16x32_bf16 v[76:79], v[128:131], v[194:197], v[76:79]
	v_mfma_f32_16x16x32_bf16 v[72:75], v[136:139], v[194:197], v[72:75]
	v_mfma_f32_16x16x32_bf16 v[124:127], v[132:135], v[148:151], v[124:127]
	v_mfma_f32_16x16x32_bf16 v[120:123], v[140:143], v[148:151], v[120:123]
	v_mfma_f32_16x16x32_bf16 v[108:111], v[132:135], v[172:175], v[108:111]
	v_mfma_f32_16x16x32_bf16 v[104:107], v[140:143], v[172:175], v[104:107]
	v_mfma_f32_16x16x32_bf16 v[92:95], v[132:135], v[180:183], v[92:95]
	v_mfma_f32_16x16x32_bf16 v[88:91], v[140:143], v[180:183], v[88:91]
	v_mfma_f32_16x16x32_bf16 v[76:79], v[132:135], v[198:201], v[76:79]
	v_mfma_f32_16x16x32_bf16 v[72:75], v[140:143], v[198:201], v[72:75]
	s_barrier
	s_add_i32 s28, 0, 0x1c000
	s_add_i32 s29, s52, s35
	v_add_u32_e32 v214, s28, v187
	v_lshl_add_u64 v[184:185], v[184:185], 0, s[8:9]
	s_mov_b32 m0, s29
	ds_read_b128 v[202:205], v214
	ds_read_b128 v[206:209], v214 offset:1024
	ds_read_b128 v[210:213], v214 offset:2048
	ds_read_b128 v[214:217], v214 offset:3072
	global_load_lds_dwordx4 v[184:185], off
	s_add_i32 m0, s29, 0x2000
	v_lshl_add_u64 v[184:185], v[218:219], 0, s[8:9]
	global_load_lds_dwordx4 v[184:185], off
	s_barrier
	s_waitcnt lgkmcnt(0)
	v_mfma_f32_16x16x32_bf16 v[116:119], v[202:205], v[144:147], v[116:119]
	v_mfma_f32_16x16x32_bf16 v[112:115], v[210:213], v[144:147], v[112:115]
	v_mfma_f32_16x16x32_bf16 v[100:103], v[202:205], v[168:171], v[100:103]
	v_mfma_f32_16x16x32_bf16 v[96:99], v[210:213], v[168:171], v[96:99]
	v_mfma_f32_16x16x32_bf16 v[84:87], v[202:205], v[176:179], v[84:87]
	v_mfma_f32_16x16x32_bf16 v[80:83], v[210:213], v[176:179], v[80:83]
	v_mfma_f32_16x16x32_bf16 v[68:71], v[202:205], v[194:197], v[68:71]
	v_mfma_f32_16x16x32_bf16 v[64:67], v[210:213], v[194:197], v[64:67]
	v_mfma_f32_16x16x32_bf16 v[116:119], v[206:209], v[148:151], v[116:119]
	v_mfma_f32_16x16x32_bf16 v[112:115], v[214:217], v[148:151], v[112:115]
	v_mfma_f32_16x16x32_bf16 v[100:103], v[206:209], v[172:175], v[100:103]
	v_mfma_f32_16x16x32_bf16 v[96:99], v[214:217], v[172:175], v[96:99]
	v_mfma_f32_16x16x32_bf16 v[84:87], v[206:209], v[180:183], v[84:87]
	v_mfma_f32_16x16x32_bf16 v[80:83], v[214:217], v[180:183], v[80:83]
	v_mfma_f32_16x16x32_bf16 v[68:71], v[206:209], v[198:201], v[68:71]
	v_mfma_f32_16x16x32_bf16 v[64:67], v[214:217], v[198:201], v[64:67]
	s_mov_b32 m0, s41
	v_lshl_add_u64 v[184:185], v[220:221], 0, s[8:9]
	s_barrier
	ds_read_b128 v[144:147], v191 offset:49152
	ds_read_b128 v[148:151], v191 offset:50176
	ds_read_b128 v[168:171], v191 offset:51200
	ds_read_b128 v[172:175], v191 offset:52224
	ds_read_b128 v[176:179], v191 offset:53248
	ds_read_b128 v[180:183], v191 offset:54272
	ds_read_b128 v[194:197], v191 offset:55296
	ds_read_b128 v[198:201], v191 offset:56320
	global_load_lds_dwordx4 v[184:185], off
	s_mov_b32 m0, s42
	v_lshl_add_u64 v[184:185], v[222:223], 0, s[8:9]
	global_load_lds_dwordx4 v[184:185], off
	s_barrier
	s_waitcnt lgkmcnt(0)
	v_mfma_f32_16x16x32_bf16 v[60:63], v[128:131], v[144:147], v[60:63]
	v_mfma_f32_16x16x32_bf16 v[56:59], v[136:139], v[144:147], v[56:59]
	v_mfma_f32_16x16x32_bf16 v[44:47], v[128:131], v[168:171], v[44:47]
	v_mfma_f32_16x16x32_bf16 v[40:43], v[136:139], v[168:171], v[40:43]
	v_mfma_f32_16x16x32_bf16 v[28:31], v[128:131], v[176:179], v[28:31]
	v_mfma_f32_16x16x32_bf16 v[24:27], v[136:139], v[176:179], v[24:27]
	v_mfma_f32_16x16x32_bf16 v[12:15], v[128:131], v[194:197], v[12:15]
	v_mfma_f32_16x16x32_bf16 v[8:11], v[136:139], v[194:197], v[8:11]
	v_mfma_f32_16x16x32_bf16 v[60:63], v[132:135], v[148:151], v[60:63]
	v_mfma_f32_16x16x32_bf16 v[56:59], v[140:143], v[148:151], v[56:59]
	v_mfma_f32_16x16x32_bf16 v[44:47], v[132:135], v[172:175], v[44:47]
	v_mfma_f32_16x16x32_bf16 v[40:43], v[140:143], v[172:175], v[40:43]
	v_mfma_f32_16x16x32_bf16 v[28:31], v[132:135], v[180:183], v[28:31]
	v_mfma_f32_16x16x32_bf16 v[24:27], v[140:143], v[180:183], v[24:27]
	v_mfma_f32_16x16x32_bf16 v[12:15], v[132:135], v[198:201], v[12:15]
	v_mfma_f32_16x16x32_bf16 v[8:11], v[140:143], v[198:201], v[8:11]
	s_barrier
	s_add_u32 s22, s22, 0x40080
	s_addc_u32 s23, s23, 0
	s_add_i32 s28, s28, s35
	s_mov_b32 m0, s28
	v_lshl_add_u64 v[128:129], s[22:23], 0, v[154:155]
	global_load_lds_dwordx4 v[128:129], off
	s_add_i32 m0, s28, 0x2000
	v_lshl_add_u64 v[128:129], s[22:23], 0, v[158:159]
	global_load_lds_dwordx4 v[128:129], off
	s_waitcnt vmcnt(6)
	s_barrier
	v_mfma_f32_16x16x32_bf16 v[52:55], v[202:205], v[144:147], v[52:55]
	v_mfma_f32_16x16x32_bf16 v[48:51], v[210:213], v[144:147], v[48:51]
	v_mfma_f32_16x16x32_bf16 v[36:39], v[202:205], v[168:171], v[36:39]
	v_mfma_f32_16x16x32_bf16 v[32:35], v[210:213], v[168:171], v[32:35]
	v_mfma_f32_16x16x32_bf16 v[20:23], v[202:205], v[176:179], v[20:23]
	v_mfma_f32_16x16x32_bf16 v[16:19], v[210:213], v[176:179], v[16:19]
	v_mfma_f32_16x16x32_bf16 v[4:7], v[202:205], v[194:197], v[4:7]
	v_mfma_f32_16x16x32_bf16 v[0:3], v[210:213], v[194:197], v[0:3]
	v_mfma_f32_16x16x32_bf16 v[52:55], v[206:209], v[148:151], v[52:55]
	v_mfma_f32_16x16x32_bf16 v[48:51], v[214:217], v[148:151], v[48:51]
	v_mfma_f32_16x16x32_bf16 v[36:39], v[206:209], v[172:175], v[36:39]
	v_mfma_f32_16x16x32_bf16 v[32:35], v[214:217], v[172:175], v[32:35]
	v_mfma_f32_16x16x32_bf16 v[20:23], v[206:209], v[180:183], v[20:23]
	v_mfma_f32_16x16x32_bf16 v[16:19], v[214:217], v[180:183], v[16:19]
	v_mfma_f32_16x16x32_bf16 v[4:7], v[206:209], v[198:201], v[4:7]
	v_mfma_f32_16x16x32_bf16 v[0:3], v[214:217], v[198:201], v[0:3]
	s_add_i32 s51, s51, 2
	s_add_u32 s20, s20, 0x100
	s_addc_u32 s21, s21, 0
	s_add_u32 s49, s49, 0x100
	s_addc_u32 s50, s50, 0
	s_cmp_gt_u32 s51, 13
	s_barrier
	s_cbranch_scc0 .LBB0_1551
	v_lshl_or_b32 v168, s6, 8, v189
	v_lshl_add_u32 v170, s18, 8, v186
	v_ashrrev_i32_e32 v169, 31, v168
	v_lshlrev_b64 v[202:203], 1, v[168:169]
	v_ashrrev_i32_e32 v171, 31, v170
	v_or_b32_e32 v182, 16, v170
	v_lshl_add_u64 v[172:173], s[64:65], 0, v[202:203]
	v_lshlrev_b64 v[204:205], 11, v[170:171]
	v_ashrrev_i32_e32 v183, 31, v182
	v_or_b32_e32 v178, 32, v170
	v_lshl_add_u64 v[128:129], v[172:173], 0, v[204:205]
	v_lshlrev_b64 v[184:185], 11, v[182:183]
	v_ashrrev_i32_e32 v179, 31, v178
	v_or_b32_e32 v174, 48, v170
	global_load_dwordx4 v[194:197], v[128:129], off
	global_load_dwordx4 v[198:201], v[128:129], off offset:256
	v_lshl_add_u64 v[128:129], v[172:173], 0, v[184:185]
	v_lshlrev_b64 v[180:181], 11, v[178:179]
	v_ashrrev_i32_e32 v175, 31, v174
	global_load_dwordx4 v[148:151], v[128:129], off
	global_load_dwordx4 v[144:147], v[128:129], off offset:256
	v_lshl_add_u64 v[128:129], v[172:173], 0, v[180:181]
	v_lshlrev_b64 v[176:177], 11, v[174:175]
	global_load_dwordx4 v[140:143], v[128:129], off
	global_load_dwordx4 v[136:139], v[128:129], off offset:256
	v_lshl_add_u64 v[128:129], v[172:173], 0, v[176:177]
	global_load_dwordx4 v[132:135], v[128:129], off
	s_nop 0
	global_load_dwordx4 v[128:131], v[128:129], off offset:256
	s_lshl_b32 s18, s6, 2
	s_ashr_i32 s19, s18, 31
	v_add_u32_e32 v252, 0x80, v170
	v_ashrrev_i32_e32 v253, 31, v252
	v_lshlrev_b64 v[252:253], 11, v[252:253]
	v_lshl_add_u64 v[252:253], v[172:173], 0, v[252:253]
	global_load_dwordx4 v[236:239], v[252:253], off
	global_load_dwordx4 v[240:243], v[252:253], off offset:256
	v_add_u32_e32 v252, 0x90, v170
	v_ashrrev_i32_e32 v253, 31, v252
	v_lshlrev_b64 v[252:253], 11, v[252:253]
	v_lshl_add_u64 v[252:253], v[172:173], 0, v[252:253]
	global_load_dwordx4 v[244:247], v[252:253], off
	global_load_dwordx4 v[248:251], v[252:253], off offset:256
	v_add_u32_e32 v252, 0xa0, v170
	v_ashrrev_i32_e32 v253, 31, v252
	v_lshlrev_b64 v[252:253], 11, v[252:253]
	v_lshl_add_u64 v[252:253], v[172:173], 0, v[252:253]
	global_load_dwordx4 v[210:213], v[252:253], off
	global_load_dwordx4 v[214:217], v[252:253], off offset:256
	s_waitcnt vmcnt(6)
	v_lshlrev_b32_e32 v206, 16, v194
	v_and_b32_e32 v207, 0xffff0000, v194
	v_lshlrev_b32_e32 v194, 16, v195
	v_and_b32_e32 v195, 0xffff0000, v195
	v_lshlrev_b32_e32 v208, 16, v196
	v_and_b32_e32 v209, 0xffff0000, v196
	v_lshlrev_b32_e32 v196, 16, v197
	v_and_b32_e32 v197, 0xffff0000, v197
	v_pk_add_f32 v[126:127], v[126:127], v[194:195]
	v_pk_add_f32 v[124:125], v[124:125], v[206:207]
	v_pk_add_f32 v[194:195], v[122:123], v[196:197]
	v_pk_add_f32 v[122:123], v[120:121], v[208:209]
	v_mul_f32_e32 v120, v125, v125
	v_mul_f32_e32 v121, v127, v127
	v_fmac_f32_e32 v120, v124, v124
	v_fmac_f32_e32 v121, v126, v126
	v_add_f32_e32 v120, v120, v121
	v_mul_f32_e32 v121, v123, v123
	v_mul_f32_e32 v196, v195, v195
	v_fmac_f32_e32 v121, v122, v122
	v_fmac_f32_e32 v196, v194, v194
	v_add_f32_e32 v121, v121, v196
	v_add_f32_e32 v206, v120, v121
	v_cvt_pk_bf16_f32 v120, v124, v125
	v_cvt_pk_bf16_f32 v121, v126, v127
	v_lshlrev_b32_e32 v124, 16, v198
	v_and_b32_e32 v125, 0xffff0000, v198
	v_lshlrev_b32_e32 v126, 16, v199
	v_and_b32_e32 v127, 0xffff0000, v199
	v_cvt_pk_bf16_f32 v122, v122, v123
	v_cvt_pk_bf16_f32 v123, v194, v195
	v_lshlrev_b32_e32 v194, 16, v200
	v_and_b32_e32 v195, 0xffff0000, v200
	v_pk_add_f32 v[118:119], v[118:119], v[126:127]
	v_pk_add_f32 v[116:117], v[116:117], v[124:125]
	v_lshlrev_b32_e32 v196, 16, v201
	v_and_b32_e32 v197, 0xffff0000, v201
	v_pk_add_f32 v[126:127], v[112:113], v[194:195]
	v_mul_f32_e32 v112, v117, v117
	v_mul_f32_e32 v113, v119, v119
	v_pk_add_f32 v[124:125], v[114:115], v[196:197]
	v_fmac_f32_e32 v112, v116, v116
	v_fmac_f32_e32 v113, v118, v118
	v_add_f32_e32 v112, v112, v113
	v_mul_f32_e32 v113, v127, v127
	v_mul_f32_e32 v114, v125, v125
	v_fmac_f32_e32 v113, v126, v126
	v_fmac_f32_e32 v114, v124, v124
	v_add_f32_e32 v113, v113, v114
	v_add_f32_e32 v112, v112, v113
	v_and_b32_e32 v114, 64, v193
	v_add_f32_e32 v113, v206, v112
	v_xor_b32_e32 v112, 16, v193
	v_add_u32_e32 v196, 64, v114
	v_cmp_lt_i32_e32 vcc, v112, v196
	v_lshl_add_u64 v[114:115], s[64:65], 0, v[204:205]
	v_lshl_add_u64 v[194:195], v[114:115], 0, v[202:203]
	v_cndmask_b32_e32 v112, v193, v112, vcc
	v_lshlrev_b32_e32 v112, 2, v112
	ds_bpermute_b32 v197, v112, v113
	global_store_dwordx4 v[194:195], v[120:123], off
	v_cvt_pk_bf16_f32 v116, v116, v117
	v_cvt_pk_bf16_f32 v117, v118, v119
	v_cvt_pk_bf16_f32 v118, v126, v127
	s_waitcnt lgkmcnt(0)
	v_add_f32_e32 v114, v113, v197
	v_xor_b32_e32 v113, 32, v193
	v_cmp_lt_i32_e32 vcc, v113, v196
	v_cvt_pk_bf16_f32 v119, v124, v125
	global_store_dwordx4 v[194:195], v[116:119], off offset:256
	s_nop 0
	v_cndmask_b32_e32 v113, v193, v113, vcc
	v_lshlrev_b32_e32 v113, 2, v113
	ds_bpermute_b32 v115, v113, v114
	s_and_saveexec_b64 s[20:21], s[2:3]
	s_cbranch_execz .LBB0_1554
	s_waitcnt lgkmcnt(0)
	v_add_f32_e32 v116, v114, v115
	v_lshlrev_b64 v[114:115], 6, v[170:171]
	v_lshl_add_u64 v[114:115], s[74:75], 0, v[114:115]
	v_lshl_add_u64 v[114:115], s[18:19], 2, v[114:115]
	s_lshl_b32 s6, s40, 2
	v_lshl_add_u64 v[114:115], v[114:115], 0, s[6:7]
	global_store_dword v[114:115], v116, off

.LBB0_1639:
	ds_read_b128 v[16:19], v212
	ds_read_b128 v[20:23], v212 offset:1024
	ds_read_b128 v[24:27], v212 offset:2048
	ds_read_b128 v[68:71], v212 offset:3072
	s_add_u32 s28, s8, 0x100
	s_addc_u32 s29, s9, 0
	s_cmp_eq_u32 s67, 12
	s_cselect_b32 s35, s59, s29
	s_cselect_b32 s34, s60, s28
	s_cselect_b32 s31, s11, s63
	s_cselect_b32 s30, s61, s62
	v_lshl_add_u64 v[176:177], s[8:9], 0, v[204:205]
	s_add_i32 m0, s42, 0xc000
	ds_read_b128 v[96:99], v213
	ds_read_b128 v[148:151], v213 offset:1024
	ds_read_b128 v[152:155], v213 offset:2048
	ds_read_b128 v[156:159], v213 offset:3072
	ds_read_b128 v[160:163], v213 offset:4096
	ds_read_b128 v[164:167], v213 offset:5120
	ds_read_b128 v[168:171], v213 offset:6144
	ds_read_b128 v[172:175], v213 offset:7168
	global_load_lds_dwordx4 v[176:177], off
	s_add_i32 m0, s42, 0xe000
	v_lshl_add_u64 v[176:177], s[8:9], 0, v[206:207]
	global_load_lds_dwordx4 v[176:177], off
	s_waitcnt lgkmcnt(8)
	s_barrier
	s_waitcnt lgkmcnt(0)
	v_mfma_f32_16x16x32_bf16 v[112:115], v[16:19], v[96:99], v[112:115]
	v_mfma_f32_16x16x32_bf16 v[40:43], v[24:27], v[96:99], v[40:43]
	v_mfma_f32_16x16x32_bf16 v[108:111], v[16:19], v[152:155], v[108:111]
	v_mfma_f32_16x16x32_bf16 v[36:39], v[24:27], v[152:155], v[36:39]
	v_mfma_f32_16x16x32_bf16 v[144:147], v[16:19], v[160:163], v[144:147]
	v_mfma_f32_16x16x32_bf16 v[140:143], v[24:27], v[160:163], v[140:143]
	v_mfma_f32_16x16x32_bf16 v[136:139], v[16:19], v[168:171], v[136:139]
	v_mfma_f32_16x16x32_bf16 v[132:135], v[24:27], v[168:171], v[132:135]
	v_mfma_f32_16x16x32_bf16 v[112:115], v[20:23], v[148:151], v[112:115]
	v_mfma_f32_16x16x32_bf16 v[40:43], v[68:71], v[148:151], v[40:43]
	v_mfma_f32_16x16x32_bf16 v[108:111], v[20:23], v[156:159], v[108:111]
	v_mfma_f32_16x16x32_bf16 v[36:39], v[68:71], v[156:159], v[36:39]
	v_mfma_f32_16x16x32_bf16 v[144:147], v[20:23], v[164:167], v[144:147]
	v_mfma_f32_16x16x32_bf16 v[140:143], v[68:71], v[164:167], v[140:143]
	v_mfma_f32_16x16x32_bf16 v[136:139], v[20:23], v[172:175], v[136:139]
	v_mfma_f32_16x16x32_bf16 v[132:135], v[68:71], v[172:175], v[132:135]
	s_barrier
	s_add_i32 s8, s52, s41
	v_lshl_add_u64 v[222:223], s[30:31], 0, v[192:193]
	s_mov_b32 m0, s8
	ds_read_b128 v[176:179], v214
	ds_read_b128 v[180:183], v214 offset:1024
	ds_read_b128 v[184:187], v214 offset:2048
	ds_read_b128 v[218:221], v214 offset:3072
	global_load_lds_dwordx4 v[222:223], off
	s_add_i32 m0, s8, 0x2000
	v_lshl_add_u64 v[224:225], s[30:31], 0, v[198:199]
	global_load_lds_dwordx4 v[224:225], off
	s_barrier
	s_waitcnt lgkmcnt(0)
	v_mfma_f32_16x16x32_bf16 v[104:107], v[176:179], v[96:99], v[104:107]
	v_mfma_f32_16x16x32_bf16 v[32:35], v[184:187], v[96:99], v[32:35]
	v_mfma_f32_16x16x32_bf16 v[28:31], v[184:187], v[152:155], v[28:31]
	v_mfma_f32_16x16x32_bf16 v[80:83], v[176:179], v[160:163], v[80:83]
	v_mfma_f32_16x16x32_bf16 v[92:95], v[184:187], v[160:163], v[92:95]
	v_mfma_f32_16x16x32_bf16 v[84:87], v[176:179], v[168:171], v[84:87]
	v_mfma_f32_16x16x32_bf16 v[88:91], v[184:187], v[168:171], v[88:91]
	v_mfma_f32_16x16x32_bf16 v[104:107], v[180:183], v[148:151], v[104:107]
	v_mfma_f32_16x16x32_bf16 v[32:35], v[218:221], v[148:151], v[32:35]
	v_mfma_f32_16x16x32_bf16 v[96:99], v[176:179], v[152:155], v[100:103]
	v_mfma_f32_16x16x32_bf16 v[28:31], v[218:221], v[156:159], v[28:31]
	v_mfma_f32_16x16x32_bf16 v[80:83], v[180:183], v[164:167], v[80:83]
	v_mfma_f32_16x16x32_bf16 v[92:95], v[218:221], v[164:167], v[92:95]
	v_mfma_f32_16x16x32_bf16 v[84:87], v[180:183], v[172:175], v[84:87]
	v_mfma_f32_16x16x32_bf16 v[88:91], v[218:221], v[172:175], v[88:91]
	v_mfma_f32_16x16x32_bf16 v[96:99], v[180:183], v[156:159], v[96:99]
	s_mov_b32 m0, s42
	v_lshl_add_u64 v[226:227], s[34:35], 0, v[194:195]
	s_barrier
	ds_read_b128 v[100:103], v213 offset:16384
	ds_read_b128 v[148:151], v213 offset:17408
	ds_read_b128 v[152:155], v213 offset:18432
	ds_read_b128 v[156:159], v213 offset:19456
	ds_read_b128 v[160:163], v213 offset:20480
	ds_read_b128 v[164:167], v213 offset:21504
	ds_read_b128 v[168:171], v213 offset:22528
	ds_read_b128 v[172:175], v213 offset:23552
	global_load_lds_dwordx4 v[226:227], off
	s_mov_b32 m0, s43
	v_lshl_add_u64 v[228:229], s[34:35], 0, v[196:197]
	global_load_lds_dwordx4 v[228:229], off
	s_barrier
	s_waitcnt lgkmcnt(0)
	v_mfma_f32_16x16x32_bf16 v[76:79], v[16:19], v[100:103], v[76:79]
	v_mfma_f32_16x16x32_bf16 v[12:15], v[24:27], v[100:103], v[12:15]
	v_mfma_f32_16x16x32_bf16 v[72:75], v[16:19], v[152:155], v[72:75]
	v_mfma_f32_16x16x32_bf16 v[8:11], v[24:27], v[152:155], v[8:11]
	v_mfma_f32_16x16x32_bf16 v[128:131], v[16:19], v[160:163], v[128:131]
	v_mfma_f32_16x16x32_bf16 v[124:127], v[24:27], v[160:163], v[124:127]
	v_mfma_f32_16x16x32_bf16 v[16:19], v[16:19], v[168:171], v[120:123]
	v_mfma_f32_16x16x32_bf16 v[76:79], v[20:23], v[148:151], v[76:79]
	v_mfma_f32_16x16x32_bf16 v[12:15], v[68:71], v[148:151], v[12:15]
	v_mfma_f32_16x16x32_bf16 v[72:75], v[20:23], v[156:159], v[72:75]
	v_mfma_f32_16x16x32_bf16 v[8:11], v[68:71], v[156:159], v[8:11]
	v_mfma_f32_16x16x32_bf16 v[128:131], v[20:23], v[164:167], v[128:131]
	v_mfma_f32_16x16x32_bf16 v[124:127], v[68:71], v[164:167], v[124:127]
	v_mfma_f32_16x16x32_bf16 v[16:19], v[20:23], v[172:175], v[16:19]
	v_mfma_f32_16x16x32_bf16 v[20:23], v[24:27], v[168:171], v[116:119]
	v_mfma_f32_16x16x32_bf16 v[20:23], v[68:71], v[172:175], v[20:23]
	s_barrier
	s_add_u32 s8, s30, 0x40000
	s_addc_u32 s9, s31, 0
	s_add_i32 s68, s53, s41
	s_mov_b32 m0, s68
	v_lshl_add_u64 v[24:25], s[8:9], 0, v[192:193]
	global_load_lds_dwordx4 v[24:25], off
	s_add_i32 m0, s68, 0x2000
	v_lshl_add_u64 v[24:25], s[8:9], 0, v[198:199]
	global_load_lds_dwordx4 v[24:25], off
	s_waitcnt vmcnt(6)
	s_barrier
	v_mfma_f32_16x16x32_bf16 v[4:7], v[184:187], v[100:103], v[4:7]
	v_mfma_f32_16x16x32_bf16 v[60:63], v[176:179], v[152:155], v[60:63]
	v_mfma_f32_16x16x32_bf16 v[0:3], v[184:187], v[152:155], v[0:3]
	v_mfma_f32_16x16x32_bf16 v[44:47], v[176:179], v[160:163], v[44:47]
	v_mfma_f32_16x16x32_bf16 v[48:51], v[184:187], v[160:163], v[48:51]
	v_mfma_f32_16x16x32_bf16 v[52:55], v[176:179], v[168:171], v[52:55]
	v_mfma_f32_16x16x32_bf16 v[56:59], v[184:187], v[168:171], v[56:59]
	v_mfma_f32_16x16x32_bf16 v[24:27], v[176:179], v[100:103], v[64:67]
	v_mfma_f32_16x16x32_bf16 v[4:7], v[218:221], v[148:151], v[4:7]
	v_mfma_f32_16x16x32_bf16 v[60:63], v[180:183], v[156:159], v[60:63]
	v_mfma_f32_16x16x32_bf16 v[0:3], v[218:221], v[156:159], v[0:3]
	v_mfma_f32_16x16x32_bf16 v[44:47], v[180:183], v[164:167], v[44:47]
	v_mfma_f32_16x16x32_bf16 v[48:51], v[218:221], v[164:167], v[48:51]
	v_mfma_f32_16x16x32_bf16 v[52:55], v[180:183], v[172:175], v[52:55]
	v_mfma_f32_16x16x32_bf16 v[56:59], v[218:221], v[172:175], v[56:59]
	v_mfma_f32_16x16x32_bf16 v[24:27], v[180:183], v[148:151], v[24:27]
	s_add_i32 s68, 0, 0x18000
	v_add_u32_e32 v100, s68, v208
	s_barrier
	ds_read_b128 v[64:67], v100
	ds_read_b128 v[68:71], v100 offset:1024
	ds_read_b128 v[116:119], v100 offset:2048
	ds_read_b128 v[148:151], v100 offset:3072
	s_add_u32 s8, s34, 0x40000
	s_addc_u32 s9, s35, 0
	s_mov_b32 m0, s44
	v_lshl_add_u64 v[176:177], s[8:9], 0, v[194:195]
	ds_read_b128 v[100:103], v213 offset:32768
	ds_read_b128 v[120:123], v213 offset:33792
	ds_read_b128 v[152:155], v213 offset:34816
	ds_read_b128 v[156:159], v213 offset:35840
	ds_read_b128 v[160:163], v213 offset:36864
	ds_read_b128 v[164:167], v213 offset:37888
	ds_read_b128 v[168:171], v213 offset:38912
	ds_read_b128 v[172:175], v213 offset:39936
	global_load_lds_dwordx4 v[176:177], off
	s_mov_b32 m0, s45
	v_lshl_add_u64 v[176:177], s[8:9], 0, v[196:197]
	global_load_lds_dwordx4 v[176:177], off
	s_waitcnt lgkmcnt(8)
	s_barrier
	s_waitcnt lgkmcnt(0)
	v_mfma_f32_16x16x32_bf16 v[112:115], v[64:67], v[100:103], v[112:115]
	v_mfma_f32_16x16x32_bf16 v[40:43], v[116:119], v[100:103], v[40:43]
	v_mfma_f32_16x16x32_bf16 v[108:111], v[64:67], v[152:155], v[108:111]
	v_mfma_f32_16x16x32_bf16 v[36:39], v[116:119], v[152:155], v[36:39]
	v_mfma_f32_16x16x32_bf16 v[144:147], v[64:67], v[160:163], v[144:147]
	v_mfma_f32_16x16x32_bf16 v[140:143], v[116:119], v[160:163], v[140:143]
	v_mfma_f32_16x16x32_bf16 v[136:139], v[64:67], v[168:171], v[136:139]
	v_mfma_f32_16x16x32_bf16 v[132:135], v[116:119], v[168:171], v[132:135]
	v_mfma_f32_16x16x32_bf16 v[112:115], v[68:71], v[120:123], v[112:115]
	v_mfma_f32_16x16x32_bf16 v[40:43], v[148:151], v[120:123], v[40:43]
	v_mfma_f32_16x16x32_bf16 v[108:111], v[68:71], v[156:159], v[108:111]
	v_mfma_f32_16x16x32_bf16 v[36:39], v[148:151], v[156:159], v[36:39]
	v_mfma_f32_16x16x32_bf16 v[144:147], v[68:71], v[164:167], v[144:147]
	v_mfma_f32_16x16x32_bf16 v[140:143], v[148:151], v[164:167], v[140:143]
	v_mfma_f32_16x16x32_bf16 v[136:139], v[68:71], v[172:175], v[136:139]
	v_mfma_f32_16x16x32_bf16 v[132:135], v[148:151], v[172:175], v[132:135]
	s_barrier
	s_add_i32 s34, 0, 0x1c000
	s_add_i32 s8, s68, s41
	v_add_u32_e32 v217, s34, v208
	v_lshl_add_u64 v[222:223], v[222:223], 0, s[18:19]
	s_mov_b32 m0, s8
	ds_read_b128 v[176:179], v217
	ds_read_b128 v[180:183], v217 offset:1024
	ds_read_b128 v[184:187], v217 offset:2048
	ds_read_b128 v[218:221], v217 offset:3072
	global_load_lds_dwordx4 v[222:223], off
	s_add_i32 m0, s8, 0x2000
	v_lshl_add_u64 v[222:223], v[224:225], 0, s[18:19]
	global_load_lds_dwordx4 v[222:223], off
	s_barrier
	s_waitcnt lgkmcnt(0)
	v_mfma_f32_16x16x32_bf16 v[104:107], v[176:179], v[100:103], v[104:107]
	v_mfma_f32_16x16x32_bf16 v[32:35], v[184:187], v[100:103], v[32:35]
	v_mfma_f32_16x16x32_bf16 v[96:99], v[176:179], v[152:155], v[96:99]
	v_mfma_f32_16x16x32_bf16 v[28:31], v[184:187], v[152:155], v[28:31]
	v_mfma_f32_16x16x32_bf16 v[80:83], v[176:179], v[160:163], v[80:83]
	v_mfma_f32_16x16x32_bf16 v[92:95], v[184:187], v[160:163], v[92:95]
	v_mfma_f32_16x16x32_bf16 v[84:87], v[176:179], v[168:171], v[84:87]
	v_mfma_f32_16x16x32_bf16 v[88:91], v[184:187], v[168:171], v[88:91]
	v_mfma_f32_16x16x32_bf16 v[104:107], v[180:183], v[120:123], v[104:107]
	v_mfma_f32_16x16x32_bf16 v[32:35], v[218:221], v[120:123], v[32:35]
	v_mfma_f32_16x16x32_bf16 v[100:103], v[180:183], v[156:159], v[96:99]
	v_mfma_f32_16x16x32_bf16 v[28:31], v[218:221], v[156:159], v[28:31]
	v_mfma_f32_16x16x32_bf16 v[80:83], v[180:183], v[164:167], v[80:83]
	v_mfma_f32_16x16x32_bf16 v[92:95], v[218:221], v[164:167], v[92:95]
	v_mfma_f32_16x16x32_bf16 v[84:87], v[180:183], v[172:175], v[84:87]
	v_mfma_f32_16x16x32_bf16 v[88:91], v[218:221], v[172:175], v[88:91]
	s_mov_b32 m0, s49
	v_lshl_add_u64 v[120:121], v[226:227], 0, s[18:19]
	s_barrier
	ds_read_b128 v[96:99], v213 offset:49152
	ds_read_b128 v[152:155], v213 offset:50176
	ds_read_b128 v[156:159], v213 offset:51200
	ds_read_b128 v[160:163], v213 offset:52224
	ds_read_b128 v[164:167], v213 offset:53248
	ds_read_b128 v[168:171], v213 offset:54272
	ds_read_b128 v[172:175], v213 offset:55296
	ds_read_b128 v[222:225], v213 offset:56320
	global_load_lds_dwordx4 v[120:121], off
	s_mov_b32 m0, s50
	v_lshl_add_u64 v[120:121], v[228:229], 0, s[18:19]
	global_load_lds_dwordx4 v[120:121], off
	s_barrier
	s_waitcnt lgkmcnt(0)
	v_mfma_f32_16x16x32_bf16 v[120:123], v[64:67], v[164:167], v[128:131]
	v_mfma_f32_16x16x32_bf16 v[128:131], v[68:71], v[168:171], v[120:123]
	v_mfma_f32_16x16x32_bf16 v[120:123], v[116:119], v[164:167], v[124:127]
	v_mfma_f32_16x16x32_bf16 v[16:19], v[64:67], v[172:175], v[16:19]
	v_mfma_f32_16x16x32_bf16 v[76:79], v[64:67], v[96:99], v[76:79]
	v_mfma_f32_16x16x32_bf16 v[12:15], v[116:119], v[96:99], v[12:15]
	v_mfma_f32_16x16x32_bf16 v[72:75], v[64:67], v[156:159], v[72:75]
	v_mfma_f32_16x16x32_bf16 v[8:11], v[116:119], v[156:159], v[8:11]
	v_mfma_f32_16x16x32_bf16 v[124:127], v[148:151], v[168:171], v[120:123]
	v_mfma_f32_16x16x32_bf16 v[120:123], v[68:71], v[222:225], v[16:19]
	v_mfma_f32_16x16x32_bf16 v[16:19], v[116:119], v[172:175], v[20:23]
	v_mfma_f32_16x16x32_bf16 v[76:79], v[68:71], v[152:155], v[76:79]
	v_mfma_f32_16x16x32_bf16 v[12:15], v[148:151], v[152:155], v[12:15]
	v_mfma_f32_16x16x32_bf16 v[72:75], v[68:71], v[160:163], v[72:75]
	v_mfma_f32_16x16x32_bf16 v[8:11], v[148:151], v[160:163], v[8:11]
	v_mfma_f32_16x16x32_bf16 v[116:119], v[148:151], v[222:225], v[16:19]
	s_barrier
	s_add_u32 s8, s30, 0x40080
	s_addc_u32 s9, s31, 0
	s_add_i32 s30, s34, s41
	s_mov_b32 m0, s30
	v_lshl_add_u64 v[16:17], s[8:9], 0, v[192:193]
	global_load_lds_dwordx4 v[16:17], off
	s_add_i32 m0, s30, 0x2000
	v_lshl_add_u64 v[16:17], s[8:9], 0, v[198:199]
	global_load_lds_dwordx4 v[16:17], off
	s_waitcnt vmcnt(6)
	s_barrier
	v_mfma_f32_16x16x32_bf16 v[16:19], v[176:179], v[96:99], v[24:27]
	v_mfma_f32_16x16x32_bf16 v[64:67], v[180:183], v[152:155], v[16:19]
	v_mfma_f32_16x16x32_bf16 v[16:19], v[176:179], v[156:159], v[60:63]
	v_mfma_f32_16x16x32_bf16 v[60:63], v[180:183], v[160:163], v[16:19]
	v_mfma_f32_16x16x32_bf16 v[16:19], v[176:179], v[164:167], v[44:47]
	v_mfma_f32_16x16x32_bf16 v[44:47], v[180:183], v[168:171], v[16:19]
	v_mfma_f32_16x16x32_bf16 v[16:19], v[184:187], v[164:167], v[48:51]
	v_mfma_f32_16x16x32_bf16 v[48:51], v[218:221], v[168:171], v[16:19]
	v_mfma_f32_16x16x32_bf16 v[16:19], v[176:179], v[172:175], v[52:55]
	v_mfma_f32_16x16x32_bf16 v[4:7], v[184:187], v[96:99], v[4:7]
	v_mfma_f32_16x16x32_bf16 v[0:3], v[184:187], v[156:159], v[0:3]
	v_mfma_f32_16x16x32_bf16 v[52:55], v[180:183], v[222:225], v[16:19]
	v_mfma_f32_16x16x32_bf16 v[16:19], v[184:187], v[172:175], v[56:59]
	v_mfma_f32_16x16x32_bf16 v[4:7], v[218:221], v[152:155], v[4:7]
	v_mfma_f32_16x16x32_bf16 v[0:3], v[218:221], v[160:163], v[0:3]
	v_mfma_f32_16x16x32_bf16 v[56:59], v[218:221], v[222:225], v[16:19]
	s_add_i32 s67, s67, 2
	s_add_u32 s62, s62, 0x100
	s_addc_u32 s63, s63, 0
	s_cmp_gt_u32 s67, 13
	s_mov_b64 s[8:9], s[28:29]
	s_barrier
	s_cbranch_scc0 .LBB0_1639
	v_cndmask_b32_e64 v16, 0, 1, s[26:27]
	v_cmp_ne_u32_e64 s[8:9], 1, v16
	s_andn2_b64 vcc, exec, s[26:27]
	s_cbranch_vccnz .LBB0_1644
	v_mov_b32_e32 v16, 0
	v_mov_b32_e32 v17, 0
	v_mov_b32_e32 v18, 0
	v_mov_b32_e32 v19, 0
	s_and_saveexec_b64 s[26:27], s[2:3]
	s_cbranch_execz .LBB0_1643
	s_lshl_b32 s28, s10, 7
	s_ashr_i32 s29, s28, 31
	v_lshl_add_u64 v[16:17], s[28:29], 2, v[202:203]
	global_load_dwordx4 v[16:19], v[16:17], off

.LBB0_1741:
	ds_read_b128 v[128:131], v190
	ds_read_b128 v[132:135], v190 offset:1024
	ds_read_b128 v[136:139], v190 offset:2048
	ds_read_b128 v[140:143], v190 offset:3072
	s_add_u32 s16, s14, 0x100
	s_addc_u32 s17, s15, 0
	s_cmp_eq_u32 s47, 40
	s_cselect_b32 s21, s1, s17
	s_cselect_b32 s20, s0, s16
	s_cselect_b32 s19, s7, s46
	s_cselect_b32 s18, s6, s45
	v_lshl_add_u64 v[184:185], s[14:15], 0, v[160:161]
	s_add_i32 m0, s28, 0xc000
	ds_read_b128 v[144:147], v191
	ds_read_b128 v[148:151], v191 offset:1024
	ds_read_b128 v[168:171], v191 offset:2048
	ds_read_b128 v[172:175], v191 offset:3072
	ds_read_b128 v[176:179], v191 offset:4096
	ds_read_b128 v[180:183], v191 offset:5120
	ds_read_b128 v[194:197], v191 offset:6144
	ds_read_b128 v[198:201], v191 offset:7168
	global_load_lds_dwordx4 v[184:185], off
	s_add_i32 m0, s28, 0xe000
	v_lshl_add_u64 v[184:185], s[14:15], 0, v[162:163]
	global_load_lds_dwordx4 v[184:185], off
	s_waitcnt lgkmcnt(8)
	s_barrier
	s_waitcnt lgkmcnt(0)
	v_mfma_f32_16x16x32_bf16 v[124:127], v[128:131], v[144:147], v[124:127]
	v_mfma_f32_16x16x32_bf16 v[120:123], v[136:139], v[144:147], v[120:123]
	v_mfma_f32_16x16x32_bf16 v[108:111], v[128:131], v[168:171], v[108:111]
	v_mfma_f32_16x16x32_bf16 v[104:107], v[136:139], v[168:171], v[104:107]
	v_mfma_f32_16x16x32_bf16 v[92:95], v[128:131], v[176:179], v[92:95]
	v_mfma_f32_16x16x32_bf16 v[88:91], v[136:139], v[176:179], v[88:91]
	v_mfma_f32_16x16x32_bf16 v[76:79], v[128:131], v[194:197], v[76:79]
	v_mfma_f32_16x16x32_bf16 v[72:75], v[136:139], v[194:197], v[72:75]
	v_mfma_f32_16x16x32_bf16 v[124:127], v[132:135], v[148:151], v[124:127]
	v_mfma_f32_16x16x32_bf16 v[120:123], v[140:143], v[148:151], v[120:123]
	v_mfma_f32_16x16x32_bf16 v[108:111], v[132:135], v[172:175], v[108:111]
	v_mfma_f32_16x16x32_bf16 v[104:107], v[140:143], v[172:175], v[104:107]
	v_mfma_f32_16x16x32_bf16 v[92:95], v[132:135], v[180:183], v[92:95]
	v_mfma_f32_16x16x32_bf16 v[88:91], v[140:143], v[180:183], v[88:91]
	v_mfma_f32_16x16x32_bf16 v[76:79], v[132:135], v[198:201], v[76:79]
	v_mfma_f32_16x16x32_bf16 v[72:75], v[140:143], v[198:201], v[72:75]
	s_barrier
	s_add_i32 s14, s39, s27
	v_lshl_add_u64 v[184:185], s[18:19], 0, v[154:155]
	s_mov_b32 m0, s14
	ds_read_b128 v[202:205], v192
	ds_read_b128 v[206:209], v192 offset:1024
	ds_read_b128 v[210:213], v192 offset:2048
	ds_read_b128 v[214:217], v192 offset:3072
	global_load_lds_dwordx4 v[184:185], off
	s_add_i32 m0, s14, 0x2000
	v_lshl_add_u64 v[218:219], s[18:19], 0, v[158:159]
	global_load_lds_dwordx4 v[218:219], off
	s_barrier
	s_waitcnt lgkmcnt(0)
	v_mfma_f32_16x16x32_bf16 v[116:119], v[202:205], v[144:147], v[116:119]
	v_mfma_f32_16x16x32_bf16 v[112:115], v[210:213], v[144:147], v[112:115]
	v_mfma_f32_16x16x32_bf16 v[100:103], v[202:205], v[168:171], v[100:103]
	v_mfma_f32_16x16x32_bf16 v[96:99], v[210:213], v[168:171], v[96:99]
	v_mfma_f32_16x16x32_bf16 v[84:87], v[202:205], v[176:179], v[84:87]
	v_mfma_f32_16x16x32_bf16 v[80:83], v[210:213], v[176:179], v[80:83]
	v_mfma_f32_16x16x32_bf16 v[68:71], v[202:205], v[194:197], v[68:71]
	v_mfma_f32_16x16x32_bf16 v[64:67], v[210:213], v[194:197], v[64:67]
	v_mfma_f32_16x16x32_bf16 v[116:119], v[206:209], v[148:151], v[116:119]
	v_mfma_f32_16x16x32_bf16 v[112:115], v[214:217], v[148:151], v[112:115]
	v_mfma_f32_16x16x32_bf16 v[100:103], v[206:209], v[172:175], v[100:103]
	v_mfma_f32_16x16x32_bf16 v[96:99], v[214:217], v[172:175], v[96:99]
	v_mfma_f32_16x16x32_bf16 v[84:87], v[206:209], v[180:183], v[84:87]
	v_mfma_f32_16x16x32_bf16 v[80:83], v[214:217], v[180:183], v[80:83]
	v_mfma_f32_16x16x32_bf16 v[68:71], v[206:209], v[198:201], v[68:71]
	v_mfma_f32_16x16x32_bf16 v[64:67], v[214:217], v[198:201], v[64:67]
	s_mov_b32 m0, s28
	v_lshl_add_u64 v[220:221], s[20:21], 0, v[152:153]
	s_barrier
	ds_read_b128 v[144:147], v191 offset:16384
	ds_read_b128 v[148:151], v191 offset:17408
	ds_read_b128 v[168:171], v191 offset:18432
	ds_read_b128 v[172:175], v191 offset:19456
	ds_read_b128 v[176:179], v191 offset:20480
	ds_read_b128 v[180:183], v191 offset:21504
	ds_read_b128 v[194:197], v191 offset:22528
	ds_read_b128 v[198:201], v191 offset:23552
	global_load_lds_dwordx4 v[220:221], off
	s_mov_b32 m0, s29
	v_lshl_add_u64 v[222:223], s[20:21], 0, v[156:157]
	global_load_lds_dwordx4 v[222:223], off
	s_barrier
	s_waitcnt lgkmcnt(0)
	v_mfma_f32_16x16x32_bf16 v[60:63], v[128:131], v[144:147], v[60:63]
	v_mfma_f32_16x16x32_bf16 v[56:59], v[136:139], v[144:147], v[56:59]
	v_mfma_f32_16x16x32_bf16 v[44:47], v[128:131], v[168:171], v[44:47]
	v_mfma_f32_16x16x32_bf16 v[40:43], v[136:139], v[168:171], v[40:43]
	v_mfma_f32_16x16x32_bf16 v[28:31], v[128:131], v[176:179], v[28:31]
	v_mfma_f32_16x16x32_bf16 v[24:27], v[136:139], v[176:179], v[24:27]
	v_mfma_f32_16x16x32_bf16 v[12:15], v[128:131], v[194:197], v[12:15]
	v_mfma_f32_16x16x32_bf16 v[8:11], v[136:139], v[194:197], v[8:11]
	v_mfma_f32_16x16x32_bf16 v[60:63], v[132:135], v[148:151], v[60:63]
	v_mfma_f32_16x16x32_bf16 v[56:59], v[140:143], v[148:151], v[56:59]
	v_mfma_f32_16x16x32_bf16 v[44:47], v[132:135], v[172:175], v[44:47]
	v_mfma_f32_16x16x32_bf16 v[40:43], v[140:143], v[172:175], v[40:43]
	v_mfma_f32_16x16x32_bf16 v[28:31], v[132:135], v[180:183], v[28:31]
	v_mfma_f32_16x16x32_bf16 v[24:27], v[140:143], v[180:183], v[24:27]
	v_mfma_f32_16x16x32_bf16 v[12:15], v[132:135], v[198:201], v[12:15]
	v_mfma_f32_16x16x32_bf16 v[8:11], v[140:143], v[198:201], v[8:11]
	s_barrier
	s_add_u32 s14, s18, 0xb0000
	s_addc_u32 s15, s19, 0
	s_add_i32 s48, s40, s27
	s_mov_b32 m0, s48
	v_lshl_add_u64 v[128:129], s[14:15], 0, v[154:155]
	global_load_lds_dwordx4 v[128:129], off
	s_add_i32 m0, s48, 0x2000
	v_lshl_add_u64 v[128:129], s[14:15], 0, v[158:159]
	global_load_lds_dwordx4 v[128:129], off
	s_waitcnt vmcnt(6)
	s_barrier
	v_mfma_f32_16x16x32_bf16 v[52:55], v[202:205], v[144:147], v[52:55]
	v_mfma_f32_16x16x32_bf16 v[48:51], v[210:213], v[144:147], v[48:51]
	v_mfma_f32_16x16x32_bf16 v[36:39], v[202:205], v[168:171], v[36:39]
	v_mfma_f32_16x16x32_bf16 v[32:35], v[210:213], v[168:171], v[32:35]
	v_mfma_f32_16x16x32_bf16 v[20:23], v[202:205], v[176:179], v[20:23]
	v_mfma_f32_16x16x32_bf16 v[16:19], v[210:213], v[176:179], v[16:19]
	v_mfma_f32_16x16x32_bf16 v[4:7], v[202:205], v[194:197], v[4:7]
	v_mfma_f32_16x16x32_bf16 v[0:3], v[210:213], v[194:197], v[0:3]
	v_mfma_f32_16x16x32_bf16 v[52:55], v[206:209], v[148:151], v[52:55]
	v_mfma_f32_16x16x32_bf16 v[48:51], v[214:217], v[148:151], v[48:51]
	v_mfma_f32_16x16x32_bf16 v[36:39], v[206:209], v[172:175], v[36:39]
	v_mfma_f32_16x16x32_bf16 v[32:35], v[214:217], v[172:175], v[32:35]
	v_mfma_f32_16x16x32_bf16 v[20:23], v[206:209], v[180:183], v[20:23]
	v_mfma_f32_16x16x32_bf16 v[16:19], v[214:217], v[180:183], v[16:19]
	v_mfma_f32_16x16x32_bf16 v[4:7], v[206:209], v[198:201], v[4:7]
	v_mfma_f32_16x16x32_bf16 v[0:3], v[214:217], v[198:201], v[0:3]
	s_add_i32 s48, 0, 0x18000
	v_add_u32_e32 v140, s48, v187
	s_barrier
	ds_read_b128 v[128:131], v140
	ds_read_b128 v[132:135], v140 offset:1024
	ds_read_b128 v[136:139], v140 offset:2048
	ds_read_b128 v[140:143], v140 offset:3072
	s_add_u32 s14, s20, 0xb0000
	s_addc_u32 s15, s21, 0
	s_mov_b32 m0, s30
	v_lshl_add_u64 v[202:203], s[14:15], 0, v[152:153]
	ds_read_b128 v[144:147], v191 offset:32768
	ds_read_b128 v[148:151], v191 offset:33792
	ds_read_b128 v[168:171], v191 offset:34816
	ds_read_b128 v[172:175], v191 offset:35840
	ds_read_b128 v[176:179], v191 offset:36864
	ds_read_b128 v[180:183], v191 offset:37888
	ds_read_b128 v[194:197], v191 offset:38912
	ds_read_b128 v[198:201], v191 offset:39936
	global_load_lds_dwordx4 v[202:203], off
	s_mov_b32 m0, s31
	v_lshl_add_u64 v[202:203], s[14:15], 0, v[156:157]
	global_load_lds_dwordx4 v[202:203], off
	s_waitcnt lgkmcnt(8)
	s_barrier
	s_waitcnt lgkmcnt(0)
	v_mfma_f32_16x16x32_bf16 v[124:127], v[128:131], v[144:147], v[124:127]
	v_mfma_f32_16x16x32_bf16 v[120:123], v[136:139], v[144:147], v[120:123]
	v_mfma_f32_16x16x32_bf16 v[108:111], v[128:131], v[168:171], v[108:111]
	v_mfma_f32_16x16x32_bf16 v[104:107], v[136:139], v[168:171], v[104:107]
	v_mfma_f32_16x16x32_bf16 v[92:95], v[128:131], v[176:179], v[92:95]
	v_mfma_f32_16x16x32_bf16 v[88:91], v[136:139], v[176:179], v[88:91]
	v_mfma_f32_16x16x32_bf16 v[76:79], v[128:131], v[194:197], v[76:79]
	v_mfma_f32_16x16x32_bf16 v[72:75], v[136:139], v[194:197], v[72:75]
	v_mfma_f32_16x16x32_bf16 v[124:127], v[132:135], v[148:151], v[124:127]
	v_mfma_f32_16x16x32_bf16 v[120:123], v[140:143], v[148:151], v[120:123]
	v_mfma_f32_16x16x32_bf16 v[108:111], v[132:135], v[172:175], v[108:111]
	v_mfma_f32_16x16x32_bf16 v[104:107], v[140:143], v[172:175], v[104:107]
	v_mfma_f32_16x16x32_bf16 v[92:95], v[132:135], v[180:183], v[92:95]
	v_mfma_f32_16x16x32_bf16 v[88:91], v[140:143], v[180:183], v[88:91]
	v_mfma_f32_16x16x32_bf16 v[76:79], v[132:135], v[198:201], v[76:79]
	v_mfma_f32_16x16x32_bf16 v[72:75], v[140:143], v[198:201], v[72:75]
	s_barrier
	s_add_i32 s20, 0, 0x1c000
	s_add_i32 s14, s48, s27
	v_add_u32_e32 v214, s20, v187
	v_lshl_add_u64 v[184:185], v[184:185], 0, s[12:13]
	s_mov_b32 m0, s14
	ds_read_b128 v[202:205], v214
	ds_read_b128 v[206:209], v214 offset:1024
	ds_read_b128 v[210:213], v214 offset:2048
	ds_read_b128 v[214:217], v214 offset:3072
	global_load_lds_dwordx4 v[184:185], off
	s_add_i32 m0, s14, 0x2000
	v_lshl_add_u64 v[184:185], v[218:219], 0, s[12:13]
	global_load_lds_dwordx4 v[184:185], off
	s_barrier
	s_waitcnt lgkmcnt(0)
	v_mfma_f32_16x16x32_bf16 v[116:119], v[202:205], v[144:147], v[116:119]
	v_mfma_f32_16x16x32_bf16 v[112:115], v[210:213], v[144:147], v[112:115]
	v_mfma_f32_16x16x32_bf16 v[100:103], v[202:205], v[168:171], v[100:103]
	v_mfma_f32_16x16x32_bf16 v[96:99], v[210:213], v[168:171], v[96:99]
	v_mfma_f32_16x16x32_bf16 v[84:87], v[202:205], v[176:179], v[84:87]
	v_mfma_f32_16x16x32_bf16 v[80:83], v[210:213], v[176:179], v[80:83]
	v_mfma_f32_16x16x32_bf16 v[68:71], v[202:205], v[194:197], v[68:71]
	v_mfma_f32_16x16x32_bf16 v[64:67], v[210:213], v[194:197], v[64:67]
	v_mfma_f32_16x16x32_bf16 v[116:119], v[206:209], v[148:151], v[116:119]
	v_mfma_f32_16x16x32_bf16 v[112:115], v[214:217], v[148:151], v[112:115]
	v_mfma_f32_16x16x32_bf16 v[100:103], v[206:209], v[172:175], v[100:103]
	v_mfma_f32_16x16x32_bf16 v[96:99], v[214:217], v[172:175], v[96:99]
	v_mfma_f32_16x16x32_bf16 v[84:87], v[206:209], v[180:183], v[84:87]
	v_mfma_f32_16x16x32_bf16 v[80:83], v[214:217], v[180:183], v[80:83]
	v_mfma_f32_16x16x32_bf16 v[68:71], v[206:209], v[198:201], v[68:71]
	v_mfma_f32_16x16x32_bf16 v[64:67], v[214:217], v[198:201], v[64:67]
	s_mov_b32 m0, s35
	v_lshl_add_u64 v[184:185], v[220:221], 0, s[12:13]
	s_barrier
	ds_read_b128 v[144:147], v191 offset:49152
	ds_read_b128 v[148:151], v191 offset:50176
	ds_read_b128 v[168:171], v191 offset:51200
	ds_read_b128 v[172:175], v191 offset:52224
	ds_read_b128 v[176:179], v191 offset:53248
	ds_read_b128 v[180:183], v191 offset:54272
	ds_read_b128 v[194:197], v191 offset:55296
	ds_read_b128 v[198:201], v191 offset:56320
	global_load_lds_dwordx4 v[184:185], off
	s_mov_b32 m0, s36
	v_lshl_add_u64 v[184:185], v[222:223], 0, s[12:13]
	global_load_lds_dwordx4 v[184:185], off
	s_barrier
	s_waitcnt lgkmcnt(0)
	v_mfma_f32_16x16x32_bf16 v[60:63], v[128:131], v[144:147], v[60:63]
	v_mfma_f32_16x16x32_bf16 v[56:59], v[136:139], v[144:147], v[56:59]
	v_mfma_f32_16x16x32_bf16 v[44:47], v[128:131], v[168:171], v[44:47]
	v_mfma_f32_16x16x32_bf16 v[40:43], v[136:139], v[168:171], v[40:43]
	v_mfma_f32_16x16x32_bf16 v[28:31], v[128:131], v[176:179], v[28:31]
	v_mfma_f32_16x16x32_bf16 v[24:27], v[136:139], v[176:179], v[24:27]
	v_mfma_f32_16x16x32_bf16 v[12:15], v[128:131], v[194:197], v[12:15]
	v_mfma_f32_16x16x32_bf16 v[8:11], v[136:139], v[194:197], v[8:11]
	v_mfma_f32_16x16x32_bf16 v[60:63], v[132:135], v[148:151], v[60:63]
	v_mfma_f32_16x16x32_bf16 v[56:59], v[140:143], v[148:151], v[56:59]
	v_mfma_f32_16x16x32_bf16 v[44:47], v[132:135], v[172:175], v[44:47]
	v_mfma_f32_16x16x32_bf16 v[40:43], v[140:143], v[172:175], v[40:43]
	v_mfma_f32_16x16x32_bf16 v[28:31], v[132:135], v[180:183], v[28:31]
	v_mfma_f32_16x16x32_bf16 v[24:27], v[140:143], v[180:183], v[24:27]
	v_mfma_f32_16x16x32_bf16 v[12:15], v[132:135], v[198:201], v[12:15]
	v_mfma_f32_16x16x32_bf16 v[8:11], v[140:143], v[198:201], v[8:11]
	s_barrier
	s_add_u32 s14, s18, 0xb0080
	s_addc_u32 s15, s19, 0
	s_add_i32 s18, s20, s27
	s_mov_b32 m0, s18
	v_lshl_add_u64 v[128:129], s[14:15], 0, v[154:155]
	global_load_lds_dwordx4 v[128:129], off
	s_add_i32 m0, s18, 0x2000
	v_lshl_add_u64 v[128:129], s[14:15], 0, v[158:159]
	global_load_lds_dwordx4 v[128:129], off
	s_waitcnt vmcnt(6)
	s_barrier
	v_mfma_f32_16x16x32_bf16 v[52:55], v[202:205], v[144:147], v[52:55]
	v_mfma_f32_16x16x32_bf16 v[48:51], v[210:213], v[144:147], v[48:51]
	v_mfma_f32_16x16x32_bf16 v[36:39], v[202:205], v[168:171], v[36:39]
	v_mfma_f32_16x16x32_bf16 v[32:35], v[210:213], v[168:171], v[32:35]
	v_mfma_f32_16x16x32_bf16 v[20:23], v[202:205], v[176:179], v[20:23]
	v_mfma_f32_16x16x32_bf16 v[16:19], v[210:213], v[176:179], v[16:19]
	v_mfma_f32_16x16x32_bf16 v[4:7], v[202:205], v[194:197], v[4:7]
	v_mfma_f32_16x16x32_bf16 v[0:3], v[210:213], v[194:197], v[0:3]
	v_mfma_f32_16x16x32_bf16 v[52:55], v[206:209], v[148:151], v[52:55]
	v_mfma_f32_16x16x32_bf16 v[48:51], v[214:217], v[148:151], v[48:51]
	v_mfma_f32_16x16x32_bf16 v[36:39], v[206:209], v[172:175], v[36:39]
	v_mfma_f32_16x16x32_bf16 v[32:35], v[214:217], v[172:175], v[32:35]
	v_mfma_f32_16x16x32_bf16 v[20:23], v[206:209], v[180:183], v[20:23]
	v_mfma_f32_16x16x32_bf16 v[16:19], v[214:217], v[180:183], v[16:19]
	v_mfma_f32_16x16x32_bf16 v[4:7], v[206:209], v[198:201], v[4:7]
	v_mfma_f32_16x16x32_bf16 v[0:3], v[214:217], v[198:201], v[0:3]
	s_add_i32 s47, s47, 2
	s_add_u32 s45, s45, 0x100
	s_addc_u32 s46, s46, 0
	s_cmp_gt_u32 s47, 41
	s_mov_b64 s[14:15], s[16:17]
	s_barrier
	s_cbranch_scc0 .LBB0_1741
	v_lshl_or_b32 v168, s10, 8, v189
	v_lshl_add_u32 v170, s44, 8, v186
	v_ashrrev_i32_e32 v169, 31, v168
	v_lshlrev_b64 v[202:203], 1, v[168:169]
	v_ashrrev_i32_e32 v171, 31, v170
	v_or_b32_e32 v182, 16, v170
	v_lshl_add_u64 v[172:173], s[64:65], 0, v[202:203]
	v_lshlrev_b64 v[204:205], 11, v[170:171]
	v_ashrrev_i32_e32 v183, 31, v182
	v_or_b32_e32 v178, 32, v170
	v_lshl_add_u64 v[128:129], v[172:173], 0, v[204:205]
	v_lshlrev_b64 v[184:185], 11, v[182:183]
	v_ashrrev_i32_e32 v179, 31, v178
	v_or_b32_e32 v174, 48, v170
	global_load_dwordx4 v[194:197], v[128:129], off
	global_load_dwordx4 v[198:201], v[128:129], off offset:256
	v_lshl_add_u64 v[128:129], v[172:173], 0, v[184:185]
	v_lshlrev_b64 v[180:181], 11, v[178:179]
	v_ashrrev_i32_e32 v175, 31, v174
	global_load_dwordx4 v[148:151], v[128:129], off
	global_load_dwordx4 v[144:147], v[128:129], off offset:256
	v_lshl_add_u64 v[128:129], v[172:173], 0, v[180:181]
	v_lshlrev_b64 v[176:177], 11, v[174:175]
	global_load_dwordx4 v[140:143], v[128:129], off
	global_load_dwordx4 v[136:139], v[128:129], off offset:256
	v_lshl_add_u64 v[128:129], v[172:173], 0, v[176:177]
	global_load_dwordx4 v[132:135], v[128:129], off
	s_nop 0
	global_load_dwordx4 v[128:131], v[128:129], off offset:256
	s_lshl_b32 s14, s10, 2
	s_ashr_i32 s15, s14, 31
	v_add_u32_e32 v252, 0x80, v170
	v_ashrrev_i32_e32 v253, 31, v252
	v_lshlrev_b64 v[252:253], 11, v[252:253]
	v_lshl_add_u64 v[252:253], v[172:173], 0, v[252:253]
	global_load_dwordx4 v[236:239], v[252:253], off
	global_load_dwordx4 v[240:243], v[252:253], off offset:256
	v_add_u32_e32 v252, 0x90, v170
	v_ashrrev_i32_e32 v253, 31, v252
	v_lshlrev_b64 v[252:253], 11, v[252:253]
	v_lshl_add_u64 v[252:253], v[172:173], 0, v[252:253]
	global_load_dwordx4 v[244:247], v[252:253], off
	global_load_dwordx4 v[248:251], v[252:253], off offset:256
	v_add_u32_e32 v252, 0xa0, v170
	v_ashrrev_i32_e32 v253, 31, v252
	v_lshlrev_b64 v[252:253], 11, v[252:253]
	v_lshl_add_u64 v[252:253], v[172:173], 0, v[252:253]
	global_load_dwordx4 v[210:213], v[252:253], off
	global_load_dwordx4 v[214:217], v[252:253], off offset:256
	s_waitcnt vmcnt(6)
	v_lshlrev_b32_e32 v206, 16, v194
	v_and_b32_e32 v207, 0xffff0000, v194
	v_lshlrev_b32_e32 v194, 16, v195
	v_and_b32_e32 v195, 0xffff0000, v195
	v_lshlrev_b32_e32 v208, 16, v196
	v_and_b32_e32 v209, 0xffff0000, v196
	v_lshlrev_b32_e32 v196, 16, v197
	v_and_b32_e32 v197, 0xffff0000, v197
	v_pk_add_f32 v[126:127], v[126:127], v[194:195]
	v_pk_add_f32 v[124:125], v[124:125], v[206:207]
	v_pk_add_f32 v[194:195], v[122:123], v[196:197]
	v_pk_add_f32 v[122:123], v[120:121], v[208:209]
	v_mul_f32_e32 v120, v125, v125
	v_mul_f32_e32 v121, v127, v127
	v_fmac_f32_e32 v120, v124, v124
	v_fmac_f32_e32 v121, v126, v126
	v_add_f32_e32 v120, v120, v121
	v_mul_f32_e32 v121, v123, v123
	v_mul_f32_e32 v196, v195, v195
	v_fmac_f32_e32 v121, v122, v122
	v_fmac_f32_e32 v196, v194, v194
	v_add_f32_e32 v121, v121, v196
	v_add_f32_e32 v206, v120, v121
	v_cvt_pk_bf16_f32 v120, v124, v125
	v_cvt_pk_bf16_f32 v121, v126, v127
	v_lshlrev_b32_e32 v124, 16, v198
	v_and_b32_e32 v125, 0xffff0000, v198
	v_lshlrev_b32_e32 v126, 16, v199
	v_and_b32_e32 v127, 0xffff0000, v199
	v_cvt_pk_bf16_f32 v122, v122, v123
	v_cvt_pk_bf16_f32 v123, v194, v195
	v_lshlrev_b32_e32 v194, 16, v200
	v_and_b32_e32 v195, 0xffff0000, v200
	v_pk_add_f32 v[118:119], v[118:119], v[126:127]
	v_pk_add_f32 v[116:117], v[116:117], v[124:125]
	v_lshlrev_b32_e32 v196, 16, v201
	v_and_b32_e32 v197, 0xffff0000, v201
	v_pk_add_f32 v[126:127], v[112:113], v[194:195]
	v_mul_f32_e32 v112, v117, v117
	v_mul_f32_e32 v113, v119, v119
	v_pk_add_f32 v[124:125], v[114:115], v[196:197]
	v_fmac_f32_e32 v112, v116, v116
	v_fmac_f32_e32 v113, v118, v118
	v_add_f32_e32 v112, v112, v113
	v_mul_f32_e32 v113, v127, v127
	v_mul_f32_e32 v114, v125, v125
	v_fmac_f32_e32 v113, v126, v126
	v_fmac_f32_e32 v114, v124, v124
	v_add_f32_e32 v113, v113, v114
	v_add_f32_e32 v112, v112, v113
	v_and_b32_e32 v114, 64, v193
	v_add_f32_e32 v113, v206, v112
	v_xor_b32_e32 v112, 16, v193
	v_add_u32_e32 v196, 64, v114
	v_cmp_lt_i32_e32 vcc, v112, v196
	v_lshl_add_u64 v[114:115], s[64:65], 0, v[204:205]
	v_lshl_add_u64 v[194:195], v[114:115], 0, v[202:203]
	v_cndmask_b32_e32 v112, v193, v112, vcc
	v_lshlrev_b32_e32 v112, 2, v112
	ds_bpermute_b32 v197, v112, v113
	global_store_dwordx4 v[194:195], v[120:123], off
	v_cvt_pk_bf16_f32 v116, v116, v117
	v_cvt_pk_bf16_f32 v117, v118, v119
	v_cvt_pk_bf16_f32 v118, v126, v127
	s_waitcnt lgkmcnt(0)
	v_add_f32_e32 v114, v113, v197
	v_xor_b32_e32 v113, 32, v193
	v_cmp_lt_i32_e32 vcc, v113, v196
	v_cvt_pk_bf16_f32 v119, v124, v125
	global_store_dwordx4 v[194:195], v[116:119], off offset:256
	s_nop 0
	v_cndmask_b32_e32 v113, v193, v113, vcc
	v_lshlrev_b32_e32 v113, 2, v113
	ds_bpermute_b32 v115, v113, v114
	s_and_saveexec_b64 s[16:17], s[2:3]
	s_cbranch_execz .LBB0_1744
	s_waitcnt lgkmcnt(0)
	v_add_f32_e32 v116, v114, v115
	v_lshlrev_b64 v[114:115], 6, v[170:171]
	v_lshl_add_u64 v[114:115], s[74:75], 0, v[114:115]
	v_lshl_add_u64 v[114:115], s[14:15], 2, v[114:115]
	s_lshl_b32 s10, s34, 2
	v_lshl_add_u64 v[114:115], v[114:115], 0, s[10:11]
	global_store_dword v[114:115], v116, off
